# gelu in GEMM1/GEMM3 epilogues: |v| via source modifiers on scalar v_fma_f32 instead of v_and + packed fma (154 value pairs, bit-identical)
# speedup vs baseline: 1.0046x; 1.0046x over previous
.LBB0_275:
	s_nop 15
	s_nop 15
	s_cmpk_lt_i32 s72, 0x5e
	s_mov_b64 s[74:75], -1
	s_cbranch_scc0 .LBB0_277
	v_lshl_add_u32 v152, s70, 8, v161
	v_lshl_or_b32 v146, s72, 8, v163
	v_ashrrev_i32_e32 v147, 31, v146
	v_ashrrev_i32_e32 v153, 31, v152
	v_pk_add_f32 v[156:157], v[124:125], 0 op_sel_hi:[1,0]
	v_lshl_add_u64 v[150:151], v[146:147], 1, s[18:19]
	v_lshlrev_b64 v[146:147], 11, v[152:153]
	v_lshl_add_u64 v[148:149], v[150:151], 0, v[146:147]
	v_fma_f32 v146, |v156|, s38, 1.0
	v_fma_f32 v147, |v157|, s38, 1.0
	v_pk_add_f32 v[154:155], v[126:127], 0 op_sel_hi:[1,0]
	v_rcp_f32_e32 v174, v146
	v_rcp_f32_e32 v175, v147
	v_mov_b64_e32 v[146:147], s[42:43]
	v_pk_mul_f32 v[180:181], v[156:157], v[156:157]
	v_pk_fma_f32 v[178:179], v[174:175], s[40:41], v[146:147] op_sel_hi:[1,0,0]
	v_pk_mul_f32 v[180:181], v[180:181], s[50:51] op_sel_hi:[1,0]
	v_pk_fma_f32 v[178:179], v[174:175], v[178:179], s[44:45] op_sel_hi:[1,1,0]
	v_exp_f32_e32 v180, v180
	v_exp_f32_e32 v181, v181
	v_fma_f32 v182, |v154|, s38, 1.0
	v_fma_f32 v183, |v155|, s38, 1.0
	v_pk_fma_f32 v[178:179], v[174:175], v[178:179], s[46:47] op_sel_hi:[1,1,0]
	v_rcp_f32_e32 v182, v182
	v_rcp_f32_e32 v183, v183
	v_pk_fma_f32 v[178:179], v[174:175], v[178:179], s[48:49] op_sel_hi:[1,1,0]
	v_max_f32_e32 v172, 0, v156
	v_pk_mul_f32 v[174:175], v[174:175], v[178:179]
	v_pk_mul_f32 v[178:179], v[154:155], v[154:155]
	v_max_f32_e32 v173, 0, v157
	v_pk_mul_f32 v[174:175], v[180:181], v[174:175]
	v_pk_add_f32 v[170:171], v[120:121], 0 op_sel_hi:[1,0]
	v_fma_f32 v156, -|v156|, v174, v172
	v_fma_f32 v157, -|v157|, v175, v173
	v_pk_fma_f32 v[172:173], v[182:183], s[40:41], v[146:147] op_sel_hi:[1,0,0]
	v_pk_mul_f32 v[174:175], v[178:179], s[50:51] op_sel_hi:[1,0]
	v_pk_fma_f32 v[172:173], v[182:183], v[172:173], s[44:45] op_sel_hi:[1,1,0]
	v_exp_f32_e32 v174, v174
	v_exp_f32_e32 v175, v175
	v_pk_fma_f32 v[172:173], v[182:183], v[172:173], s[46:47] op_sel_hi:[1,1,0]
	v_pk_add_f32 v[158:159], v[122:123], 0 op_sel_hi:[1,0]
	v_pk_fma_f32 v[172:173], v[182:183], v[172:173], s[48:49] op_sel_hi:[1,1,0]
	v_max_f32_e32 v176, 0, v154
	v_pk_mul_f32 v[172:173], v[182:183], v[172:173]
	v_max_f32_e32 v177, 0, v155
	v_pk_mul_f32 v[172:173], v[174:175], v[172:173]
	v_fma_f32 v178, |v170|, s38, 1.0
	v_fma_f32 v179, |v171|, s38, 1.0
	v_pk_mul_f32 v[180:181], v[170:171], v[170:171]
	v_rcp_f32_e32 v178, v178
	v_rcp_f32_e32 v179, v179
	v_fma_f32 v172, -|v154|, v172, v176
	v_fma_f32 v173, -|v155|, v173, v177
	v_pk_fma_f32 v[176:177], v[178:179], s[40:41], v[146:147] op_sel_hi:[1,0,0]
	v_pk_mul_f32 v[180:181], v[180:181], s[50:51] op_sel_hi:[1,0]
	v_pk_fma_f32 v[176:177], v[178:179], v[176:177], s[44:45] op_sel_hi:[1,1,0]
	v_exp_f32_e32 v180, v180
	v_exp_f32_e32 v181, v181
	v_fma_f32 v182, |v158|, s38, 1.0
	v_fma_f32 v183, |v159|, s38, 1.0
	v_pk_fma_f32 v[176:177], v[178:179], v[176:177], s[46:47] op_sel_hi:[1,1,0]
	v_rcp_f32_e32 v182, v182
	v_rcp_f32_e32 v183, v183
	v_pk_fma_f32 v[176:177], v[178:179], v[176:177], s[48:49] op_sel_hi:[1,1,0]
	v_max_f32_e32 v174, 0, v170
	v_pk_mul_f32 v[176:177], v[178:179], v[176:177]
	v_pk_mul_f32 v[178:179], v[158:159], v[158:159]
	v_max_f32_e32 v175, 0, v171
	v_pk_mul_f32 v[176:177], v[180:181], v[176:177]
	v_max_f32_e32 v154, 0, v158
	v_fma_f32 v170, -|v170|, v176, v174
	v_fma_f32 v171, -|v171|, v177, v175
	v_pk_fma_f32 v[174:175], v[182:183], s[40:41], v[146:147] op_sel_hi:[1,0,0]
	v_pk_mul_f32 v[176:177], v[178:179], s[50:51] op_sel_hi:[1,0]
	v_pk_fma_f32 v[174:175], v[182:183], v[174:175], s[44:45] op_sel_hi:[1,1,0]
	v_exp_f32_e32 v176, v176
	v_exp_f32_e32 v177, v177
	v_pk_fma_f32 v[174:175], v[182:183], v[174:175], s[46:47] op_sel_hi:[1,1,0]
	v_max_f32_e32 v155, 0, v159
	v_pk_fma_f32 v[174:175], v[182:183], v[174:175], s[48:49] op_sel_hi:[1,1,0]
	s_mov_b64 s[0:1], 0x40000
	v_pk_mul_f32 v[174:175], v[182:183], v[174:175]
	s_mov_b64 s[74:75], 0
	v_pk_mul_f32 v[174:175], v[176:177], v[174:175]
	s_nop 0
	v_fma_f32 v158, -|v158|, v174, v154
	v_fma_f32 v159, -|v159|, v175, v155
	v_cvt_pk_bf16_f32 v154, v156, v157
	v_cvt_pk_bf16_f32 v155, v172, v173
	v_cvt_pk_bf16_f32 v156, v170, v171
	v_pk_add_f32 v[174:175], v[112:113], 0 op_sel_hi:[1,0]
	v_cvt_pk_bf16_f32 v157, v158, v159
	global_store_dwordx4 v[148:149], v[154:157], off
	v_pk_add_f32 v[158:159], v[114:115], 0 op_sel_hi:[1,0]
	s_nop 0
	v_pk_add_f32 v[156:157], v[116:117], 0 op_sel_hi:[1,0]
	v_pk_add_f32 v[154:155], v[118:119], 0 op_sel_hi:[1,0]
	v_fma_f32 v172, |v156|, s38, 1.0
	v_fma_f32 v173, |v157|, s38, 1.0
	v_pk_mul_f32 v[180:181], v[156:157], v[156:157]
	v_rcp_f32_e32 v172, v172
	v_rcp_f32_e32 v173, v173
	v_pk_mul_f32 v[180:181], v[180:181], s[50:51] op_sel_hi:[1,0]
	v_pk_fma_f32 v[178:179], v[172:173], s[40:41], v[146:147] op_sel_hi:[1,0,0]
	v_exp_f32_e32 v180, v180
	v_pk_fma_f32 v[178:179], v[172:173], v[178:179], s[44:45] op_sel_hi:[1,1,0]
	v_exp_f32_e32 v181, v181
	v_fma_f32 v182, |v154|, s38, 1.0
	v_fma_f32 v183, |v155|, s38, 1.0
	v_pk_fma_f32 v[178:179], v[172:173], v[178:179], s[46:47] op_sel_hi:[1,1,0]
	v_rcp_f32_e32 v182, v182
	v_rcp_f32_e32 v183, v183
	v_pk_fma_f32 v[178:179], v[172:173], v[178:179], s[48:49] op_sel_hi:[1,1,0]
	v_max_f32_e32 v170, 0, v156
	v_pk_mul_f32 v[172:173], v[172:173], v[178:179]
	v_pk_mul_f32 v[178:179], v[154:155], v[154:155]
	v_max_f32_e32 v171, 0, v157
	v_pk_mul_f32 v[172:173], v[180:181], v[172:173]
	v_max_f32_e32 v176, 0, v154
	v_fma_f32 v156, -|v156|, v172, v170
	v_fma_f32 v157, -|v157|, v173, v171
	v_pk_fma_f32 v[170:171], v[182:183], s[40:41], v[146:147] op_sel_hi:[1,0,0]
	v_pk_mul_f32 v[172:173], v[178:179], s[50:51] op_sel_hi:[1,0]
	v_pk_fma_f32 v[170:171], v[182:183], v[170:171], s[44:45] op_sel_hi:[1,1,0]
	v_exp_f32_e32 v172, v172
	v_exp_f32_e32 v173, v173
	v_pk_fma_f32 v[170:171], v[182:183], v[170:171], s[46:47] op_sel_hi:[1,1,0]
	v_max_f32_e32 v177, 0, v155
	v_pk_fma_f32 v[170:171], v[182:183], v[170:171], s[48:49] op_sel_hi:[1,1,0]
	v_pk_mul_f32 v[180:181], v[174:175], v[174:175]
	v_pk_mul_f32 v[170:171], v[182:183], v[170:171]
	v_pk_mul_f32 v[180:181], v[180:181], s[50:51] op_sel_hi:[1,0]
	v_pk_mul_f32 v[170:171], v[172:173], v[170:171]
	v_fma_f32 v178, |v174|, s38, 1.0
	v_fma_f32 v179, |v175|, s38, 1.0
	v_fma_f32 v170, -|v154|, v170, v176
	v_fma_f32 v171, -|v155|, v171, v177
	v_rcp_f32_e32 v178, v178
	v_rcp_f32_e32 v179, v179
	v_exp_f32_e32 v180, v180
	v_pk_fma_f32 v[176:177], v[178:179], s[40:41], v[146:147] op_sel_hi:[1,0,0]
	v_exp_f32_e32 v181, v181
	v_pk_fma_f32 v[176:177], v[178:179], v[176:177], s[44:45] op_sel_hi:[1,1,0]
	v_fma_f32 v182, |v158|, s38, 1.0
	v_fma_f32 v183, |v159|, s38, 1.0
	v_pk_fma_f32 v[176:177], v[178:179], v[176:177], s[46:47] op_sel_hi:[1,1,0]
	v_rcp_f32_e32 v182, v182
	v_rcp_f32_e32 v183, v183
	v_pk_fma_f32 v[176:177], v[178:179], v[176:177], s[48:49] op_sel_hi:[1,1,0]
	v_max_f32_e32 v172, 0, v174
	v_pk_mul_f32 v[176:177], v[178:179], v[176:177]
	v_pk_mul_f32 v[178:179], v[158:159], v[158:159]
	v_max_f32_e32 v173, 0, v175
	v_pk_mul_f32 v[176:177], v[180:181], v[176:177]
	v_max_f32_e32 v154, 0, v158
	v_fma_f32 v172, -|v174|, v176, v172
	v_fma_f32 v173, -|v175|, v177, v173
	v_pk_fma_f32 v[174:175], v[182:183], s[40:41], v[146:147] op_sel_hi:[1,0,0]
	v_pk_mul_f32 v[176:177], v[178:179], s[50:51] op_sel_hi:[1,0]
	v_pk_fma_f32 v[174:175], v[182:183], v[174:175], s[44:45] op_sel_hi:[1,1,0]
	v_exp_f32_e32 v176, v176
	v_exp_f32_e32 v177, v177
	v_pk_fma_f32 v[174:175], v[182:183], v[174:175], s[46:47] op_sel_hi:[1,1,0]
	v_max_f32_e32 v155, 0, v159
	v_pk_fma_f32 v[174:175], v[182:183], v[174:175], s[48:49] op_sel_hi:[1,1,0]
	s_nop 0
	v_pk_mul_f32 v[174:175], v[182:183], v[174:175]
	s_nop 0
	v_pk_mul_f32 v[174:175], v[176:177], v[174:175]
	v_pk_add_f32 v[176:177], v[104:105], 0 op_sel_hi:[1,0]
	v_fma_f32 v158, -|v158|, v174, v154
	v_fma_f32 v159, -|v159|, v175, v155
	v_cvt_pk_bf16_f32 v154, v156, v157
	v_cvt_pk_bf16_f32 v155, v170, v171
	v_cvt_pk_bf16_f32 v156, v172, v173
	v_pk_add_f32 v[170:171], v[106:107], 0 op_sel_hi:[1,0]
	v_cvt_pk_bf16_f32 v157, v158, v159
	v_pk_add_f32 v[158:159], v[108:109], 0 op_sel_hi:[1,0]
	global_store_dwordx4 v[148:149], v[154:157], off offset:256
	v_fma_f32 v174, |v158|, s38, 1.0
	v_fma_f32 v175, |v159|, s38, 1.0
	v_pk_add_f32 v[156:157], v[110:111], 0 op_sel_hi:[1,0]
	v_rcp_f32_e32 v174, v174
	v_rcp_f32_e32 v175, v175
	v_pk_mul_f32 v[182:183], v[158:159], v[158:159]
	v_pk_fma_f32 v[180:181], v[174:175], s[40:41], v[146:147] op_sel_hi:[1,0,0]
	v_pk_mul_f32 v[182:183], v[182:183], s[50:51] op_sel_hi:[1,0]
	v_pk_fma_f32 v[180:181], v[174:175], v[180:181], s[44:45] op_sel_hi:[1,1,0]
	v_exp_f32_e32 v182, v182
	v_exp_f32_e32 v183, v183
	v_fma_f32 v184, |v156|, s38, 1.0
	v_fma_f32 v185, |v157|, s38, 1.0
	v_pk_fma_f32 v[180:181], v[174:175], v[180:181], s[46:47] op_sel_hi:[1,1,0]
	v_rcp_f32_e32 v184, v184
	v_rcp_f32_e32 v185, v185
	v_pk_fma_f32 v[180:181], v[174:175], v[180:181], s[48:49] op_sel_hi:[1,1,0]
	v_max_f32_e32 v172, 0, v158
	v_pk_mul_f32 v[174:175], v[174:175], v[180:181]
	v_pk_mul_f32 v[180:181], v[156:157], v[156:157]
	v_max_f32_e32 v173, 0, v159
	v_pk_mul_f32 v[174:175], v[182:183], v[174:175]
	v_max_f32_e32 v178, 0, v156
	v_fma_f32 v158, -|v158|, v174, v172
	v_fma_f32 v159, -|v159|, v175, v173
	v_pk_fma_f32 v[172:173], v[184:185], s[40:41], v[146:147] op_sel_hi:[1,0,0]
	v_pk_mul_f32 v[174:175], v[180:181], s[50:51] op_sel_hi:[1,0]
	v_pk_fma_f32 v[172:173], v[184:185], v[172:173], s[44:45] op_sel_hi:[1,1,0]
	v_exp_f32_e32 v174, v174
	v_exp_f32_e32 v175, v175
	v_pk_fma_f32 v[172:173], v[184:185], v[172:173], s[46:47] op_sel_hi:[1,1,0]
	v_max_f32_e32 v179, 0, v157
	v_pk_fma_f32 v[172:173], v[184:185], v[172:173], s[48:49] op_sel_hi:[1,1,0]
	v_pk_mul_f32 v[182:183], v[176:177], v[176:177]
	v_pk_mul_f32 v[172:173], v[184:185], v[172:173]
	v_pk_mul_f32 v[182:183], v[182:183], s[50:51] op_sel_hi:[1,0]
	v_pk_mul_f32 v[172:173], v[174:175], v[172:173]
	v_fma_f32 v180, |v176|, s38, 1.0
	v_fma_f32 v181, |v177|, s38, 1.0
	v_fma_f32 v172, -|v156|, v172, v178
	v_fma_f32 v173, -|v157|, v173, v179
	v_rcp_f32_e32 v180, v180
	v_rcp_f32_e32 v181, v181
	v_exp_f32_e32 v182, v182
	v_pk_fma_f32 v[178:179], v[180:181], s[40:41], v[146:147] op_sel_hi:[1,0,0]
	v_exp_f32_e32 v183, v183
	v_pk_fma_f32 v[178:179], v[180:181], v[178:179], s[44:45] op_sel_hi:[1,1,0]
	v_fma_f32 v184, |v170|, s38, 1.0
	v_fma_f32 v185, |v171|, s38, 1.0
	v_pk_fma_f32 v[178:179], v[180:181], v[178:179], s[46:47] op_sel_hi:[1,1,0]
	v_rcp_f32_e32 v184, v184
	v_rcp_f32_e32 v185, v185
	v_pk_fma_f32 v[178:179], v[180:181], v[178:179], s[48:49] op_sel_hi:[1,1,0]
	v_max_f32_e32 v174, 0, v176
	v_pk_mul_f32 v[178:179], v[180:181], v[178:179]
	v_pk_mul_f32 v[180:181], v[170:171], v[170:171]
	v_max_f32_e32 v175, 0, v177
	v_pk_mul_f32 v[178:179], v[182:183], v[178:179]
	v_or_b32_e32 v154, 16, v152
	v_fma_f32 v174, -|v176|, v178, v174
	v_fma_f32 v175, -|v177|, v179, v175
	v_pk_fma_f32 v[176:177], v[184:185], s[40:41], v[146:147] op_sel_hi:[1,0,0]
	v_pk_mul_f32 v[178:179], v[180:181], s[50:51] op_sel_hi:[1,0]
	v_pk_fma_f32 v[176:177], v[184:185], v[176:177], s[44:45] op_sel_hi:[1,1,0]
	v_exp_f32_e32 v178, v178
	v_exp_f32_e32 v179, v179
	v_pk_fma_f32 v[176:177], v[184:185], v[176:177], s[46:47] op_sel_hi:[1,1,0]
	v_ashrrev_i32_e32 v155, 31, v154
	v_pk_fma_f32 v[176:177], v[184:185], v[176:177], s[48:49] op_sel_hi:[1,1,0]
	v_lshlrev_b64 v[154:155], 11, v[154:155]
	v_pk_mul_f32 v[176:177], v[184:185], v[176:177]
	v_max_f32_e32 v156, 0, v170
	v_max_f32_e32 v157, 0, v171
	v_pk_mul_f32 v[176:177], v[178:179], v[176:177]
	v_lshl_add_u64 v[154:155], v[150:151], 0, v[154:155]
	v_fma_f32 v170, -|v170|, v176, v156
	v_fma_f32 v171, -|v171|, v177, v157
	v_cvt_pk_bf16_f32 v156, v158, v159
	v_cvt_pk_bf16_f32 v157, v172, v173
	v_cvt_pk_bf16_f32 v158, v174, v175
	v_pk_add_f32 v[176:177], v[96:97], 0 op_sel_hi:[1,0]
	v_cvt_pk_bf16_f32 v159, v170, v171
	global_store_dwordx4 v[154:155], v[156:159], off
	v_pk_add_f32 v[170:171], v[98:99], 0 op_sel_hi:[1,0]
	s_nop 0
	v_pk_add_f32 v[158:159], v[100:101], 0 op_sel_hi:[1,0]
	v_pk_add_f32 v[156:157], v[102:103], 0 op_sel_hi:[1,0]
	v_fma_f32 v174, |v158|, s38, 1.0
	v_fma_f32 v175, |v159|, s38, 1.0
	v_pk_mul_f32 v[182:183], v[158:159], v[158:159]
	v_rcp_f32_e32 v174, v174
	v_rcp_f32_e32 v175, v175
	v_pk_mul_f32 v[182:183], v[182:183], s[50:51] op_sel_hi:[1,0]
	v_pk_fma_f32 v[180:181], v[174:175], s[40:41], v[146:147] op_sel_hi:[1,0,0]
	v_exp_f32_e32 v182, v182
	v_pk_fma_f32 v[180:181], v[174:175], v[180:181], s[44:45] op_sel_hi:[1,1,0]
	v_exp_f32_e32 v183, v183
	v_fma_f32 v184, |v156|, s38, 1.0
	v_fma_f32 v185, |v157|, s38, 1.0
	v_pk_fma_f32 v[180:181], v[174:175], v[180:181], s[46:47] op_sel_hi:[1,1,0]
	v_rcp_f32_e32 v184, v184
	v_rcp_f32_e32 v185, v185
	v_pk_fma_f32 v[180:181], v[174:175], v[180:181], s[48:49] op_sel_hi:[1,1,0]
	v_max_f32_e32 v172, 0, v158
	v_pk_mul_f32 v[174:175], v[174:175], v[180:181]
	v_pk_mul_f32 v[180:181], v[156:157], v[156:157]
	v_max_f32_e32 v173, 0, v159
	v_pk_mul_f32 v[174:175], v[182:183], v[174:175]
	v_max_f32_e32 v178, 0, v156
	v_fma_f32 v158, -|v158|, v174, v172
	v_fma_f32 v159, -|v159|, v175, v173
	v_pk_fma_f32 v[172:173], v[184:185], s[40:41], v[146:147] op_sel_hi:[1,0,0]
	v_pk_mul_f32 v[174:175], v[180:181], s[50:51] op_sel_hi:[1,0]
	v_pk_fma_f32 v[172:173], v[184:185], v[172:173], s[44:45] op_sel_hi:[1,1,0]
	v_exp_f32_e32 v174, v174
	v_exp_f32_e32 v175, v175
	v_pk_fma_f32 v[172:173], v[184:185], v[172:173], s[46:47] op_sel_hi:[1,1,0]
	v_max_f32_e32 v179, 0, v157
	v_pk_fma_f32 v[172:173], v[184:185], v[172:173], s[48:49] op_sel_hi:[1,1,0]
	v_pk_mul_f32 v[182:183], v[176:177], v[176:177]
	v_pk_mul_f32 v[172:173], v[184:185], v[172:173]
	v_pk_mul_f32 v[182:183], v[182:183], s[50:51] op_sel_hi:[1,0]
	v_pk_mul_f32 v[172:173], v[174:175], v[172:173]
	v_fma_f32 v180, |v176|, s38, 1.0
	v_fma_f32 v181, |v177|, s38, 1.0
	v_fma_f32 v172, -|v156|, v172, v178
	v_fma_f32 v173, -|v157|, v173, v179
	v_rcp_f32_e32 v180, v180
	v_rcp_f32_e32 v181, v181
	v_exp_f32_e32 v182, v182
	v_pk_fma_f32 v[178:179], v[180:181], s[40:41], v[146:147] op_sel_hi:[1,0,0]
	v_exp_f32_e32 v183, v183
	v_pk_fma_f32 v[178:179], v[180:181], v[178:179], s[44:45] op_sel_hi:[1,1,0]
	v_fma_f32 v184, |v170|, s38, 1.0
	v_fma_f32 v185, |v171|, s38, 1.0
	v_pk_fma_f32 v[178:179], v[180:181], v[178:179], s[46:47] op_sel_hi:[1,1,0]
	v_rcp_f32_e32 v184, v184
	v_rcp_f32_e32 v185, v185
	v_pk_fma_f32 v[178:179], v[180:181], v[178:179], s[48:49] op_sel_hi:[1,1,0]
	v_max_f32_e32 v174, 0, v176
	v_pk_mul_f32 v[178:179], v[180:181], v[178:179]
	v_pk_mul_f32 v[180:181], v[170:171], v[170:171]
	v_max_f32_e32 v175, 0, v177
	v_pk_mul_f32 v[178:179], v[182:183], v[178:179]
	v_max_f32_e32 v156, 0, v170
	v_fma_f32 v174, -|v176|, v178, v174
	v_fma_f32 v175, -|v177|, v179, v175
	v_pk_fma_f32 v[176:177], v[184:185], s[40:41], v[146:147] op_sel_hi:[1,0,0]
	v_pk_mul_f32 v[178:179], v[180:181], s[50:51] op_sel_hi:[1,0]
	v_pk_fma_f32 v[176:177], v[184:185], v[176:177], s[44:45] op_sel_hi:[1,1,0]
	v_exp_f32_e32 v178, v178
	v_exp_f32_e32 v179, v179
	v_pk_fma_f32 v[176:177], v[184:185], v[176:177], s[46:47] op_sel_hi:[1,1,0]
	v_max_f32_e32 v157, 0, v171
	v_pk_fma_f32 v[176:177], v[184:185], v[176:177], s[48:49] op_sel_hi:[1,1,0]
	s_nop 0
	v_pk_mul_f32 v[176:177], v[184:185], v[176:177]
	s_nop 0
	v_pk_mul_f32 v[176:177], v[178:179], v[176:177]
	s_nop 0
	v_fma_f32 v170, -|v170|, v176, v156
	v_fma_f32 v171, -|v171|, v177, v157
	v_cvt_pk_bf16_f32 v156, v158, v159
	v_cvt_pk_bf16_f32 v157, v172, v173
	v_cvt_pk_bf16_f32 v158, v174, v175
	v_pk_add_f32 v[176:177], v[88:89], 0 op_sel_hi:[1,0]
	v_cvt_pk_bf16_f32 v159, v170, v171
	global_store_dwordx4 v[154:155], v[156:159], off offset:256
	v_pk_add_f32 v[170:171], v[90:91], 0 op_sel_hi:[1,0]
	v_or_b32_e32 v154, 32, v152
	v_pk_add_f32 v[158:159], v[92:93], 0 op_sel_hi:[1,0]
	v_pk_add_f32 v[156:157], v[94:95], 0 op_sel_hi:[1,0]
	v_fma_f32 v174, |v158|, s38, 1.0
	v_fma_f32 v175, |v159|, s38, 1.0
	v_pk_mul_f32 v[182:183], v[158:159], v[158:159]
	v_rcp_f32_e32 v174, v174
	v_rcp_f32_e32 v175, v175
	v_pk_mul_f32 v[182:183], v[182:183], s[50:51] op_sel_hi:[1,0]
	v_pk_fma_f32 v[180:181], v[174:175], s[40:41], v[146:147] op_sel_hi:[1,0,0]
	v_exp_f32_e32 v182, v182
	v_pk_fma_f32 v[180:181], v[174:175], v[180:181], s[44:45] op_sel_hi:[1,1,0]
	v_exp_f32_e32 v183, v183
	v_fma_f32 v184, |v156|, s38, 1.0
	v_fma_f32 v185, |v157|, s38, 1.0
	v_pk_fma_f32 v[180:181], v[174:175], v[180:181], s[46:47] op_sel_hi:[1,1,0]
	v_rcp_f32_e32 v184, v184
	v_rcp_f32_e32 v185, v185
	v_pk_fma_f32 v[180:181], v[174:175], v[180:181], s[48:49] op_sel_hi:[1,1,0]
	v_max_f32_e32 v172, 0, v158
	v_pk_mul_f32 v[174:175], v[174:175], v[180:181]
	v_pk_mul_f32 v[180:181], v[156:157], v[156:157]
	v_max_f32_e32 v173, 0, v159
	v_pk_mul_f32 v[174:175], v[182:183], v[174:175]
	v_max_f32_e32 v178, 0, v156
	v_fma_f32 v158, -|v158|, v174, v172
	v_fma_f32 v159, -|v159|, v175, v173
	v_pk_fma_f32 v[172:173], v[184:185], s[40:41], v[146:147] op_sel_hi:[1,0,0]
	v_pk_mul_f32 v[174:175], v[180:181], s[50:51] op_sel_hi:[1,0]
	v_pk_fma_f32 v[172:173], v[184:185], v[172:173], s[44:45] op_sel_hi:[1,1,0]
	v_exp_f32_e32 v174, v174
	v_exp_f32_e32 v175, v175
	v_pk_fma_f32 v[172:173], v[184:185], v[172:173], s[46:47] op_sel_hi:[1,1,0]
	v_max_f32_e32 v179, 0, v157
	v_pk_fma_f32 v[172:173], v[184:185], v[172:173], s[48:49] op_sel_hi:[1,1,0]
	v_pk_mul_f32 v[182:183], v[176:177], v[176:177]
	v_pk_mul_f32 v[172:173], v[184:185], v[172:173]
	v_pk_mul_f32 v[182:183], v[182:183], s[50:51] op_sel_hi:[1,0]
	v_pk_mul_f32 v[172:173], v[174:175], v[172:173]
	v_fma_f32 v180, |v176|, s38, 1.0
	v_fma_f32 v181, |v177|, s38, 1.0
	v_fma_f32 v172, -|v156|, v172, v178
	v_fma_f32 v173, -|v157|, v173, v179
	v_rcp_f32_e32 v180, v180
	v_rcp_f32_e32 v181, v181
	v_exp_f32_e32 v182, v182
	v_pk_fma_f32 v[178:179], v[180:181], s[40:41], v[146:147] op_sel_hi:[1,0,0]
	v_exp_f32_e32 v183, v183
	v_pk_fma_f32 v[178:179], v[180:181], v[178:179], s[44:45] op_sel_hi:[1,1,0]
	v_fma_f32 v184, |v170|, s38, 1.0
	v_fma_f32 v185, |v171|, s38, 1.0
	v_pk_fma_f32 v[178:179], v[180:181], v[178:179], s[46:47] op_sel_hi:[1,1,0]
	v_rcp_f32_e32 v184, v184
	v_rcp_f32_e32 v185, v185
	v_pk_fma_f32 v[178:179], v[180:181], v[178:179], s[48:49] op_sel_hi:[1,1,0]
	v_max_f32_e32 v174, 0, v176
	v_pk_mul_f32 v[178:179], v[180:181], v[178:179]
	v_pk_mul_f32 v[180:181], v[170:171], v[170:171]
	v_max_f32_e32 v175, 0, v177
	v_pk_mul_f32 v[178:179], v[182:183], v[178:179]
	v_ashrrev_i32_e32 v155, 31, v154
	v_fma_f32 v174, -|v176|, v178, v174
	v_fma_f32 v175, -|v177|, v179, v175
	v_pk_fma_f32 v[176:177], v[184:185], s[40:41], v[146:147] op_sel_hi:[1,0,0]
	v_pk_mul_f32 v[178:179], v[180:181], s[50:51] op_sel_hi:[1,0]
	v_pk_fma_f32 v[176:177], v[184:185], v[176:177], s[44:45] op_sel_hi:[1,1,0]
	v_exp_f32_e32 v178, v178
	v_exp_f32_e32 v179, v179
	v_pk_fma_f32 v[176:177], v[184:185], v[176:177], s[46:47] op_sel_hi:[1,1,0]
	v_lshlrev_b64 v[154:155], 11, v[154:155]
	v_pk_fma_f32 v[176:177], v[184:185], v[176:177], s[48:49] op_sel_hi:[1,1,0]
	v_max_f32_e32 v156, 0, v170
	v_pk_mul_f32 v[176:177], v[184:185], v[176:177]
	v_max_f32_e32 v157, 0, v171
	v_pk_mul_f32 v[176:177], v[178:179], v[176:177]
	v_lshl_add_u64 v[154:155], v[150:151], 0, v[154:155]
	v_fma_f32 v170, -|v170|, v176, v156
	v_fma_f32 v171, -|v171|, v177, v157
	v_cvt_pk_bf16_f32 v156, v158, v159
	v_cvt_pk_bf16_f32 v157, v172, v173
	v_cvt_pk_bf16_f32 v158, v174, v175
	v_pk_add_f32 v[176:177], v[80:81], 0 op_sel_hi:[1,0]
	v_cvt_pk_bf16_f32 v159, v170, v171
	global_store_dwordx4 v[154:155], v[156:159], off
	v_pk_add_f32 v[170:171], v[82:83], 0 op_sel_hi:[1,0]
	v_or_b32_e32 v152, 48, v152
	v_pk_add_f32 v[158:159], v[84:85], 0 op_sel_hi:[1,0]
	v_pk_add_f32 v[156:157], v[86:87], 0 op_sel_hi:[1,0]
	v_fma_f32 v174, |v158|, s38, 1.0
	v_fma_f32 v175, |v159|, s38, 1.0
	v_pk_mul_f32 v[182:183], v[158:159], v[158:159]
	v_rcp_f32_e32 v174, v174
	v_rcp_f32_e32 v175, v175
	v_pk_mul_f32 v[182:183], v[182:183], s[50:51] op_sel_hi:[1,0]
	v_pk_fma_f32 v[180:181], v[174:175], s[40:41], v[146:147] op_sel_hi:[1,0,0]
	v_exp_f32_e32 v182, v182
	v_pk_fma_f32 v[180:181], v[174:175], v[180:181], s[44:45] op_sel_hi:[1,1,0]
	v_exp_f32_e32 v183, v183
	v_fma_f32 v184, |v156|, s38, 1.0
	v_fma_f32 v185, |v157|, s38, 1.0
	v_pk_fma_f32 v[180:181], v[174:175], v[180:181], s[46:47] op_sel_hi:[1,1,0]
	v_rcp_f32_e32 v184, v184
	v_rcp_f32_e32 v185, v185
	v_pk_fma_f32 v[180:181], v[174:175], v[180:181], s[48:49] op_sel_hi:[1,1,0]
	v_max_f32_e32 v172, 0, v158
	v_pk_mul_f32 v[174:175], v[174:175], v[180:181]
	v_pk_mul_f32 v[180:181], v[156:157], v[156:157]
	v_max_f32_e32 v173, 0, v159
	v_pk_mul_f32 v[174:175], v[182:183], v[174:175]
	v_max_f32_e32 v178, 0, v156
	v_fma_f32 v158, -|v158|, v174, v172
	v_fma_f32 v159, -|v159|, v175, v173
	v_pk_fma_f32 v[172:173], v[184:185], s[40:41], v[146:147] op_sel_hi:[1,0,0]
	v_pk_mul_f32 v[174:175], v[180:181], s[50:51] op_sel_hi:[1,0]
	v_pk_fma_f32 v[172:173], v[184:185], v[172:173], s[44:45] op_sel_hi:[1,1,0]
	v_exp_f32_e32 v174, v174
	v_exp_f32_e32 v175, v175
	v_pk_fma_f32 v[172:173], v[184:185], v[172:173], s[46:47] op_sel_hi:[1,1,0]
	v_max_f32_e32 v179, 0, v157
	v_pk_fma_f32 v[172:173], v[184:185], v[172:173], s[48:49] op_sel_hi:[1,1,0]
	v_pk_mul_f32 v[182:183], v[176:177], v[176:177]
	v_pk_mul_f32 v[172:173], v[184:185], v[172:173]
	v_pk_mul_f32 v[182:183], v[182:183], s[50:51] op_sel_hi:[1,0]
	v_pk_mul_f32 v[172:173], v[174:175], v[172:173]
	v_fma_f32 v180, |v176|, s38, 1.0
	v_fma_f32 v181, |v177|, s38, 1.0
	v_fma_f32 v172, -|v156|, v172, v178
	v_fma_f32 v173, -|v157|, v173, v179
	v_rcp_f32_e32 v180, v180
	v_rcp_f32_e32 v181, v181
	v_exp_f32_e32 v182, v182
	v_pk_fma_f32 v[178:179], v[180:181], s[40:41], v[146:147] op_sel_hi:[1,0,0]
	v_exp_f32_e32 v183, v183
	v_pk_fma_f32 v[178:179], v[180:181], v[178:179], s[44:45] op_sel_hi:[1,1,0]
	v_fma_f32 v184, |v170|, s38, 1.0
	v_fma_f32 v185, |v171|, s38, 1.0
	v_pk_fma_f32 v[178:179], v[180:181], v[178:179], s[46:47] op_sel_hi:[1,1,0]
	v_rcp_f32_e32 v184, v184
	v_rcp_f32_e32 v185, v185
	v_pk_fma_f32 v[178:179], v[180:181], v[178:179], s[48:49] op_sel_hi:[1,1,0]
	v_max_f32_e32 v174, 0, v176
	v_pk_mul_f32 v[178:179], v[180:181], v[178:179]
	v_pk_mul_f32 v[180:181], v[170:171], v[170:171]
	v_max_f32_e32 v175, 0, v177
	v_pk_mul_f32 v[178:179], v[182:183], v[178:179]
	v_max_f32_e32 v156, 0, v170
	v_fma_f32 v174, -|v176|, v178, v174
	v_fma_f32 v175, -|v177|, v179, v175
	v_pk_fma_f32 v[176:177], v[184:185], s[40:41], v[146:147] op_sel_hi:[1,0,0]
	v_pk_mul_f32 v[178:179], v[180:181], s[50:51] op_sel_hi:[1,0]
	v_pk_fma_f32 v[176:177], v[184:185], v[176:177], s[44:45] op_sel_hi:[1,1,0]
	v_exp_f32_e32 v178, v178
	v_exp_f32_e32 v179, v179
	v_pk_fma_f32 v[176:177], v[184:185], v[176:177], s[46:47] op_sel_hi:[1,1,0]
	v_max_f32_e32 v157, 0, v171
	v_pk_fma_f32 v[176:177], v[184:185], v[176:177], s[48:49] op_sel_hi:[1,1,0]
	v_ashrrev_i32_e32 v153, 31, v152
	v_pk_mul_f32 v[176:177], v[184:185], v[176:177]
	v_lshlrev_b64 v[152:153], 11, v[152:153]
	v_pk_mul_f32 v[176:177], v[178:179], v[176:177]
	v_lshl_add_u64 v[150:151], v[150:151], 0, v[152:153]
	v_fma_f32 v170, -|v170|, v176, v156
	v_fma_f32 v171, -|v171|, v177, v157
	v_cvt_pk_bf16_f32 v156, v158, v159
	v_cvt_pk_bf16_f32 v157, v172, v173
	v_cvt_pk_bf16_f32 v158, v174, v175
	v_pk_add_f32 v[152:153], v[78:79], 0 op_sel_hi:[1,0]
	v_cvt_pk_bf16_f32 v159, v170, v171
	global_store_dwordx4 v[154:155], v[156:159], off offset:256
	v_pk_add_f32 v[154:155], v[76:77], 0 op_sel_hi:[1,0]
	v_and_b32_e32 v175, 0x7fffffff, v153
	v_fma_f32 v170, |v154|, s38, 1.0
	v_fma_f32 v171, |v155|, s38, 1.0
	v_pk_mul_f32 v[178:179], v[154:155], v[154:155]
	v_rcp_f32_e32 v170, v170
	v_rcp_f32_e32 v171, v171
	v_and_b32_e32 v174, 0x7fffffff, v152
	v_pk_mul_f32 v[178:179], v[178:179], s[50:51] op_sel_hi:[1,0]
	v_pk_fma_f32 v[180:181], v[174:175], s[38:39], 1.0 op_sel_hi:[1,0,0]
	v_pk_fma_f32 v[176:177], v[170:171], s[40:41], v[146:147] op_sel_hi:[1,0,0]
	v_exp_f32_e32 v178, v178
	v_pk_fma_f32 v[176:177], v[170:171], v[176:177], s[44:45] op_sel_hi:[1,1,0]
	v_exp_f32_e32 v179, v179
	v_pk_fma_f32 v[176:177], v[170:171], v[176:177], s[46:47] op_sel_hi:[1,1,0]
	v_rcp_f32_e32 v180, v180
	v_rcp_f32_e32 v181, v181
	v_pk_fma_f32 v[176:177], v[170:171], v[176:177], s[48:49] op_sel_hi:[1,1,0]
	v_max_f32_e32 v158, 0, v154
	v_pk_mul_f32 v[170:171], v[170:171], v[176:177]
	v_pk_mul_f32 v[176:177], v[152:153], v[152:153]
	v_max_f32_e32 v159, 0, v155
	v_pk_mul_f32 v[170:171], v[178:179], v[170:171]
	v_pk_add_f32 v[172:173], v[72:73], 0 op_sel_hi:[1,0]
	v_fma_f32 v154, -|v154|, v170, v158
	v_fma_f32 v155, -|v155|, v171, v159
	v_pk_fma_f32 v[158:159], v[180:181], s[40:41], v[146:147] op_sel_hi:[1,0,0]
	v_pk_mul_f32 v[170:171], v[176:177], s[50:51] op_sel_hi:[1,0]
	v_pk_fma_f32 v[158:159], v[180:181], v[158:159], s[44:45] op_sel_hi:[1,1,0]
	v_exp_f32_e32 v170, v170
	v_exp_f32_e32 v171, v171
	v_pk_fma_f32 v[158:159], v[180:181], v[158:159], s[46:47] op_sel_hi:[1,1,0]
	v_pk_add_f32 v[156:157], v[74:75], 0 op_sel_hi:[1,0]
	v_pk_fma_f32 v[158:159], v[180:181], v[158:159], s[48:49] op_sel_hi:[1,1,0]
	v_max_f32_e32 v152, 0, v152
	v_pk_mul_f32 v[158:159], v[180:181], v[158:159]
	v_max_f32_e32 v153, 0, v153
	v_pk_mul_f32 v[158:159], v[170:171], v[158:159]
	v_fma_f32 v176, |v172|, s38, 1.0
	v_fma_f32 v177, |v173|, s38, 1.0
	v_pk_mul_f32 v[178:179], v[172:173], v[172:173]
	v_rcp_f32_e32 v176, v176
	v_rcp_f32_e32 v177, v177
	v_pk_fma_f32 v[158:159], v[174:175], v[158:159], v[152:153] neg_lo:[1,0,0] neg_hi:[1,0,0]
	v_pk_fma_f32 v[174:175], v[176:177], s[40:41], v[146:147] op_sel_hi:[1,0,0]
	v_pk_mul_f32 v[178:179], v[178:179], s[50:51] op_sel_hi:[1,0]
	v_pk_fma_f32 v[174:175], v[176:177], v[174:175], s[44:45] op_sel_hi:[1,1,0]
	v_exp_f32_e32 v178, v178
	v_exp_f32_e32 v179, v179
	v_fma_f32 v180, |v156|, s38, 1.0
	v_fma_f32 v181, |v157|, s38, 1.0
	v_pk_fma_f32 v[174:175], v[176:177], v[174:175], s[46:47] op_sel_hi:[1,1,0]
	v_rcp_f32_e32 v180, v180
	v_rcp_f32_e32 v181, v181
	v_pk_fma_f32 v[174:175], v[176:177], v[174:175], s[48:49] op_sel_hi:[1,1,0]
	v_max_f32_e32 v170, 0, v172
	v_pk_mul_f32 v[174:175], v[176:177], v[174:175]
	v_pk_mul_f32 v[176:177], v[156:157], v[156:157]
	v_max_f32_e32 v171, 0, v173
	v_pk_mul_f32 v[174:175], v[178:179], v[174:175]
	v_max_f32_e32 v152, 0, v156
	v_fma_f32 v170, -|v172|, v174, v170
	v_fma_f32 v171, -|v173|, v175, v171
	v_pk_fma_f32 v[172:173], v[180:181], s[40:41], v[146:147] op_sel_hi:[1,0,0]
	v_pk_mul_f32 v[174:175], v[176:177], s[50:51] op_sel_hi:[1,0]
	v_pk_fma_f32 v[172:173], v[180:181], v[172:173], s[44:45] op_sel_hi:[1,1,0]
	v_exp_f32_e32 v174, v174
	v_exp_f32_e32 v175, v175
	v_pk_fma_f32 v[172:173], v[180:181], v[172:173], s[46:47] op_sel_hi:[1,1,0]
	v_max_f32_e32 v153, 0, v157
	v_pk_fma_f32 v[172:173], v[180:181], v[172:173], s[48:49] op_sel_hi:[1,1,0]
	s_nop 0
	v_pk_mul_f32 v[172:173], v[180:181], v[172:173]
	s_nop 0
	v_pk_mul_f32 v[172:173], v[174:175], v[172:173]
	s_nop 0
	v_fma_f32 v156, -|v156|, v172, v152
	v_fma_f32 v157, -|v157|, v173, v153
	v_cvt_pk_bf16_f32 v152, v154, v155
	v_cvt_pk_bf16_f32 v153, v158, v159
	v_cvt_pk_bf16_f32 v154, v170, v171
	v_pk_add_f32 v[172:173], v[64:65], 0 op_sel_hi:[1,0]
	v_cvt_pk_bf16_f32 v155, v156, v157
	global_store_dwordx4 v[150:151], v[152:155], off
	v_pk_add_f32 v[156:157], v[66:67], 0 op_sel_hi:[1,0]
	s_nop 0
	v_pk_add_f32 v[154:155], v[68:69], 0 op_sel_hi:[1,0]
	v_pk_add_f32 v[152:153], v[70:71], 0 op_sel_hi:[1,0]
	v_fma_f32 v170, |v154|, s38, 1.0
	v_fma_f32 v171, |v155|, s38, 1.0
	v_pk_mul_f32 v[178:179], v[154:155], v[154:155]
	v_rcp_f32_e32 v170, v170
	v_rcp_f32_e32 v171, v171
	v_pk_mul_f32 v[178:179], v[178:179], s[50:51] op_sel_hi:[1,0]
	v_pk_fma_f32 v[176:177], v[170:171], s[40:41], v[146:147] op_sel_hi:[1,0,0]
	v_exp_f32_e32 v178, v178
	v_pk_fma_f32 v[176:177], v[170:171], v[176:177], s[44:45] op_sel_hi:[1,1,0]
	v_exp_f32_e32 v179, v179
	v_fma_f32 v180, |v152|, s38, 1.0
	v_fma_f32 v181, |v153|, s38, 1.0
	v_pk_fma_f32 v[176:177], v[170:171], v[176:177], s[46:47] op_sel_hi:[1,1,0]
	v_rcp_f32_e32 v180, v180
	v_rcp_f32_e32 v181, v181
	v_pk_fma_f32 v[176:177], v[170:171], v[176:177], s[48:49] op_sel_hi:[1,1,0]
	v_max_f32_e32 v158, 0, v154
	v_pk_mul_f32 v[170:171], v[170:171], v[176:177]
	v_pk_mul_f32 v[176:177], v[152:153], v[152:153]
	v_max_f32_e32 v159, 0, v155
	v_pk_mul_f32 v[170:171], v[178:179], v[170:171]
	v_max_f32_e32 v174, 0, v152
	v_fma_f32 v154, -|v154|, v170, v158
	v_fma_f32 v155, -|v155|, v171, v159
	v_pk_fma_f32 v[158:159], v[180:181], s[40:41], v[146:147] op_sel_hi:[1,0,0]
	v_pk_mul_f32 v[170:171], v[176:177], s[50:51] op_sel_hi:[1,0]
	v_pk_fma_f32 v[158:159], v[180:181], v[158:159], s[44:45] op_sel_hi:[1,1,0]
	v_exp_f32_e32 v170, v170
	v_exp_f32_e32 v171, v171
	v_pk_fma_f32 v[158:159], v[180:181], v[158:159], s[46:47] op_sel_hi:[1,1,0]
	v_max_f32_e32 v175, 0, v153
	v_pk_fma_f32 v[158:159], v[180:181], v[158:159], s[48:49] op_sel_hi:[1,1,0]
	v_pk_mul_f32 v[178:179], v[172:173], v[172:173]
	v_pk_mul_f32 v[158:159], v[180:181], v[158:159]
	v_pk_mul_f32 v[178:179], v[178:179], s[50:51] op_sel_hi:[1,0]
	v_pk_mul_f32 v[158:159], v[170:171], v[158:159]
	v_fma_f32 v176, |v172|, s38, 1.0
	v_fma_f32 v177, |v173|, s38, 1.0
	v_fma_f32 v158, -|v152|, v158, v174
	v_fma_f32 v159, -|v153|, v159, v175
	v_rcp_f32_e32 v176, v176
	v_rcp_f32_e32 v177, v177
	v_exp_f32_e32 v178, v178
	v_pk_fma_f32 v[174:175], v[176:177], s[40:41], v[146:147] op_sel_hi:[1,0,0]
	v_exp_f32_e32 v179, v179
	v_pk_fma_f32 v[174:175], v[176:177], v[174:175], s[44:45] op_sel_hi:[1,1,0]
	v_fma_f32 v180, |v156|, s38, 1.0
	v_fma_f32 v181, |v157|, s38, 1.0
	v_pk_fma_f32 v[174:175], v[176:177], v[174:175], s[46:47] op_sel_hi:[1,1,0]
	v_rcp_f32_e32 v180, v180
	v_rcp_f32_e32 v181, v181
	v_pk_fma_f32 v[174:175], v[176:177], v[174:175], s[48:49] op_sel_hi:[1,1,0]
	v_max_f32_e32 v170, 0, v172
	v_pk_mul_f32 v[174:175], v[176:177], v[174:175]
	v_pk_mul_f32 v[176:177], v[156:157], v[156:157]
	v_max_f32_e32 v171, 0, v173
	v_pk_mul_f32 v[174:175], v[178:179], v[174:175]
	v_max_f32_e32 v152, 0, v156
	v_fma_f32 v170, -|v172|, v174, v170
	v_fma_f32 v171, -|v173|, v175, v171
	v_pk_fma_f32 v[172:173], v[180:181], s[40:41], v[146:147] op_sel_hi:[1,0,0]
	v_pk_mul_f32 v[174:175], v[176:177], s[50:51] op_sel_hi:[1,0]
	v_pk_fma_f32 v[172:173], v[180:181], v[172:173], s[44:45] op_sel_hi:[1,1,0]
	v_exp_f32_e32 v174, v174
	v_exp_f32_e32 v175, v175
	v_pk_fma_f32 v[172:173], v[180:181], v[172:173], s[46:47] op_sel_hi:[1,1,0]
	v_max_f32_e32 v153, 0, v157
	v_pk_fma_f32 v[172:173], v[180:181], v[172:173], s[48:49] op_sel_hi:[1,1,0]
	s_nop 0
	v_pk_mul_f32 v[172:173], v[180:181], v[172:173]
	s_nop 0
	v_pk_mul_f32 v[172:173], v[174:175], v[172:173]
	s_nop 0
	v_fma_f32 v156, -|v156|, v172, v152
	v_fma_f32 v157, -|v157|, v173, v153
	v_cvt_pk_bf16_f32 v152, v154, v155
	v_cvt_pk_bf16_f32 v153, v158, v159
	v_cvt_pk_bf16_f32 v154, v170, v171
	v_pk_add_f32 v[172:173], v[56:57], 0 op_sel_hi:[1,0]
	v_cvt_pk_bf16_f32 v155, v156, v157
	global_store_dwordx4 v[150:151], v[152:155], off offset:256
	v_pk_add_f32 v[156:157], v[58:59], 0 op_sel_hi:[1,0]
	v_lshl_add_u64 v[150:151], v[148:149], 0, s[0:1]
	v_pk_add_f32 v[154:155], v[60:61], 0 op_sel_hi:[1,0]
	v_pk_add_f32 v[152:153], v[62:63], 0 op_sel_hi:[1,0]
	v_fma_f32 v170, |v154|, s38, 1.0
	v_fma_f32 v171, |v155|, s38, 1.0
	v_pk_mul_f32 v[178:179], v[154:155], v[154:155]
	v_rcp_f32_e32 v170, v170
	v_rcp_f32_e32 v171, v171
	v_pk_mul_f32 v[178:179], v[178:179], s[50:51] op_sel_hi:[1,0]
	v_pk_fma_f32 v[176:177], v[170:171], s[40:41], v[146:147] op_sel_hi:[1,0,0]
	v_exp_f32_e32 v178, v178
	v_pk_fma_f32 v[176:177], v[170:171], v[176:177], s[44:45] op_sel_hi:[1,1,0]
	v_exp_f32_e32 v179, v179
	v_fma_f32 v180, |v152|, s38, 1.0
	v_fma_f32 v181, |v153|, s38, 1.0
	v_pk_fma_f32 v[176:177], v[170:171], v[176:177], s[46:47] op_sel_hi:[1,1,0]
	v_rcp_f32_e32 v180, v180
	v_rcp_f32_e32 v181, v181
	v_pk_fma_f32 v[176:177], v[170:171], v[176:177], s[48:49] op_sel_hi:[1,1,0]
	v_max_f32_e32 v158, 0, v154
	v_pk_mul_f32 v[170:171], v[170:171], v[176:177]
	v_pk_mul_f32 v[176:177], v[152:153], v[152:153]
	v_max_f32_e32 v159, 0, v155
	v_pk_mul_f32 v[170:171], v[178:179], v[170:171]
	v_max_f32_e32 v174, 0, v152
	v_fma_f32 v154, -|v154|, v170, v158
	v_fma_f32 v155, -|v155|, v171, v159
	v_pk_fma_f32 v[158:159], v[180:181], s[40:41], v[146:147] op_sel_hi:[1,0,0]
	v_pk_mul_f32 v[170:171], v[176:177], s[50:51] op_sel_hi:[1,0]
	v_pk_fma_f32 v[158:159], v[180:181], v[158:159], s[44:45] op_sel_hi:[1,1,0]
	v_exp_f32_e32 v170, v170
	v_exp_f32_e32 v171, v171
	v_pk_fma_f32 v[158:159], v[180:181], v[158:159], s[46:47] op_sel_hi:[1,1,0]
	v_max_f32_e32 v175, 0, v153
	v_pk_fma_f32 v[158:159], v[180:181], v[158:159], s[48:49] op_sel_hi:[1,1,0]
	v_pk_mul_f32 v[178:179], v[172:173], v[172:173]
	v_pk_mul_f32 v[158:159], v[180:181], v[158:159]
	v_pk_mul_f32 v[178:179], v[178:179], s[50:51] op_sel_hi:[1,0]
	v_pk_mul_f32 v[158:159], v[170:171], v[158:159]
	v_fma_f32 v176, |v172|, s38, 1.0
	v_fma_f32 v177, |v173|, s38, 1.0
	v_fma_f32 v158, -|v152|, v158, v174
	v_fma_f32 v159, -|v153|, v159, v175
	v_rcp_f32_e32 v176, v176
	v_rcp_f32_e32 v177, v177
	v_exp_f32_e32 v178, v178
	v_pk_fma_f32 v[174:175], v[176:177], s[40:41], v[146:147] op_sel_hi:[1,0,0]
	v_exp_f32_e32 v179, v179
	v_pk_fma_f32 v[174:175], v[176:177], v[174:175], s[44:45] op_sel_hi:[1,1,0]
	v_fma_f32 v180, |v156|, s38, 1.0
	v_fma_f32 v181, |v157|, s38, 1.0
	v_pk_fma_f32 v[174:175], v[176:177], v[174:175], s[46:47] op_sel_hi:[1,1,0]
	v_rcp_f32_e32 v180, v180
	v_rcp_f32_e32 v181, v181
	v_pk_fma_f32 v[174:175], v[176:177], v[174:175], s[48:49] op_sel_hi:[1,1,0]
	v_max_f32_e32 v170, 0, v172
	v_pk_mul_f32 v[174:175], v[176:177], v[174:175]
	v_pk_mul_f32 v[176:177], v[156:157], v[156:157]
	v_max_f32_e32 v171, 0, v173
	v_pk_mul_f32 v[174:175], v[178:179], v[174:175]
	v_max_f32_e32 v152, 0, v156
	v_fma_f32 v170, -|v172|, v174, v170
	v_fma_f32 v171, -|v173|, v175, v171
	v_pk_fma_f32 v[172:173], v[180:181], s[40:41], v[146:147] op_sel_hi:[1,0,0]
	v_pk_mul_f32 v[174:175], v[176:177], s[50:51] op_sel_hi:[1,0]
	v_pk_fma_f32 v[172:173], v[180:181], v[172:173], s[44:45] op_sel_hi:[1,1,0]
	v_exp_f32_e32 v174, v174
	v_exp_f32_e32 v175, v175
	v_pk_fma_f32 v[172:173], v[180:181], v[172:173], s[46:47] op_sel_hi:[1,1,0]
	v_max_f32_e32 v153, 0, v157
	v_pk_fma_f32 v[172:173], v[180:181], v[172:173], s[48:49] op_sel_hi:[1,1,0]
	s_mov_b32 s0, 0x40000
	v_pk_mul_f32 v[172:173], v[180:181], v[172:173]
	s_nop 0
	v_pk_mul_f32 v[172:173], v[174:175], v[172:173]
	s_nop 0
	v_fma_f32 v156, -|v156|, v172, v152
	v_fma_f32 v157, -|v157|, v173, v153
	v_cvt_pk_bf16_f32 v152, v154, v155
	v_cvt_pk_bf16_f32 v153, v158, v159
	v_cvt_pk_bf16_f32 v154, v170, v171
	v_pk_add_f32 v[172:173], v[48:49], 0 op_sel_hi:[1,0]
	v_cvt_pk_bf16_f32 v155, v156, v157
	v_add_co_u32_e32 v156, vcc, s0, v148
	s_mov_b64 s[0:1], 0x48000
	s_nop 0
	v_addc_co_u32_e32 v157, vcc, 0, v149, vcc
	global_store_dwordx4 v[156:157], v[152:155], off
	v_pk_add_f32 v[156:157], v[50:51], 0 op_sel_hi:[1,0]
	s_nop 0
	v_pk_add_f32 v[154:155], v[52:53], 0 op_sel_hi:[1,0]
	v_pk_add_f32 v[152:153], v[54:55], 0 op_sel_hi:[1,0]
	v_fma_f32 v170, |v154|, s38, 1.0
	v_fma_f32 v171, |v155|, s38, 1.0
	v_pk_mul_f32 v[178:179], v[154:155], v[154:155]
	v_rcp_f32_e32 v170, v170
	v_rcp_f32_e32 v171, v171
	v_pk_mul_f32 v[178:179], v[178:179], s[50:51] op_sel_hi:[1,0]
	v_pk_fma_f32 v[176:177], v[170:171], s[40:41], v[146:147] op_sel_hi:[1,0,0]
	v_exp_f32_e32 v178, v178
	v_pk_fma_f32 v[176:177], v[170:171], v[176:177], s[44:45] op_sel_hi:[1,1,0]
	v_exp_f32_e32 v179, v179
	v_fma_f32 v180, |v152|, s38, 1.0
	v_fma_f32 v181, |v153|, s38, 1.0
	v_pk_fma_f32 v[176:177], v[170:171], v[176:177], s[46:47] op_sel_hi:[1,1,0]
	v_rcp_f32_e32 v180, v180
	v_rcp_f32_e32 v181, v181
	v_pk_fma_f32 v[176:177], v[170:171], v[176:177], s[48:49] op_sel_hi:[1,1,0]
	v_max_f32_e32 v158, 0, v154
	v_pk_mul_f32 v[170:171], v[170:171], v[176:177]
	v_pk_mul_f32 v[176:177], v[152:153], v[152:153]
	v_max_f32_e32 v159, 0, v155
	v_pk_mul_f32 v[170:171], v[178:179], v[170:171]
	v_max_f32_e32 v174, 0, v152
	v_fma_f32 v154, -|v154|, v170, v158
	v_fma_f32 v155, -|v155|, v171, v159
	v_pk_fma_f32 v[158:159], v[180:181], s[40:41], v[146:147] op_sel_hi:[1,0,0]
	v_pk_mul_f32 v[170:171], v[176:177], s[50:51] op_sel_hi:[1,0]
	v_pk_fma_f32 v[158:159], v[180:181], v[158:159], s[44:45] op_sel_hi:[1,1,0]
	v_exp_f32_e32 v170, v170
	v_exp_f32_e32 v171, v171
	v_pk_fma_f32 v[158:159], v[180:181], v[158:159], s[46:47] op_sel_hi:[1,1,0]
	v_max_f32_e32 v175, 0, v153
	v_pk_fma_f32 v[158:159], v[180:181], v[158:159], s[48:49] op_sel_hi:[1,1,0]
	v_pk_mul_f32 v[178:179], v[172:173], v[172:173]
	v_pk_mul_f32 v[158:159], v[180:181], v[158:159]
	v_pk_mul_f32 v[178:179], v[178:179], s[50:51] op_sel_hi:[1,0]
	v_pk_mul_f32 v[158:159], v[170:171], v[158:159]
	v_fma_f32 v176, |v172|, s38, 1.0
	v_fma_f32 v177, |v173|, s38, 1.0
	v_fma_f32 v158, -|v152|, v158, v174
	v_fma_f32 v159, -|v153|, v159, v175
	v_rcp_f32_e32 v176, v176
	v_rcp_f32_e32 v177, v177
	v_exp_f32_e32 v178, v178
	v_pk_fma_f32 v[174:175], v[176:177], s[40:41], v[146:147] op_sel_hi:[1,0,0]
	v_exp_f32_e32 v179, v179
	v_pk_fma_f32 v[174:175], v[176:177], v[174:175], s[44:45] op_sel_hi:[1,1,0]
	v_fma_f32 v180, |v156|, s38, 1.0
	v_fma_f32 v181, |v157|, s38, 1.0
	v_pk_fma_f32 v[174:175], v[176:177], v[174:175], s[46:47] op_sel_hi:[1,1,0]
	v_rcp_f32_e32 v180, v180
	v_rcp_f32_e32 v181, v181
	v_pk_fma_f32 v[174:175], v[176:177], v[174:175], s[48:49] op_sel_hi:[1,1,0]
	v_max_f32_e32 v170, 0, v172
	v_pk_mul_f32 v[174:175], v[176:177], v[174:175]
	v_pk_mul_f32 v[176:177], v[156:157], v[156:157]
	v_max_f32_e32 v171, 0, v173
	v_pk_mul_f32 v[174:175], v[178:179], v[174:175]
	v_max_f32_e32 v152, 0, v156
	v_fma_f32 v170, -|v172|, v174, v170
	v_fma_f32 v171, -|v173|, v175, v171
	v_pk_fma_f32 v[172:173], v[180:181], s[40:41], v[146:147] op_sel_hi:[1,0,0]
	v_pk_mul_f32 v[174:175], v[176:177], s[50:51] op_sel_hi:[1,0]
	v_pk_fma_f32 v[172:173], v[180:181], v[172:173], s[44:45] op_sel_hi:[1,1,0]
	v_exp_f32_e32 v174, v174
	v_exp_f32_e32 v175, v175
	v_pk_fma_f32 v[172:173], v[180:181], v[172:173], s[46:47] op_sel_hi:[1,1,0]
	v_max_f32_e32 v153, 0, v157
	v_pk_fma_f32 v[172:173], v[180:181], v[172:173], s[48:49] op_sel_hi:[1,1,0]
	s_nop 0
	v_pk_mul_f32 v[172:173], v[180:181], v[172:173]
	s_nop 0
	v_pk_mul_f32 v[172:173], v[174:175], v[172:173]
	s_nop 0
	v_fma_f32 v156, -|v156|, v172, v152
	v_fma_f32 v157, -|v157|, v173, v153
	v_cvt_pk_bf16_f32 v152, v154, v155
	v_cvt_pk_bf16_f32 v153, v158, v159
	v_cvt_pk_bf16_f32 v154, v170, v171
	v_pk_add_f32 v[172:173], v[40:41], 0 op_sel_hi:[1,0]
	v_cvt_pk_bf16_f32 v155, v156, v157
	global_store_dwordx4 v[150:151], v[152:155], off offset:256
	v_pk_add_f32 v[156:157], v[42:43], 0 op_sel_hi:[1,0]
	v_lshl_add_u64 v[150:151], v[148:149], 0, s[0:1]
	v_pk_add_f32 v[154:155], v[44:45], 0 op_sel_hi:[1,0]
	v_pk_add_f32 v[152:153], v[46:47], 0 op_sel_hi:[1,0]
	v_fma_f32 v170, |v154|, s38, 1.0
	v_fma_f32 v171, |v155|, s38, 1.0
	v_pk_mul_f32 v[178:179], v[154:155], v[154:155]
	v_rcp_f32_e32 v170, v170
	v_rcp_f32_e32 v171, v171
	v_pk_mul_f32 v[178:179], v[178:179], s[50:51] op_sel_hi:[1,0]
	v_pk_fma_f32 v[176:177], v[170:171], s[40:41], v[146:147] op_sel_hi:[1,0,0]
	v_exp_f32_e32 v178, v178
	v_pk_fma_f32 v[176:177], v[170:171], v[176:177], s[44:45] op_sel_hi:[1,1,0]
	v_exp_f32_e32 v179, v179
	v_fma_f32 v180, |v152|, s38, 1.0
	v_fma_f32 v181, |v153|, s38, 1.0
	v_pk_fma_f32 v[176:177], v[170:171], v[176:177], s[46:47] op_sel_hi:[1,1,0]
	v_rcp_f32_e32 v180, v180
	v_rcp_f32_e32 v181, v181
	v_pk_fma_f32 v[176:177], v[170:171], v[176:177], s[48:49] op_sel_hi:[1,1,0]
	v_max_f32_e32 v158, 0, v154
	v_pk_mul_f32 v[170:171], v[170:171], v[176:177]
	v_pk_mul_f32 v[176:177], v[152:153], v[152:153]
	v_max_f32_e32 v159, 0, v155
	v_pk_mul_f32 v[170:171], v[178:179], v[170:171]
	v_max_f32_e32 v174, 0, v152
	v_fma_f32 v154, -|v154|, v170, v158
	v_fma_f32 v155, -|v155|, v171, v159
	v_pk_fma_f32 v[158:159], v[180:181], s[40:41], v[146:147] op_sel_hi:[1,0,0]
	v_pk_mul_f32 v[170:171], v[176:177], s[50:51] op_sel_hi:[1,0]
	v_pk_fma_f32 v[158:159], v[180:181], v[158:159], s[44:45] op_sel_hi:[1,1,0]
	v_exp_f32_e32 v170, v170
	v_exp_f32_e32 v171, v171
	v_pk_fma_f32 v[158:159], v[180:181], v[158:159], s[46:47] op_sel_hi:[1,1,0]
	v_max_f32_e32 v175, 0, v153
	v_pk_fma_f32 v[158:159], v[180:181], v[158:159], s[48:49] op_sel_hi:[1,1,0]
	v_pk_mul_f32 v[178:179], v[172:173], v[172:173]
	v_pk_mul_f32 v[158:159], v[180:181], v[158:159]
	v_pk_mul_f32 v[178:179], v[178:179], s[50:51] op_sel_hi:[1,0]
	v_pk_mul_f32 v[158:159], v[170:171], v[158:159]
	v_fma_f32 v176, |v172|, s38, 1.0
	v_fma_f32 v177, |v173|, s38, 1.0
	v_fma_f32 v158, -|v152|, v158, v174
	v_fma_f32 v159, -|v153|, v159, v175
	v_rcp_f32_e32 v176, v176
	v_rcp_f32_e32 v177, v177
	v_exp_f32_e32 v178, v178
	v_pk_fma_f32 v[174:175], v[176:177], s[40:41], v[146:147] op_sel_hi:[1,0,0]
	v_exp_f32_e32 v179, v179
	v_pk_fma_f32 v[174:175], v[176:177], v[174:175], s[44:45] op_sel_hi:[1,1,0]
	v_fma_f32 v180, |v156|, s38, 1.0
	v_fma_f32 v181, |v157|, s38, 1.0
	v_pk_fma_f32 v[174:175], v[176:177], v[174:175], s[46:47] op_sel_hi:[1,1,0]
	v_rcp_f32_e32 v180, v180
	v_rcp_f32_e32 v181, v181
	v_pk_fma_f32 v[174:175], v[176:177], v[174:175], s[48:49] op_sel_hi:[1,1,0]
	v_max_f32_e32 v170, 0, v172
	v_pk_mul_f32 v[174:175], v[176:177], v[174:175]
	v_pk_mul_f32 v[176:177], v[156:157], v[156:157]
	v_max_f32_e32 v171, 0, v173
	v_pk_mul_f32 v[174:175], v[178:179], v[174:175]
	v_max_f32_e32 v152, 0, v156
	v_fma_f32 v170, -|v172|, v174, v170
	v_fma_f32 v171, -|v173|, v175, v171
	v_pk_fma_f32 v[172:173], v[180:181], s[40:41], v[146:147] op_sel_hi:[1,0,0]
	v_pk_mul_f32 v[174:175], v[176:177], s[50:51] op_sel_hi:[1,0]
	v_pk_fma_f32 v[172:173], v[180:181], v[172:173], s[44:45] op_sel_hi:[1,1,0]
	v_exp_f32_e32 v174, v174
	v_exp_f32_e32 v175, v175
	v_pk_fma_f32 v[172:173], v[180:181], v[172:173], s[46:47] op_sel_hi:[1,1,0]
	v_max_f32_e32 v153, 0, v157
	v_pk_fma_f32 v[172:173], v[180:181], v[172:173], s[48:49] op_sel_hi:[1,1,0]
	s_mov_b32 s0, 0x48000
	v_pk_mul_f32 v[172:173], v[180:181], v[172:173]
	s_nop 0
	v_pk_mul_f32 v[172:173], v[174:175], v[172:173]
	s_nop 0
	v_fma_f32 v156, -|v156|, v172, v152
	v_fma_f32 v157, -|v157|, v173, v153
	v_cvt_pk_bf16_f32 v152, v154, v155
	v_cvt_pk_bf16_f32 v153, v158, v159
	v_cvt_pk_bf16_f32 v154, v170, v171
	v_pk_add_f32 v[172:173], v[32:33], 0 op_sel_hi:[1,0]
	v_cvt_pk_bf16_f32 v155, v156, v157
	v_add_co_u32_e32 v156, vcc, s0, v148
	s_mov_b64 s[0:1], 0x50000
	s_nop 0
	v_addc_co_u32_e32 v157, vcc, 0, v149, vcc
	global_store_dwordx4 v[156:157], v[152:155], off
	v_pk_add_f32 v[156:157], v[34:35], 0 op_sel_hi:[1,0]
	s_nop 0
	v_pk_add_f32 v[154:155], v[36:37], 0 op_sel_hi:[1,0]
	v_pk_add_f32 v[152:153], v[38:39], 0 op_sel_hi:[1,0]
	v_fma_f32 v170, |v154|, s38, 1.0
	v_fma_f32 v171, |v155|, s38, 1.0
	v_pk_mul_f32 v[178:179], v[154:155], v[154:155]
	v_rcp_f32_e32 v170, v170
	v_rcp_f32_e32 v171, v171
	v_pk_mul_f32 v[178:179], v[178:179], s[50:51] op_sel_hi:[1,0]
	v_pk_fma_f32 v[176:177], v[170:171], s[40:41], v[146:147] op_sel_hi:[1,0,0]
	v_exp_f32_e32 v178, v178
	v_pk_fma_f32 v[176:177], v[170:171], v[176:177], s[44:45] op_sel_hi:[1,1,0]
	v_exp_f32_e32 v179, v179
	v_fma_f32 v180, |v152|, s38, 1.0
	v_fma_f32 v181, |v153|, s38, 1.0
	v_pk_fma_f32 v[176:177], v[170:171], v[176:177], s[46:47] op_sel_hi:[1,1,0]
	v_rcp_f32_e32 v180, v180
	v_rcp_f32_e32 v181, v181
	v_pk_fma_f32 v[176:177], v[170:171], v[176:177], s[48:49] op_sel_hi:[1,1,0]
	v_max_f32_e32 v158, 0, v154
	v_pk_mul_f32 v[170:171], v[170:171], v[176:177]
	v_pk_mul_f32 v[176:177], v[152:153], v[152:153]
	v_max_f32_e32 v159, 0, v155
	v_pk_mul_f32 v[170:171], v[178:179], v[170:171]
	v_max_f32_e32 v174, 0, v152
	v_fma_f32 v154, -|v154|, v170, v158
	v_fma_f32 v155, -|v155|, v171, v159
	v_pk_fma_f32 v[158:159], v[180:181], s[40:41], v[146:147] op_sel_hi:[1,0,0]
	v_pk_mul_f32 v[170:171], v[176:177], s[50:51] op_sel_hi:[1,0]
	v_pk_fma_f32 v[158:159], v[180:181], v[158:159], s[44:45] op_sel_hi:[1,1,0]
	v_exp_f32_e32 v170, v170
	v_exp_f32_e32 v171, v171
	v_pk_fma_f32 v[158:159], v[180:181], v[158:159], s[46:47] op_sel_hi:[1,1,0]
	v_max_f32_e32 v175, 0, v153
	v_pk_fma_f32 v[158:159], v[180:181], v[158:159], s[48:49] op_sel_hi:[1,1,0]
	v_pk_mul_f32 v[178:179], v[172:173], v[172:173]
	v_pk_mul_f32 v[158:159], v[180:181], v[158:159]
	v_pk_mul_f32 v[178:179], v[178:179], s[50:51] op_sel_hi:[1,0]
	v_pk_mul_f32 v[158:159], v[170:171], v[158:159]
	v_fma_f32 v176, |v172|, s38, 1.0
	v_fma_f32 v177, |v173|, s38, 1.0
	v_fma_f32 v158, -|v152|, v158, v174
	v_fma_f32 v159, -|v153|, v159, v175
	v_rcp_f32_e32 v176, v176
	v_rcp_f32_e32 v177, v177
	v_exp_f32_e32 v178, v178
	v_pk_fma_f32 v[174:175], v[176:177], s[40:41], v[146:147] op_sel_hi:[1,0,0]
	v_exp_f32_e32 v179, v179
	v_pk_fma_f32 v[174:175], v[176:177], v[174:175], s[44:45] op_sel_hi:[1,1,0]
	v_fma_f32 v180, |v156|, s38, 1.0
	v_fma_f32 v181, |v157|, s38, 1.0
	v_pk_fma_f32 v[174:175], v[176:177], v[174:175], s[46:47] op_sel_hi:[1,1,0]
	v_rcp_f32_e32 v180, v180
	v_rcp_f32_e32 v181, v181
	v_pk_fma_f32 v[174:175], v[176:177], v[174:175], s[48:49] op_sel_hi:[1,1,0]
	v_max_f32_e32 v170, 0, v172
	v_pk_mul_f32 v[174:175], v[176:177], v[174:175]
	v_pk_mul_f32 v[176:177], v[156:157], v[156:157]
	v_max_f32_e32 v171, 0, v173
	v_pk_mul_f32 v[174:175], v[178:179], v[174:175]
	v_max_f32_e32 v152, 0, v156
	v_fma_f32 v170, -|v172|, v174, v170
	v_fma_f32 v171, -|v173|, v175, v171
	v_pk_fma_f32 v[172:173], v[180:181], s[40:41], v[146:147] op_sel_hi:[1,0,0]
	v_pk_mul_f32 v[174:175], v[176:177], s[50:51] op_sel_hi:[1,0]
	v_pk_fma_f32 v[172:173], v[180:181], v[172:173], s[44:45] op_sel_hi:[1,1,0]
	v_exp_f32_e32 v174, v174
	v_exp_f32_e32 v175, v175
	v_pk_fma_f32 v[172:173], v[180:181], v[172:173], s[46:47] op_sel_hi:[1,1,0]
	v_max_f32_e32 v153, 0, v157
	v_pk_fma_f32 v[172:173], v[180:181], v[172:173], s[48:49] op_sel_hi:[1,1,0]
	s_nop 0
	v_pk_mul_f32 v[172:173], v[180:181], v[172:173]
	s_nop 0
	v_pk_mul_f32 v[172:173], v[174:175], v[172:173]
	s_nop 0
	v_fma_f32 v156, -|v156|, v172, v152
	v_fma_f32 v157, -|v157|, v173, v153
	v_cvt_pk_bf16_f32 v152, v154, v155
	v_cvt_pk_bf16_f32 v153, v158, v159
	v_cvt_pk_bf16_f32 v154, v170, v171
	v_pk_add_f32 v[172:173], v[24:25], 0 op_sel_hi:[1,0]
	v_cvt_pk_bf16_f32 v155, v156, v157
	global_store_dwordx4 v[150:151], v[152:155], off offset:256
	v_pk_add_f32 v[156:157], v[26:27], 0 op_sel_hi:[1,0]
	v_lshl_add_u64 v[150:151], v[148:149], 0, s[0:1]
	v_pk_add_f32 v[154:155], v[28:29], 0 op_sel_hi:[1,0]
	v_pk_add_f32 v[152:153], v[30:31], 0 op_sel_hi:[1,0]
	v_fma_f32 v170, |v154|, s38, 1.0
	v_fma_f32 v171, |v155|, s38, 1.0
	v_pk_mul_f32 v[178:179], v[154:155], v[154:155]
	v_rcp_f32_e32 v170, v170
	v_rcp_f32_e32 v171, v171
	v_pk_mul_f32 v[178:179], v[178:179], s[50:51] op_sel_hi:[1,0]
	v_pk_fma_f32 v[176:177], v[170:171], s[40:41], v[146:147] op_sel_hi:[1,0,0]
	v_exp_f32_e32 v178, v178
	v_pk_fma_f32 v[176:177], v[170:171], v[176:177], s[44:45] op_sel_hi:[1,1,0]
	v_exp_f32_e32 v179, v179
	v_fma_f32 v180, |v152|, s38, 1.0
	v_fma_f32 v181, |v153|, s38, 1.0
	v_pk_fma_f32 v[176:177], v[170:171], v[176:177], s[46:47] op_sel_hi:[1,1,0]
	v_rcp_f32_e32 v180, v180
	v_rcp_f32_e32 v181, v181
	v_pk_fma_f32 v[176:177], v[170:171], v[176:177], s[48:49] op_sel_hi:[1,1,0]
	v_max_f32_e32 v158, 0, v154
	v_pk_mul_f32 v[170:171], v[170:171], v[176:177]
	v_pk_mul_f32 v[176:177], v[152:153], v[152:153]
	v_max_f32_e32 v159, 0, v155
	v_pk_mul_f32 v[170:171], v[178:179], v[170:171]
	v_max_f32_e32 v174, 0, v152
	v_fma_f32 v154, -|v154|, v170, v158
	v_fma_f32 v155, -|v155|, v171, v159
	v_pk_fma_f32 v[158:159], v[180:181], s[40:41], v[146:147] op_sel_hi:[1,0,0]
	v_pk_mul_f32 v[170:171], v[176:177], s[50:51] op_sel_hi:[1,0]
	v_pk_fma_f32 v[158:159], v[180:181], v[158:159], s[44:45] op_sel_hi:[1,1,0]
	v_exp_f32_e32 v170, v170
	v_exp_f32_e32 v171, v171
	v_pk_fma_f32 v[158:159], v[180:181], v[158:159], s[46:47] op_sel_hi:[1,1,0]
	v_max_f32_e32 v175, 0, v153
	v_pk_fma_f32 v[158:159], v[180:181], v[158:159], s[48:49] op_sel_hi:[1,1,0]
	v_pk_mul_f32 v[178:179], v[172:173], v[172:173]
	v_pk_mul_f32 v[158:159], v[180:181], v[158:159]
	v_pk_mul_f32 v[178:179], v[178:179], s[50:51] op_sel_hi:[1,0]
	v_pk_mul_f32 v[158:159], v[170:171], v[158:159]
	v_fma_f32 v176, |v172|, s38, 1.0
	v_fma_f32 v177, |v173|, s38, 1.0
	v_fma_f32 v158, -|v152|, v158, v174
	v_fma_f32 v159, -|v153|, v159, v175
	v_rcp_f32_e32 v176, v176
	v_rcp_f32_e32 v177, v177
	v_exp_f32_e32 v178, v178
	v_pk_fma_f32 v[174:175], v[176:177], s[40:41], v[146:147] op_sel_hi:[1,0,0]
	v_exp_f32_e32 v179, v179
	v_pk_fma_f32 v[174:175], v[176:177], v[174:175], s[44:45] op_sel_hi:[1,1,0]
	v_fma_f32 v180, |v156|, s38, 1.0
	v_fma_f32 v181, |v157|, s38, 1.0
	v_pk_fma_f32 v[174:175], v[176:177], v[174:175], s[46:47] op_sel_hi:[1,1,0]
	v_rcp_f32_e32 v180, v180
	v_rcp_f32_e32 v181, v181
	v_pk_fma_f32 v[174:175], v[176:177], v[174:175], s[48:49] op_sel_hi:[1,1,0]
	v_max_f32_e32 v170, 0, v172
	v_pk_mul_f32 v[174:175], v[176:177], v[174:175]
	v_pk_mul_f32 v[176:177], v[156:157], v[156:157]
	v_max_f32_e32 v171, 0, v173
	v_pk_mul_f32 v[174:175], v[178:179], v[174:175]
	v_max_f32_e32 v152, 0, v156
	v_fma_f32 v170, -|v172|, v174, v170
	v_fma_f32 v171, -|v173|, v175, v171
	v_pk_fma_f32 v[172:173], v[180:181], s[40:41], v[146:147] op_sel_hi:[1,0,0]
	v_pk_mul_f32 v[174:175], v[176:177], s[50:51] op_sel_hi:[1,0]
	v_pk_fma_f32 v[172:173], v[180:181], v[172:173], s[44:45] op_sel_hi:[1,1,0]
	v_exp_f32_e32 v174, v174
	v_exp_f32_e32 v175, v175
	v_pk_fma_f32 v[172:173], v[180:181], v[172:173], s[46:47] op_sel_hi:[1,1,0]
	v_max_f32_e32 v153, 0, v157
	v_pk_fma_f32 v[172:173], v[180:181], v[172:173], s[48:49] op_sel_hi:[1,1,0]
	s_nop 0
	v_pk_mul_f32 v[172:173], v[180:181], v[172:173]
	s_nop 0
	v_pk_mul_f32 v[172:173], v[174:175], v[172:173]
	s_nop 0
	v_fma_f32 v156, -|v156|, v172, v152
	v_fma_f32 v157, -|v157|, v173, v153
	v_cvt_pk_bf16_f32 v152, v154, v155
	v_cvt_pk_bf16_f32 v153, v158, v159
	v_cvt_pk_bf16_f32 v154, v170, v171
	v_pk_add_f32 v[172:173], v[16:17], 0 op_sel_hi:[1,0]
	v_cvt_pk_bf16_f32 v155, v156, v157
	v_add_co_u32_e32 v156, vcc, s84, v148
	s_nop 1
	v_addc_co_u32_e32 v157, vcc, 0, v149, vcc
	global_store_dwordx4 v[156:157], v[152:155], off
	v_pk_add_f32 v[156:157], v[18:19], 0 op_sel_hi:[1,0]
	s_nop 0
	v_pk_add_f32 v[154:155], v[20:21], 0 op_sel_hi:[1,0]
	v_pk_add_f32 v[152:153], v[22:23], 0 op_sel_hi:[1,0]
	v_fma_f32 v170, |v154|, s38, 1.0
	v_fma_f32 v171, |v155|, s38, 1.0
	v_pk_mul_f32 v[178:179], v[154:155], v[154:155]
	v_rcp_f32_e32 v170, v170
	v_rcp_f32_e32 v171, v171
	v_pk_mul_f32 v[178:179], v[178:179], s[50:51] op_sel_hi:[1,0]
	v_pk_fma_f32 v[176:177], v[170:171], s[40:41], v[146:147] op_sel_hi:[1,0,0]
	v_exp_f32_e32 v178, v178
	v_pk_fma_f32 v[176:177], v[170:171], v[176:177], s[44:45] op_sel_hi:[1,1,0]
	v_exp_f32_e32 v179, v179
	v_fma_f32 v180, |v152|, s38, 1.0
	v_fma_f32 v181, |v153|, s38, 1.0
	v_pk_fma_f32 v[176:177], v[170:171], v[176:177], s[46:47] op_sel_hi:[1,1,0]
	v_rcp_f32_e32 v180, v180
	v_rcp_f32_e32 v181, v181
	v_pk_fma_f32 v[176:177], v[170:171], v[176:177], s[48:49] op_sel_hi:[1,1,0]
	v_max_f32_e32 v158, 0, v154
	v_pk_mul_f32 v[170:171], v[170:171], v[176:177]
	v_pk_mul_f32 v[176:177], v[152:153], v[152:153]
	v_max_f32_e32 v159, 0, v155
	v_pk_mul_f32 v[170:171], v[178:179], v[170:171]
	v_max_f32_e32 v174, 0, v152
	v_fma_f32 v154, -|v154|, v170, v158
	v_fma_f32 v155, -|v155|, v171, v159
	v_pk_fma_f32 v[158:159], v[180:181], s[40:41], v[146:147] op_sel_hi:[1,0,0]
	v_pk_mul_f32 v[170:171], v[176:177], s[50:51] op_sel_hi:[1,0]
	v_pk_fma_f32 v[158:159], v[180:181], v[158:159], s[44:45] op_sel_hi:[1,1,0]
	v_exp_f32_e32 v170, v170
	v_exp_f32_e32 v171, v171
	v_pk_fma_f32 v[158:159], v[180:181], v[158:159], s[46:47] op_sel_hi:[1,1,0]
	v_max_f32_e32 v175, 0, v153
	v_pk_fma_f32 v[158:159], v[180:181], v[158:159], s[48:49] op_sel_hi:[1,1,0]
	v_pk_mul_f32 v[178:179], v[172:173], v[172:173]
	v_pk_mul_f32 v[158:159], v[180:181], v[158:159]
	v_pk_mul_f32 v[178:179], v[178:179], s[50:51] op_sel_hi:[1,0]
	v_pk_mul_f32 v[158:159], v[170:171], v[158:159]
	v_fma_f32 v176, |v172|, s38, 1.0
	v_fma_f32 v177, |v173|, s38, 1.0
	v_fma_f32 v158, -|v152|, v158, v174
	v_fma_f32 v159, -|v153|, v159, v175
	v_rcp_f32_e32 v176, v176
	v_rcp_f32_e32 v177, v177
	v_exp_f32_e32 v178, v178
	v_pk_fma_f32 v[174:175], v[176:177], s[40:41], v[146:147] op_sel_hi:[1,0,0]
	v_exp_f32_e32 v179, v179
	v_pk_fma_f32 v[174:175], v[176:177], v[174:175], s[44:45] op_sel_hi:[1,1,0]
	v_fma_f32 v180, |v156|, s38, 1.0
	v_fma_f32 v181, |v157|, s38, 1.0
	v_pk_fma_f32 v[174:175], v[176:177], v[174:175], s[46:47] op_sel_hi:[1,1,0]
	v_rcp_f32_e32 v180, v180
	v_rcp_f32_e32 v181, v181
	v_pk_fma_f32 v[174:175], v[176:177], v[174:175], s[48:49] op_sel_hi:[1,1,0]
	v_max_f32_e32 v170, 0, v172
	v_pk_mul_f32 v[174:175], v[176:177], v[174:175]
	v_pk_mul_f32 v[176:177], v[156:157], v[156:157]
	v_max_f32_e32 v171, 0, v173
	v_pk_mul_f32 v[174:175], v[178:179], v[174:175]
	v_max_f32_e32 v152, 0, v156
	v_fma_f32 v170, -|v172|, v174, v170
	v_fma_f32 v171, -|v173|, v175, v171
	v_pk_fma_f32 v[172:173], v[180:181], s[40:41], v[146:147] op_sel_hi:[1,0,0]
	v_pk_mul_f32 v[174:175], v[176:177], s[50:51] op_sel_hi:[1,0]
	v_pk_fma_f32 v[172:173], v[180:181], v[172:173], s[44:45] op_sel_hi:[1,1,0]
	v_exp_f32_e32 v174, v174
	v_exp_f32_e32 v175, v175
	v_pk_fma_f32 v[172:173], v[180:181], v[172:173], s[46:47] op_sel_hi:[1,1,0]
	v_max_f32_e32 v153, 0, v157
	v_pk_fma_f32 v[172:173], v[180:181], v[172:173], s[48:49] op_sel_hi:[1,1,0]
	s_nop 0
	v_pk_mul_f32 v[172:173], v[180:181], v[172:173]
	s_nop 0
	v_pk_mul_f32 v[172:173], v[174:175], v[172:173]
	s_nop 0
	v_fma_f32 v156, -|v156|, v172, v152
	v_fma_f32 v157, -|v157|, v173, v153
	v_cvt_pk_bf16_f32 v152, v154, v155
	v_cvt_pk_bf16_f32 v153, v158, v159
	v_cvt_pk_bf16_f32 v154, v170, v171
	v_pk_add_f32 v[172:173], v[8:9], 0 op_sel_hi:[1,0]
	v_cvt_pk_bf16_f32 v155, v156, v157
	global_store_dwordx4 v[150:151], v[152:155], off offset:256
	v_pk_add_f32 v[156:157], v[10:11], 0 op_sel_hi:[1,0]
	v_lshl_add_u64 v[150:151], v[148:149], 0, s[52:53]
	v_pk_add_f32 v[154:155], v[12:13], 0 op_sel_hi:[1,0]
	v_pk_add_f32 v[152:153], v[14:15], 0 op_sel_hi:[1,0]
	v_fma_f32 v170, |v154|, s38, 1.0
	v_fma_f32 v171, |v155|, s38, 1.0
	v_pk_mul_f32 v[178:179], v[154:155], v[154:155]
	v_rcp_f32_e32 v170, v170
	v_rcp_f32_e32 v171, v171
	v_pk_mul_f32 v[178:179], v[178:179], s[50:51] op_sel_hi:[1,0]
	v_pk_fma_f32 v[176:177], v[170:171], s[40:41], v[146:147] op_sel_hi:[1,0,0]
	v_exp_f32_e32 v178, v178
	v_pk_fma_f32 v[176:177], v[170:171], v[176:177], s[44:45] op_sel_hi:[1,1,0]
	v_exp_f32_e32 v179, v179
	v_fma_f32 v180, |v152|, s38, 1.0
	v_fma_f32 v181, |v153|, s38, 1.0
	v_pk_fma_f32 v[176:177], v[170:171], v[176:177], s[46:47] op_sel_hi:[1,1,0]
	v_rcp_f32_e32 v180, v180
	v_rcp_f32_e32 v181, v181
	v_pk_fma_f32 v[176:177], v[170:171], v[176:177], s[48:49] op_sel_hi:[1,1,0]
	v_max_f32_e32 v158, 0, v154
	v_pk_mul_f32 v[170:171], v[170:171], v[176:177]
	v_pk_mul_f32 v[176:177], v[152:153], v[152:153]
	v_max_f32_e32 v159, 0, v155
	v_pk_mul_f32 v[170:171], v[178:179], v[170:171]
	v_max_f32_e32 v174, 0, v152
	v_fma_f32 v154, -|v154|, v170, v158
	v_fma_f32 v155, -|v155|, v171, v159
	v_pk_fma_f32 v[158:159], v[180:181], s[40:41], v[146:147] op_sel_hi:[1,0,0]
	v_pk_mul_f32 v[170:171], v[176:177], s[50:51] op_sel_hi:[1,0]
	v_pk_fma_f32 v[158:159], v[180:181], v[158:159], s[44:45] op_sel_hi:[1,1,0]
	v_exp_f32_e32 v170, v170
	v_exp_f32_e32 v171, v171
	v_pk_fma_f32 v[158:159], v[180:181], v[158:159], s[46:47] op_sel_hi:[1,1,0]
	v_max_f32_e32 v175, 0, v153
	v_pk_fma_f32 v[158:159], v[180:181], v[158:159], s[48:49] op_sel_hi:[1,1,0]
	v_pk_mul_f32 v[178:179], v[172:173], v[172:173]
	v_pk_mul_f32 v[158:159], v[180:181], v[158:159]
	v_pk_mul_f32 v[178:179], v[178:179], s[50:51] op_sel_hi:[1,0]
	v_pk_mul_f32 v[158:159], v[170:171], v[158:159]
	v_fma_f32 v176, |v172|, s38, 1.0
	v_fma_f32 v177, |v173|, s38, 1.0
	v_fma_f32 v158, -|v152|, v158, v174
	v_fma_f32 v159, -|v153|, v159, v175
	v_rcp_f32_e32 v176, v176
	v_rcp_f32_e32 v177, v177
	v_exp_f32_e32 v178, v178
	v_pk_fma_f32 v[174:175], v[176:177], s[40:41], v[146:147] op_sel_hi:[1,0,0]
	v_exp_f32_e32 v179, v179
	v_pk_fma_f32 v[174:175], v[176:177], v[174:175], s[44:45] op_sel_hi:[1,1,0]
	v_fma_f32 v180, |v156|, s38, 1.0
	v_fma_f32 v181, |v157|, s38, 1.0
	v_pk_fma_f32 v[174:175], v[176:177], v[174:175], s[46:47] op_sel_hi:[1,1,0]
	v_rcp_f32_e32 v180, v180
	v_rcp_f32_e32 v181, v181
	v_pk_fma_f32 v[174:175], v[176:177], v[174:175], s[48:49] op_sel_hi:[1,1,0]
	v_max_f32_e32 v170, 0, v172
	v_pk_mul_f32 v[174:175], v[176:177], v[174:175]
	v_pk_mul_f32 v[176:177], v[156:157], v[156:157]
	v_max_f32_e32 v171, 0, v173
	v_pk_mul_f32 v[174:175], v[178:179], v[174:175]
	v_max_f32_e32 v152, 0, v156
	v_fma_f32 v170, -|v172|, v174, v170
	v_fma_f32 v171, -|v173|, v175, v171
	v_pk_fma_f32 v[172:173], v[180:181], s[40:41], v[146:147] op_sel_hi:[1,0,0]
	v_pk_mul_f32 v[174:175], v[176:177], s[50:51] op_sel_hi:[1,0]
	v_pk_fma_f32 v[172:173], v[180:181], v[172:173], s[44:45] op_sel_hi:[1,1,0]
	v_exp_f32_e32 v174, v174
	v_exp_f32_e32 v175, v175
	v_pk_fma_f32 v[172:173], v[180:181], v[172:173], s[46:47] op_sel_hi:[1,1,0]
	v_max_f32_e32 v153, 0, v157
	v_pk_fma_f32 v[172:173], v[180:181], v[172:173], s[48:49] op_sel_hi:[1,1,0]
	v_add_co_u32_e32 v148, vcc, s85, v148
	v_pk_mul_f32 v[172:173], v[180:181], v[172:173]
	s_nop 0
	v_addc_co_u32_e32 v149, vcc, 0, v149, vcc
	v_pk_mul_f32 v[172:173], v[174:175], v[172:173]
	s_nop 0
	v_fma_f32 v156, -|v156|, v172, v152
	v_fma_f32 v157, -|v157|, v173, v153
	v_cvt_pk_bf16_f32 v152, v154, v155
	v_cvt_pk_bf16_f32 v153, v158, v159
	v_cvt_pk_bf16_f32 v154, v170, v171
	v_pk_add_f32 v[170:171], v[0:1], 0 op_sel_hi:[1,0]
	v_cvt_pk_bf16_f32 v155, v156, v157
	global_store_dwordx4 v[148:149], v[152:155], off
	v_pk_add_f32 v[148:149], v[6:7], 0 op_sel_hi:[1,0]
	s_nop 0
	v_pk_add_f32 v[152:153], v[4:5], 0 op_sel_hi:[1,0]
	v_and_b32_e32 v173, 0x7fffffff, v149
	v_fma_f32 v158, |v152|, s38, 1.0
	v_fma_f32 v159, |v153|, s38, 1.0
	v_pk_mul_f32 v[176:177], v[152:153], v[152:153]
	v_rcp_f32_e32 v158, v158
	v_rcp_f32_e32 v159, v159
	v_and_b32_e32 v172, 0x7fffffff, v148
	v_pk_mul_f32 v[176:177], v[176:177], s[50:51] op_sel_hi:[1,0]
	v_pk_fma_f32 v[178:179], v[172:173], s[38:39], 1.0 op_sel_hi:[1,0,0]
	v_pk_fma_f32 v[174:175], v[158:159], s[40:41], v[146:147] op_sel_hi:[1,0,0]
	v_exp_f32_e32 v176, v176
	v_pk_fma_f32 v[174:175], v[158:159], v[174:175], s[44:45] op_sel_hi:[1,1,0]
	v_exp_f32_e32 v177, v177
	v_pk_fma_f32 v[174:175], v[158:159], v[174:175], s[46:47] op_sel_hi:[1,1,0]
	v_rcp_f32_e32 v178, v178
	v_rcp_f32_e32 v179, v179
	v_pk_fma_f32 v[174:175], v[158:159], v[174:175], s[48:49] op_sel_hi:[1,1,0]
	v_max_f32_e32 v156, 0, v152
	v_pk_mul_f32 v[158:159], v[158:159], v[174:175]
	v_pk_mul_f32 v[174:175], v[148:149], v[148:149]
	v_max_f32_e32 v157, 0, v153
	v_pk_mul_f32 v[158:159], v[176:177], v[158:159]
	v_pk_add_f32 v[154:155], v[2:3], 0 op_sel_hi:[1,0]
	v_fma_f32 v152, -|v152|, v158, v156
	v_fma_f32 v153, -|v153|, v159, v157
	v_pk_fma_f32 v[156:157], v[178:179], s[40:41], v[146:147] op_sel_hi:[1,0,0]
	v_pk_mul_f32 v[158:159], v[174:175], s[50:51] op_sel_hi:[1,0]
	v_pk_fma_f32 v[156:157], v[178:179], v[156:157], s[44:45] op_sel_hi:[1,1,0]
	v_exp_f32_e32 v158, v158
	v_exp_f32_e32 v159, v159
	v_pk_fma_f32 v[156:157], v[178:179], v[156:157], s[46:47] op_sel_hi:[1,1,0]
	v_max_f32_e32 v148, 0, v148
	v_pk_fma_f32 v[156:157], v[178:179], v[156:157], s[48:49] op_sel_hi:[1,1,0]
	v_max_f32_e32 v149, 0, v149
	v_pk_mul_f32 v[156:157], v[178:179], v[156:157]
	v_pk_mul_f32 v[176:177], v[170:171], v[170:171]
	v_pk_mul_f32 v[156:157], v[158:159], v[156:157]
	v_fma_f32 v174, |v170|, s38, 1.0
	v_fma_f32 v175, |v171|, s38, 1.0
	v_pk_fma_f32 v[148:149], v[172:173], v[156:157], v[148:149] neg_lo:[1,0,0] neg_hi:[1,0,0]
	v_rcp_f32_e32 v174, v174
	v_rcp_f32_e32 v175, v175
	v_pk_mul_f32 v[176:177], v[176:177], s[50:51] op_sel_hi:[1,0]
	v_pk_fma_f32 v[172:173], v[174:175], s[40:41], v[146:147] op_sel_hi:[1,0,0]
	v_exp_f32_e32 v176, v176
	v_pk_fma_f32 v[172:173], v[174:175], v[172:173], s[44:45] op_sel_hi:[1,1,0]
	v_exp_f32_e32 v177, v177
	v_fma_f32 v178, |v154|, s38, 1.0
	v_fma_f32 v179, |v155|, s38, 1.0
	v_pk_fma_f32 v[172:173], v[174:175], v[172:173], s[46:47] op_sel_hi:[1,1,0]
	v_rcp_f32_e32 v178, v178
	v_rcp_f32_e32 v179, v179
	v_pk_fma_f32 v[172:173], v[174:175], v[172:173], s[48:49] op_sel_hi:[1,1,0]
	v_max_f32_e32 v158, 0, v170
	v_pk_mul_f32 v[172:173], v[174:175], v[172:173]
	v_pk_mul_f32 v[174:175], v[154:155], v[154:155]
	v_max_f32_e32 v159, 0, v171
	v_pk_mul_f32 v[172:173], v[176:177], v[172:173]
	v_pk_fma_f32 v[146:147], v[178:179], s[40:41], v[146:147] op_sel_hi:[1,0,0]
	v_fma_f32 v158, -|v170|, v172, v158
	v_fma_f32 v159, -|v171|, v173, v159
	v_pk_mul_f32 v[170:171], v[174:175], s[50:51] op_sel_hi:[1,0]
	v_pk_fma_f32 v[146:147], v[178:179], v[146:147], s[44:45] op_sel_hi:[1,1,0]
	v_exp_f32_e32 v170, v170
	v_exp_f32_e32 v171, v171
	v_pk_fma_f32 v[146:147], v[178:179], v[146:147], s[46:47] op_sel_hi:[1,1,0]
	v_max_f32_e32 v156, 0, v154
	v_pk_fma_f32 v[146:147], v[178:179], v[146:147], s[48:49] op_sel_hi:[1,1,0]
	v_max_f32_e32 v157, 0, v155
	v_pk_mul_f32 v[146:147], v[178:179], v[146:147]
	s_nop 0
	v_pk_mul_f32 v[146:147], v[170:171], v[146:147]
	s_nop 0
	v_fma_f32 v154, -|v154|, v146, v156
	v_fma_f32 v155, -|v155|, v147, v157
	v_cvt_pk_bf16_f32 v146, v152, v153
	v_cvt_pk_bf16_f32 v147, v148, v149
	v_cvt_pk_bf16_f32 v148, v158, v159
	s_nop 0
	v_cvt_pk_bf16_f32 v149, v154, v155
	global_store_dwordx4 v[150:151], v[146:149], off offset:256

.LBB0_280:
	s_andn2_b64 vcc, exec, s[70:71]
	s_cbranch_vccnz .LBB0_314
	v_ashrrev_i32_e32 v155, 31, v154
	v_lshl_add_u64 v[150:151], v[154:155], 2, s[14:15]
	global_load_dword v169, v[150:151], off
	v_lshlrev_b64 v[146:147], 15, v[154:155]
	v_lshl_add_u64 v[146:147], s[22:23], 0, v[146:147]
	v_lshl_add_u64 v[148:149], v[146:147], 0, v[152:153]
	v_fma_f32 v146, |v124|, s38, 1.0
	v_fma_f32 v147, |v125|, s38, 1.0
	v_pk_mul_f32 v[174:175], v[124:125], v[124:125]
	v_rcp_f32_e32 v158, v146
	v_rcp_f32_e32 v159, v147
	v_mov_b64_e32 v[146:147], s[42:43]
	v_pk_fma_f32 v[172:173], v[158:159], s[40:41], v[146:147] op_sel_hi:[1,0,0]
	v_pk_mul_f32 v[174:175], v[174:175], s[50:51] op_sel_hi:[1,0]
	v_pk_fma_f32 v[172:173], v[158:159], v[172:173], s[44:45] op_sel_hi:[1,1,0]
	v_exp_f32_e32 v174, v174
	v_exp_f32_e32 v175, v175
	v_fma_f32 v176, |v126|, s38, 1.0
	v_fma_f32 v177, |v127|, s38, 1.0
	v_pk_fma_f32 v[172:173], v[158:159], v[172:173], s[46:47] op_sel_hi:[1,1,0]
	v_rcp_f32_e32 v176, v176
	v_rcp_f32_e32 v177, v177
	v_pk_fma_f32 v[172:173], v[158:159], v[172:173], s[48:49] op_sel_hi:[1,1,0]
	v_pk_mul_f32 v[158:159], v[158:159], v[172:173]
	v_pk_mul_f32 v[172:173], v[126:127], v[126:127]
	v_max_f32_e32 v156, 0, v124
	v_max_f32_e32 v157, 0, v125
	v_pk_mul_f32 v[158:159], v[174:175], v[158:159]
	v_fma_f32 v156, -|v124|, v158, v156
	v_fma_f32 v157, -|v125|, v159, v157
	v_pk_fma_f32 v[124:125], v[176:177], s[40:41], v[146:147] op_sel_hi:[1,0,0]
	v_pk_mul_f32 v[158:159], v[172:173], s[50:51] op_sel_hi:[1,0]
	v_pk_fma_f32 v[124:125], v[176:177], v[124:125], s[44:45] op_sel_hi:[1,1,0]
	v_exp_f32_e32 v158, v158
	v_exp_f32_e32 v159, v159
	v_pk_fma_f32 v[124:125], v[176:177], v[124:125], s[46:47] op_sel_hi:[1,1,0]
	v_pk_fma_f32 v[124:125], v[176:177], v[124:125], s[48:49] op_sel_hi:[1,1,0]
	v_max_f32_e32 v170, 0, v126
	v_pk_mul_f32 v[124:125], v[176:177], v[124:125]
	v_max_f32_e32 v171, 0, v127
	v_pk_mul_f32 v[124:125], v[158:159], v[124:125]
	v_fma_f32 v172, |v120|, s38, 1.0
	v_fma_f32 v173, |v121|, s38, 1.0
	v_pk_mul_f32 v[174:175], v[120:121], v[120:121]
	v_rcp_f32_e32 v172, v172
	v_rcp_f32_e32 v173, v173
	v_fma_f32 v126, -|v126|, v124, v170
	v_fma_f32 v127, -|v127|, v125, v171
	v_pk_fma_f32 v[124:125], v[172:173], s[40:41], v[146:147] op_sel_hi:[1,0,0]
	v_pk_mul_f32 v[174:175], v[174:175], s[50:51] op_sel_hi:[1,0]
	v_pk_fma_f32 v[124:125], v[172:173], v[124:125], s[44:45] op_sel_hi:[1,1,0]
	v_exp_f32_e32 v174, v174
	v_exp_f32_e32 v175, v175
	v_fma_f32 v176, |v122|, s38, 1.0
	v_fma_f32 v177, |v123|, s38, 1.0
	v_pk_fma_f32 v[124:125], v[172:173], v[124:125], s[46:47] op_sel_hi:[1,1,0]
	v_rcp_f32_e32 v176, v176
	v_rcp_f32_e32 v177, v177
	v_pk_fma_f32 v[124:125], v[172:173], v[124:125], s[48:49] op_sel_hi:[1,1,0]
	v_pk_mul_f32 v[124:125], v[172:173], v[124:125]
	v_pk_mul_f32 v[172:173], v[122:123], v[122:123]
	v_max_f32_e32 v158, 0, v120
	v_max_f32_e32 v159, 0, v121
	v_pk_mul_f32 v[124:125], v[174:175], v[124:125]
	v_fma_f32 v124, -|v120|, v124, v158
	v_fma_f32 v125, -|v121|, v125, v159
	v_pk_fma_f32 v[120:121], v[176:177], s[40:41], v[146:147] op_sel_hi:[1,0,0]
	v_pk_mul_f32 v[158:159], v[172:173], s[50:51] op_sel_hi:[1,0]
	v_pk_fma_f32 v[120:121], v[176:177], v[120:121], s[44:45] op_sel_hi:[1,1,0]
	v_exp_f32_e32 v158, v158
	v_exp_f32_e32 v159, v159
	v_pk_fma_f32 v[120:121], v[176:177], v[120:121], s[46:47] op_sel_hi:[1,1,0]
	v_pk_fma_f32 v[120:121], v[176:177], v[120:121], s[48:49] op_sel_hi:[1,1,0]
	v_max_f32_e32 v170, 0, v122
	v_pk_mul_f32 v[120:121], v[176:177], v[120:121]
	v_max_f32_e32 v171, 0, v123
	v_pk_mul_f32 v[120:121], v[158:159], v[120:121]
	v_pk_mul_f32 v[174:175], v[116:117], v[116:117]
	v_fma_f32 v122, -|v122|, v120, v170
	v_fma_f32 v123, -|v123|, v121, v171
	s_waitcnt vmcnt(0)
	v_pk_mul_f32 v[120:121], v[156:157], v[168:169] op_sel:[0,1] op_sel_hi:[1,1]
	v_cvt_pk_bf16_f32 v170, v120, v121
	v_pk_mul_f32 v[120:121], v[126:127], v[168:169] op_sel:[0,1] op_sel_hi:[1,1]
	v_cvt_pk_bf16_f32 v171, v120, v121
	v_pk_mul_f32 v[120:121], v[124:125], v[168:169] op_sel:[0,1] op_sel_hi:[1,1]
	v_cvt_pk_bf16_f32 v172, v120, v121
	v_pk_mul_f32 v[120:121], v[122:123], v[168:169] op_sel:[0,1] op_sel_hi:[1,1]
	v_cvt_pk_bf16_f32 v173, v120, v121
	v_fma_f32 v158, |v116|, s38, 1.0
	v_fma_f32 v159, |v117|, s38, 1.0
	global_store_dwordx4 v[148:149], v[170:173], off
	v_rcp_f32_e32 v158, v158
	v_rcp_f32_e32 v159, v159
	v_pk_mul_f32 v[174:175], v[174:175], s[50:51] op_sel_hi:[1,0]
	v_pk_fma_f32 v[172:173], v[158:159], s[40:41], v[146:147] op_sel_hi:[1,0,0]
	v_exp_f32_e32 v174, v174
	v_pk_fma_f32 v[172:173], v[158:159], v[172:173], s[44:45] op_sel_hi:[1,1,0]
	v_exp_f32_e32 v175, v175
	v_fma_f32 v176, |v118|, s38, 1.0
	v_fma_f32 v177, |v119|, s38, 1.0
	v_pk_fma_f32 v[172:173], v[158:159], v[172:173], s[46:47] op_sel_hi:[1,1,0]
	v_rcp_f32_e32 v176, v176
	v_rcp_f32_e32 v177, v177
	v_pk_fma_f32 v[172:173], v[158:159], v[172:173], s[48:49] op_sel_hi:[1,1,0]
	v_pk_mul_f32 v[158:159], v[158:159], v[172:173]
	v_pk_mul_f32 v[172:173], v[118:119], v[118:119]
	v_max_f32_e32 v120, 0, v116
	v_max_f32_e32 v121, 0, v117
	v_pk_mul_f32 v[158:159], v[174:175], v[158:159]
	v_fma_f32 v120, -|v116|, v158, v120
	v_fma_f32 v121, -|v117|, v159, v121
	v_pk_fma_f32 v[116:117], v[176:177], s[40:41], v[146:147] op_sel_hi:[1,0,0]
	v_pk_mul_f32 v[158:159], v[172:173], s[50:51] op_sel_hi:[1,0]
	v_pk_fma_f32 v[116:117], v[176:177], v[116:117], s[44:45] op_sel_hi:[1,1,0]
	v_exp_f32_e32 v158, v158
	v_exp_f32_e32 v159, v159
	v_pk_fma_f32 v[116:117], v[176:177], v[116:117], s[46:47] op_sel_hi:[1,1,0]
	v_pk_fma_f32 v[116:117], v[176:177], v[116:117], s[48:49] op_sel_hi:[1,1,0]
	v_max_f32_e32 v170, 0, v118
	v_pk_mul_f32 v[116:117], v[176:177], v[116:117]
	v_max_f32_e32 v171, 0, v119
	v_pk_mul_f32 v[116:117], v[158:159], v[116:117]
	v_fma_f32 v172, |v112|, s38, 1.0
	v_fma_f32 v173, |v113|, s38, 1.0
	v_pk_mul_f32 v[174:175], v[112:113], v[112:113]
	v_rcp_f32_e32 v172, v172
	v_rcp_f32_e32 v173, v173
	v_fma_f32 v118, -|v118|, v116, v170
	v_fma_f32 v119, -|v119|, v117, v171
	v_pk_fma_f32 v[116:117], v[172:173], s[40:41], v[146:147] op_sel_hi:[1,0,0]
	v_pk_mul_f32 v[174:175], v[174:175], s[50:51] op_sel_hi:[1,0]
	v_pk_fma_f32 v[116:117], v[172:173], v[116:117], s[44:45] op_sel_hi:[1,1,0]
	v_exp_f32_e32 v174, v174
	v_exp_f32_e32 v175, v175
	v_fma_f32 v176, |v114|, s38, 1.0
	v_fma_f32 v177, |v115|, s38, 1.0
	v_pk_fma_f32 v[116:117], v[172:173], v[116:117], s[46:47] op_sel_hi:[1,1,0]
	v_rcp_f32_e32 v176, v176
	v_rcp_f32_e32 v177, v177
	v_pk_fma_f32 v[116:117], v[172:173], v[116:117], s[48:49] op_sel_hi:[1,1,0]
	v_pk_mul_f32 v[116:117], v[172:173], v[116:117]
	v_pk_mul_f32 v[172:173], v[114:115], v[114:115]
	v_max_f32_e32 v158, 0, v112
	v_max_f32_e32 v159, 0, v113
	v_pk_mul_f32 v[116:117], v[174:175], v[116:117]
	v_fma_f32 v116, -|v112|, v116, v158
	v_fma_f32 v117, -|v113|, v117, v159
	v_pk_fma_f32 v[112:113], v[176:177], s[40:41], v[146:147] op_sel_hi:[1,0,0]
	v_pk_mul_f32 v[158:159], v[172:173], s[50:51] op_sel_hi:[1,0]
	v_pk_fma_f32 v[112:113], v[176:177], v[112:113], s[44:45] op_sel_hi:[1,1,0]
	v_exp_f32_e32 v158, v158
	v_exp_f32_e32 v159, v159
	v_pk_fma_f32 v[112:113], v[176:177], v[112:113], s[46:47] op_sel_hi:[1,1,0]
	v_pk_fma_f32 v[112:113], v[176:177], v[112:113], s[48:49] op_sel_hi:[1,1,0]
	v_max_f32_e32 v170, 0, v114
	v_pk_mul_f32 v[112:113], v[176:177], v[112:113]
	v_max_f32_e32 v171, 0, v115
	v_pk_mul_f32 v[112:113], v[158:159], v[112:113]
	v_pk_mul_f32 v[176:177], v[108:109], v[108:109]
	v_fma_f32 v112, -|v114|, v112, v170
	v_fma_f32 v113, -|v115|, v113, v171
	v_pk_mul_f32 v[114:115], v[120:121], v[168:169] op_sel:[0,1] op_sel_hi:[1,1]
	v_cvt_pk_bf16_f32 v170, v114, v115
	v_pk_mul_f32 v[114:115], v[118:119], v[168:169] op_sel:[0,1] op_sel_hi:[1,1]
	v_cvt_pk_bf16_f32 v171, v114, v115
	v_pk_mul_f32 v[114:115], v[116:117], v[168:169] op_sel:[0,1] op_sel_hi:[1,1]
	v_cvt_pk_bf16_f32 v172, v114, v115
	v_pk_mul_f32 v[114:115], v[112:113], v[168:169] op_sel:[0,1] op_sel_hi:[1,1]
	v_cvt_pk_bf16_f32 v173, v114, v115
	global_store_dwordx4 v[148:149], v[170:173], off offset:256
	global_load_dword v155, v[150:151], off offset:64
	v_or_b32_e32 v114, 16, v154
	v_fma_f32 v158, |v108|, s38, 1.0
	v_fma_f32 v159, |v109|, s38, 1.0
	v_ashrrev_i32_e32 v115, 31, v114
	v_rcp_f32_e32 v172, v158
	v_rcp_f32_e32 v173, v159
	v_lshlrev_b64 v[114:115], 15, v[114:115]
	v_lshl_add_u64 v[114:115], s[22:23], 0, v[114:115]
	v_lshl_add_u64 v[158:159], v[114:115], 0, v[152:153]
	v_pk_fma_f32 v[174:175], v[172:173], s[40:41], v[146:147] op_sel_hi:[1,0,0]
	v_pk_mul_f32 v[176:177], v[176:177], s[50:51] op_sel_hi:[1,0]
	v_pk_fma_f32 v[174:175], v[172:173], v[174:175], s[44:45] op_sel_hi:[1,1,0]
	v_exp_f32_e32 v176, v176
	v_exp_f32_e32 v177, v177
	v_fma_f32 v178, |v110|, s38, 1.0
	v_fma_f32 v179, |v111|, s38, 1.0
	v_pk_fma_f32 v[174:175], v[172:173], v[174:175], s[46:47] op_sel_hi:[1,1,0]
	v_rcp_f32_e32 v178, v178
	v_rcp_f32_e32 v179, v179
	v_pk_fma_f32 v[174:175], v[172:173], v[174:175], s[48:49] op_sel_hi:[1,1,0]
	v_pk_mul_f32 v[172:173], v[172:173], v[174:175]
	v_pk_mul_f32 v[174:175], v[110:111], v[110:111]
	v_max_f32_e32 v170, 0, v108
	v_max_f32_e32 v171, 0, v109
	v_pk_mul_f32 v[172:173], v[176:177], v[172:173]
	v_fma_f32 v170, -|v108|, v172, v170
	v_fma_f32 v171, -|v109|, v173, v171
	v_pk_fma_f32 v[108:109], v[178:179], s[40:41], v[146:147] op_sel_hi:[1,0,0]
	v_pk_mul_f32 v[172:173], v[174:175], s[50:51] op_sel_hi:[1,0]
	v_pk_fma_f32 v[108:109], v[178:179], v[108:109], s[44:45] op_sel_hi:[1,1,0]
	v_exp_f32_e32 v172, v172
	v_exp_f32_e32 v173, v173
	v_pk_fma_f32 v[108:109], v[178:179], v[108:109], s[46:47] op_sel_hi:[1,1,0]
	v_pk_fma_f32 v[108:109], v[178:179], v[108:109], s[48:49] op_sel_hi:[1,1,0]
	v_max_f32_e32 v114, 0, v110
	v_pk_mul_f32 v[108:109], v[178:179], v[108:109]
	v_max_f32_e32 v115, 0, v111
	v_pk_mul_f32 v[108:109], v[172:173], v[108:109]
	v_fma_f32 v174, |v104|, s38, 1.0
	v_fma_f32 v175, |v105|, s38, 1.0
	v_pk_mul_f32 v[176:177], v[104:105], v[104:105]
	v_rcp_f32_e32 v174, v174
	v_rcp_f32_e32 v175, v175
	v_fma_f32 v110, -|v110|, v108, v114
	v_fma_f32 v111, -|v111|, v109, v115
	v_pk_fma_f32 v[108:109], v[174:175], s[40:41], v[146:147] op_sel_hi:[1,0,0]
	v_pk_mul_f32 v[176:177], v[176:177], s[50:51] op_sel_hi:[1,0]
	v_pk_fma_f32 v[108:109], v[174:175], v[108:109], s[44:45] op_sel_hi:[1,1,0]
	v_exp_f32_e32 v176, v176
	v_exp_f32_e32 v177, v177
	v_fma_f32 v178, |v106|, s38, 1.0
	v_fma_f32 v179, |v107|, s38, 1.0
	v_pk_fma_f32 v[108:109], v[174:175], v[108:109], s[46:47] op_sel_hi:[1,1,0]
	v_rcp_f32_e32 v178, v178
	v_rcp_f32_e32 v179, v179
	v_pk_fma_f32 v[108:109], v[174:175], v[108:109], s[48:49] op_sel_hi:[1,1,0]
	v_pk_mul_f32 v[108:109], v[174:175], v[108:109]
	v_pk_mul_f32 v[174:175], v[106:107], v[106:107]
	v_max_f32_e32 v172, 0, v104
	v_max_f32_e32 v173, 0, v105
	v_pk_mul_f32 v[108:109], v[176:177], v[108:109]
	v_fma_f32 v108, -|v104|, v108, v172
	v_fma_f32 v109, -|v105|, v109, v173
	v_pk_fma_f32 v[104:105], v[178:179], s[40:41], v[146:147] op_sel_hi:[1,0,0]
	v_pk_mul_f32 v[172:173], v[174:175], s[50:51] op_sel_hi:[1,0]
	v_pk_fma_f32 v[104:105], v[178:179], v[104:105], s[44:45] op_sel_hi:[1,1,0]
	v_exp_f32_e32 v172, v172
	v_exp_f32_e32 v173, v173
	v_pk_fma_f32 v[104:105], v[178:179], v[104:105], s[46:47] op_sel_hi:[1,1,0]
	v_pk_fma_f32 v[104:105], v[178:179], v[104:105], s[48:49] op_sel_hi:[1,1,0]
	v_max_f32_e32 v114, 0, v106
	v_pk_mul_f32 v[104:105], v[178:179], v[104:105]
	v_max_f32_e32 v115, 0, v107
	v_pk_mul_f32 v[104:105], v[172:173], v[104:105]
	v_pk_mul_f32 v[174:175], v[100:101], v[100:101]
	v_fma_f32 v104, -|v106|, v104, v114
	v_fma_f32 v105, -|v107|, v105, v115
	v_pk_mul_f32 v[106:107], v[170:171], v[170:171]
	v_pk_mul_f32 v[174:175], v[174:175], s[50:51] op_sel_hi:[1,0]
	v_pk_fma_f32 v[114:115], v[156:157], v[156:157], v[106:107]
	s_waitcnt vmcnt(0)
	v_pk_mul_f32 v[106:107], v[170:171], v[154:155] op_sel:[0,1] op_sel_hi:[1,1]
	v_cvt_pk_bf16_f32 v170, v106, v107
	v_pk_mul_f32 v[106:107], v[110:111], v[154:155] op_sel:[0,1] op_sel_hi:[1,1]
	v_cvt_pk_bf16_f32 v171, v106, v107
	v_pk_mul_f32 v[106:107], v[108:109], v[154:155] op_sel:[0,1] op_sel_hi:[1,1]
	v_cvt_pk_bf16_f32 v172, v106, v107
	v_pk_mul_f32 v[106:107], v[104:105], v[154:155] op_sel:[0,1] op_sel_hi:[1,1]
	v_cvt_pk_bf16_f32 v173, v106, v107
	v_fma_f32 v156, |v100|, s38, 1.0
	v_fma_f32 v157, |v101|, s38, 1.0
	global_store_dwordx4 v[158:159], v[170:173], off
	v_rcp_f32_e32 v156, v156
	v_rcp_f32_e32 v157, v157
	v_exp_f32_e32 v174, v174
	v_pk_fma_f32 v[172:173], v[156:157], s[40:41], v[146:147] op_sel_hi:[1,0,0]
	v_exp_f32_e32 v175, v175
	v_pk_fma_f32 v[172:173], v[156:157], v[172:173], s[44:45] op_sel_hi:[1,1,0]
	v_fma_f32 v176, |v102|, s38, 1.0
	v_fma_f32 v177, |v103|, s38, 1.0
	v_pk_fma_f32 v[172:173], v[156:157], v[172:173], s[46:47] op_sel_hi:[1,1,0]
	v_rcp_f32_e32 v176, v176
	v_rcp_f32_e32 v177, v177
	v_pk_fma_f32 v[172:173], v[156:157], v[172:173], s[48:49] op_sel_hi:[1,1,0]
	v_pk_mul_f32 v[156:157], v[156:157], v[172:173]
	v_pk_mul_f32 v[172:173], v[102:103], v[102:103]
	v_max_f32_e32 v106, 0, v100
	v_max_f32_e32 v107, 0, v101
	v_pk_mul_f32 v[156:157], v[174:175], v[156:157]
	v_fma_f32 v106, -|v100|, v156, v106
	v_fma_f32 v107, -|v101|, v157, v107
	v_pk_fma_f32 v[100:101], v[176:177], s[40:41], v[146:147] op_sel_hi:[1,0,0]
	v_pk_mul_f32 v[156:157], v[172:173], s[50:51] op_sel_hi:[1,0]
	v_pk_fma_f32 v[100:101], v[176:177], v[100:101], s[44:45] op_sel_hi:[1,1,0]
	v_exp_f32_e32 v156, v156
	v_exp_f32_e32 v157, v157
	v_pk_fma_f32 v[100:101], v[176:177], v[100:101], s[46:47] op_sel_hi:[1,1,0]
	v_pk_fma_f32 v[100:101], v[176:177], v[100:101], s[48:49] op_sel_hi:[1,1,0]
	v_max_f32_e32 v170, 0, v102
	v_pk_mul_f32 v[100:101], v[176:177], v[100:101]
	v_max_f32_e32 v171, 0, v103
	v_pk_mul_f32 v[100:101], v[156:157], v[100:101]
	v_fma_f32 v172, |v96|, s38, 1.0
	v_fma_f32 v173, |v97|, s38, 1.0
	v_pk_mul_f32 v[174:175], v[96:97], v[96:97]
	v_rcp_f32_e32 v172, v172
	v_rcp_f32_e32 v173, v173
	v_fma_f32 v102, -|v102|, v100, v170
	v_fma_f32 v103, -|v103|, v101, v171
	v_pk_fma_f32 v[100:101], v[172:173], s[40:41], v[146:147] op_sel_hi:[1,0,0]
	v_pk_mul_f32 v[174:175], v[174:175], s[50:51] op_sel_hi:[1,0]
	v_pk_fma_f32 v[100:101], v[172:173], v[100:101], s[44:45] op_sel_hi:[1,1,0]
	v_exp_f32_e32 v174, v174
	v_exp_f32_e32 v175, v175
	v_fma_f32 v176, |v98|, s38, 1.0
	v_fma_f32 v177, |v99|, s38, 1.0
	v_pk_fma_f32 v[100:101], v[172:173], v[100:101], s[46:47] op_sel_hi:[1,1,0]
	v_rcp_f32_e32 v176, v176
	v_rcp_f32_e32 v177, v177
	v_pk_fma_f32 v[100:101], v[172:173], v[100:101], s[48:49] op_sel_hi:[1,1,0]
	v_pk_mul_f32 v[100:101], v[172:173], v[100:101]
	v_pk_mul_f32 v[172:173], v[98:99], v[98:99]
	v_max_f32_e32 v156, 0, v96
	v_max_f32_e32 v157, 0, v97
	v_pk_mul_f32 v[100:101], v[174:175], v[100:101]
	v_fma_f32 v100, -|v96|, v100, v156
	v_fma_f32 v101, -|v97|, v101, v157
	v_pk_fma_f32 v[96:97], v[176:177], s[40:41], v[146:147] op_sel_hi:[1,0,0]
	v_pk_mul_f32 v[156:157], v[172:173], s[50:51] op_sel_hi:[1,0]
	v_pk_fma_f32 v[96:97], v[176:177], v[96:97], s[44:45] op_sel_hi:[1,1,0]
	v_exp_f32_e32 v156, v156
	v_exp_f32_e32 v157, v157
	v_pk_fma_f32 v[96:97], v[176:177], v[96:97], s[46:47] op_sel_hi:[1,1,0]
	v_pk_fma_f32 v[96:97], v[176:177], v[96:97], s[48:49] op_sel_hi:[1,1,0]
	v_max_f32_e32 v170, 0, v98
	v_pk_mul_f32 v[96:97], v[176:177], v[96:97]
	v_max_f32_e32 v171, 0, v99
	v_pk_mul_f32 v[96:97], v[156:157], v[96:97]
	v_pk_mul_f32 v[174:175], v[92:93], v[92:93]
	v_fma_f32 v96, -|v98|, v96, v170
	v_fma_f32 v97, -|v99|, v97, v171
	v_pk_mul_f32 v[98:99], v[106:107], v[154:155] op_sel:[0,1] op_sel_hi:[1,1]
	v_cvt_pk_bf16_f32 v170, v98, v99
	v_pk_mul_f32 v[98:99], v[102:103], v[154:155] op_sel:[0,1] op_sel_hi:[1,1]
	v_cvt_pk_bf16_f32 v171, v98, v99
	v_pk_mul_f32 v[98:99], v[100:101], v[154:155] op_sel:[0,1] op_sel_hi:[1,1]
	v_cvt_pk_bf16_f32 v172, v98, v99
	v_pk_mul_f32 v[98:99], v[96:97], v[154:155] op_sel:[0,1] op_sel_hi:[1,1]
	v_cvt_pk_bf16_f32 v173, v98, v99
	global_store_dwordx4 v[158:159], v[170:173], off offset:256
	global_load_dword v155, v[150:151], off offset:128
	v_fma_f32 v156, |v92|, s38, 1.0
	v_fma_f32 v157, |v93|, s38, 1.0
	v_or_b32_e32 v98, 32, v154
	v_rcp_f32_e32 v170, v156
	v_rcp_f32_e32 v171, v157
	v_ashrrev_i32_e32 v99, 31, v98
	v_lshlrev_b64 v[98:99], 15, v[98:99]
	v_lshl_add_u64 v[98:99], s[22:23], 0, v[98:99]
	v_lshl_add_u64 v[156:157], v[98:99], 0, v[152:153]
	v_pk_fma_f32 v[172:173], v[170:171], s[40:41], v[146:147] op_sel_hi:[1,0,0]
	v_pk_mul_f32 v[174:175], v[174:175], s[50:51] op_sel_hi:[1,0]
	v_pk_fma_f32 v[172:173], v[170:171], v[172:173], s[44:45] op_sel_hi:[1,1,0]
	v_exp_f32_e32 v174, v174
	v_exp_f32_e32 v175, v175
	v_fma_f32 v176, |v94|, s38, 1.0
	v_fma_f32 v177, |v95|, s38, 1.0
	v_pk_fma_f32 v[172:173], v[170:171], v[172:173], s[46:47] op_sel_hi:[1,1,0]
	v_rcp_f32_e32 v176, v176
	v_rcp_f32_e32 v177, v177
	v_pk_fma_f32 v[172:173], v[170:171], v[172:173], s[48:49] op_sel_hi:[1,1,0]
	v_pk_mul_f32 v[170:171], v[170:171], v[172:173]
	v_pk_mul_f32 v[172:173], v[94:95], v[94:95]
	v_max_f32_e32 v158, 0, v92
	v_max_f32_e32 v159, 0, v93
	v_pk_mul_f32 v[170:171], v[174:175], v[170:171]
	v_fma_f32 v158, -|v92|, v170, v158
	v_fma_f32 v159, -|v93|, v171, v159
	v_pk_fma_f32 v[92:93], v[176:177], s[40:41], v[146:147] op_sel_hi:[1,0,0]
	v_pk_mul_f32 v[170:171], v[172:173], s[50:51] op_sel_hi:[1,0]
	v_pk_fma_f32 v[92:93], v[176:177], v[92:93], s[44:45] op_sel_hi:[1,1,0]
	v_exp_f32_e32 v170, v170
	v_exp_f32_e32 v171, v171
	v_pk_fma_f32 v[92:93], v[176:177], v[92:93], s[46:47] op_sel_hi:[1,1,0]
	v_pk_fma_f32 v[92:93], v[176:177], v[92:93], s[48:49] op_sel_hi:[1,1,0]
	v_max_f32_e32 v98, 0, v94
	v_pk_mul_f32 v[92:93], v[176:177], v[92:93]
	v_max_f32_e32 v99, 0, v95
	v_pk_mul_f32 v[92:93], v[170:171], v[92:93]
	v_fma_f32 v172, |v88|, s38, 1.0
	v_fma_f32 v173, |v89|, s38, 1.0
	v_pk_mul_f32 v[174:175], v[88:89], v[88:89]
	v_rcp_f32_e32 v172, v172
	v_rcp_f32_e32 v173, v173
	v_fma_f32 v94, -|v94|, v92, v98
	v_fma_f32 v95, -|v95|, v93, v99
	v_pk_fma_f32 v[92:93], v[172:173], s[40:41], v[146:147] op_sel_hi:[1,0,0]
	v_pk_mul_f32 v[174:175], v[174:175], s[50:51] op_sel_hi:[1,0]
	v_pk_fma_f32 v[92:93], v[172:173], v[92:93], s[44:45] op_sel_hi:[1,1,0]
	v_exp_f32_e32 v174, v174
	v_exp_f32_e32 v175, v175
	v_fma_f32 v176, |v90|, s38, 1.0
	v_fma_f32 v177, |v91|, s38, 1.0
	v_pk_fma_f32 v[92:93], v[172:173], v[92:93], s[46:47] op_sel_hi:[1,1,0]
	v_rcp_f32_e32 v176, v176
	v_rcp_f32_e32 v177, v177
	v_pk_fma_f32 v[92:93], v[172:173], v[92:93], s[48:49] op_sel_hi:[1,1,0]
	v_pk_mul_f32 v[92:93], v[172:173], v[92:93]
	v_pk_mul_f32 v[172:173], v[90:91], v[90:91]
	v_max_f32_e32 v170, 0, v88
	v_max_f32_e32 v171, 0, v89
	v_pk_mul_f32 v[92:93], v[174:175], v[92:93]
	v_fma_f32 v92, -|v88|, v92, v170
	v_fma_f32 v93, -|v89|, v93, v171
	v_pk_fma_f32 v[88:89], v[176:177], s[40:41], v[146:147] op_sel_hi:[1,0,0]
	v_pk_mul_f32 v[170:171], v[172:173], s[50:51] op_sel_hi:[1,0]
	v_pk_fma_f32 v[88:89], v[176:177], v[88:89], s[44:45] op_sel_hi:[1,1,0]
	v_exp_f32_e32 v170, v170
	v_exp_f32_e32 v171, v171
	v_pk_fma_f32 v[88:89], v[176:177], v[88:89], s[46:47] op_sel_hi:[1,1,0]
	v_pk_fma_f32 v[88:89], v[176:177], v[88:89], s[48:49] op_sel_hi:[1,1,0]
	v_max_f32_e32 v98, 0, v90
	v_pk_mul_f32 v[88:89], v[176:177], v[88:89]
	v_max_f32_e32 v99, 0, v91
	v_pk_mul_f32 v[88:89], v[170:171], v[88:89]
	s_nop 0
	v_fma_f32 v88, -|v90|, v88, v98
	v_fma_f32 v89, -|v91|, v89, v99
	s_waitcnt vmcnt(0)
	v_pk_mul_f32 v[90:91], v[158:159], v[154:155] op_sel:[0,1] op_sel_hi:[1,1]
	v_cvt_pk_bf16_f32 v170, v90, v91
	v_pk_mul_f32 v[90:91], v[94:95], v[154:155] op_sel:[0,1] op_sel_hi:[1,1]
	v_cvt_pk_bf16_f32 v171, v90, v91
	v_pk_mul_f32 v[90:91], v[92:93], v[154:155] op_sel:[0,1] op_sel_hi:[1,1]
	v_cvt_pk_bf16_f32 v172, v90, v91
	v_pk_mul_f32 v[90:91], v[88:89], v[154:155] op_sel:[0,1] op_sel_hi:[1,1]
	v_cvt_pk_bf16_f32 v173, v90, v91
	v_pk_fma_f32 v[98:99], v[158:159], v[158:159], v[114:115]
	v_fma_f32 v114, |v84|, s38, 1.0
	v_fma_f32 v115, |v85|, s38, 1.0
	global_store_dwordx4 v[156:157], v[170:173], off
	v_rcp_f32_e32 v114, v114
	v_rcp_f32_e32 v115, v115
	v_pk_mul_f32 v[172:173], v[84:85], v[84:85]
	v_pk_fma_f32 v[170:171], v[114:115], s[40:41], v[146:147] op_sel_hi:[1,0,0]
	v_pk_mul_f32 v[172:173], v[172:173], s[50:51] op_sel_hi:[1,0]
	v_pk_fma_f32 v[170:171], v[114:115], v[170:171], s[44:45] op_sel_hi:[1,1,0]
	v_exp_f32_e32 v172, v172
	v_exp_f32_e32 v173, v173
	v_fma_f32 v174, |v86|, s38, 1.0
	v_fma_f32 v175, |v87|, s38, 1.0
	v_pk_fma_f32 v[170:171], v[114:115], v[170:171], s[46:47] op_sel_hi:[1,1,0]
	v_rcp_f32_e32 v174, v174
	v_rcp_f32_e32 v175, v175
	v_pk_fma_f32 v[170:171], v[114:115], v[170:171], s[48:49] op_sel_hi:[1,1,0]
	v_pk_mul_f32 v[114:115], v[114:115], v[170:171]
	v_pk_mul_f32 v[170:171], v[86:87], v[86:87]
	v_max_f32_e32 v90, 0, v84
	v_max_f32_e32 v91, 0, v85
	v_pk_mul_f32 v[114:115], v[172:173], v[114:115]
	v_fma_f32 v90, -|v84|, v114, v90
	v_fma_f32 v91, -|v85|, v115, v91
	v_pk_fma_f32 v[84:85], v[174:175], s[40:41], v[146:147] op_sel_hi:[1,0,0]
	v_pk_mul_f32 v[114:115], v[170:171], s[50:51] op_sel_hi:[1,0]
	v_pk_fma_f32 v[84:85], v[174:175], v[84:85], s[44:45] op_sel_hi:[1,1,0]
	v_exp_f32_e32 v114, v114
	v_exp_f32_e32 v115, v115
	v_pk_fma_f32 v[84:85], v[174:175], v[84:85], s[46:47] op_sel_hi:[1,1,0]
	v_pk_fma_f32 v[84:85], v[174:175], v[84:85], s[48:49] op_sel_hi:[1,1,0]
	v_max_f32_e32 v158, 0, v86
	v_pk_mul_f32 v[84:85], v[174:175], v[84:85]
	v_max_f32_e32 v159, 0, v87
	v_pk_mul_f32 v[84:85], v[114:115], v[84:85]
	v_fma_f32 v170, |v80|, s38, 1.0
	v_fma_f32 v171, |v81|, s38, 1.0
	v_pk_mul_f32 v[172:173], v[80:81], v[80:81]
	v_rcp_f32_e32 v170, v170
	v_rcp_f32_e32 v171, v171
	v_fma_f32 v86, -|v86|, v84, v158
	v_fma_f32 v87, -|v87|, v85, v159
	v_pk_fma_f32 v[84:85], v[170:171], s[40:41], v[146:147] op_sel_hi:[1,0,0]
	v_pk_mul_f32 v[172:173], v[172:173], s[50:51] op_sel_hi:[1,0]
	v_pk_fma_f32 v[84:85], v[170:171], v[84:85], s[44:45] op_sel_hi:[1,1,0]
	v_exp_f32_e32 v172, v172
	v_exp_f32_e32 v173, v173
	v_fma_f32 v174, |v82|, s38, 1.0
	v_fma_f32 v175, |v83|, s38, 1.0
	v_pk_fma_f32 v[84:85], v[170:171], v[84:85], s[46:47] op_sel_hi:[1,1,0]
	v_rcp_f32_e32 v174, v174
	v_rcp_f32_e32 v175, v175
	v_pk_fma_f32 v[84:85], v[170:171], v[84:85], s[48:49] op_sel_hi:[1,1,0]
	v_pk_mul_f32 v[84:85], v[170:171], v[84:85]
	v_pk_mul_f32 v[170:171], v[82:83], v[82:83]
	v_max_f32_e32 v114, 0, v80
	v_max_f32_e32 v115, 0, v81
	v_pk_mul_f32 v[84:85], v[172:173], v[84:85]
	v_fma_f32 v84, -|v80|, v84, v114
	v_fma_f32 v85, -|v81|, v85, v115
	v_pk_fma_f32 v[80:81], v[174:175], s[40:41], v[146:147] op_sel_hi:[1,0,0]
	v_pk_mul_f32 v[114:115], v[170:171], s[50:51] op_sel_hi:[1,0]
	v_pk_fma_f32 v[80:81], v[174:175], v[80:81], s[44:45] op_sel_hi:[1,1,0]
	v_exp_f32_e32 v114, v114
	v_exp_f32_e32 v115, v115
	v_pk_fma_f32 v[80:81], v[174:175], v[80:81], s[46:47] op_sel_hi:[1,1,0]
	v_pk_fma_f32 v[80:81], v[174:175], v[80:81], s[48:49] op_sel_hi:[1,1,0]
	v_max_f32_e32 v158, 0, v82
	v_pk_mul_f32 v[80:81], v[174:175], v[80:81]
	v_max_f32_e32 v159, 0, v83
	v_pk_mul_f32 v[80:81], v[114:115], v[80:81]
	s_nop 0
	v_fma_f32 v80, -|v82|, v80, v158
	v_fma_f32 v81, -|v83|, v81, v159
	v_pk_mul_f32 v[82:83], v[90:91], v[154:155] op_sel:[0,1] op_sel_hi:[1,1]
	v_cvt_pk_bf16_f32 v170, v82, v83
	v_pk_mul_f32 v[82:83], v[86:87], v[154:155] op_sel:[0,1] op_sel_hi:[1,1]
	v_cvt_pk_bf16_f32 v171, v82, v83
	v_pk_mul_f32 v[82:83], v[84:85], v[154:155] op_sel:[0,1] op_sel_hi:[1,1]
	v_cvt_pk_bf16_f32 v172, v82, v83
	v_pk_mul_f32 v[82:83], v[80:81], v[154:155] op_sel:[0,1] op_sel_hi:[1,1]
	v_cvt_pk_bf16_f32 v173, v82, v83
	global_store_dwordx4 v[156:157], v[170:173], off offset:256
	global_load_dword v169, v[150:151], off offset:192
	v_or_b32_e32 v82, 48, v154
	v_fma_f32 v114, |v76|, s38, 1.0
	v_fma_f32 v115, |v77|, s38, 1.0
	v_ashrrev_i32_e32 v83, 31, v82
	v_rcp_f32_e32 v156, v114
	v_rcp_f32_e32 v157, v115
	v_lshlrev_b64 v[82:83], 15, v[82:83]
	v_lshl_add_u64 v[82:83], s[22:23], 0, v[82:83]
	v_pk_mul_f32 v[158:159], v[76:77], v[76:77]
	v_lshl_add_u64 v[114:115], v[82:83], 0, v[152:153]
	v_pk_fma_f32 v[152:153], v[156:157], s[40:41], v[146:147] op_sel_hi:[1,0,0]
	v_pk_mul_f32 v[158:159], v[158:159], s[50:51] op_sel_hi:[1,0]
	v_pk_fma_f32 v[152:153], v[156:157], v[152:153], s[44:45] op_sel_hi:[1,1,0]
	v_exp_f32_e32 v158, v158
	v_exp_f32_e32 v159, v159
	v_fma_f32 v170, |v78|, s38, 1.0
	v_fma_f32 v171, |v79|, s38, 1.0
	v_pk_fma_f32 v[152:153], v[156:157], v[152:153], s[46:47] op_sel_hi:[1,1,0]
	v_rcp_f32_e32 v170, v170
	v_rcp_f32_e32 v171, v171
	v_pk_fma_f32 v[152:153], v[156:157], v[152:153], s[48:49] op_sel_hi:[1,1,0]
	v_pk_mul_f32 v[152:153], v[156:157], v[152:153]
	v_pk_mul_f32 v[156:157], v[78:79], v[78:79]
	v_max_f32_e32 v154, 0, v76
	v_max_f32_e32 v155, 0, v77
	v_pk_mul_f32 v[152:153], v[158:159], v[152:153]
	v_fma_f32 v152, -|v76|, v152, v154
	v_fma_f32 v153, -|v77|, v153, v155
	v_pk_fma_f32 v[76:77], v[170:171], s[40:41], v[146:147] op_sel_hi:[1,0,0]
	v_pk_mul_f32 v[154:155], v[156:157], s[50:51] op_sel_hi:[1,0]
	v_pk_fma_f32 v[76:77], v[170:171], v[76:77], s[44:45] op_sel_hi:[1,1,0]
	v_exp_f32_e32 v154, v154
	v_exp_f32_e32 v155, v155
	v_pk_fma_f32 v[76:77], v[170:171], v[76:77], s[46:47] op_sel_hi:[1,1,0]
	v_pk_fma_f32 v[76:77], v[170:171], v[76:77], s[48:49] op_sel_hi:[1,1,0]
	v_max_f32_e32 v82, 0, v78
	v_pk_mul_f32 v[76:77], v[170:171], v[76:77]
	v_max_f32_e32 v83, 0, v79
	v_pk_mul_f32 v[76:77], v[154:155], v[76:77]
	v_fma_f32 v156, |v72|, s38, 1.0
	v_fma_f32 v157, |v73|, s38, 1.0
	v_pk_mul_f32 v[158:159], v[72:73], v[72:73]
	v_rcp_f32_e32 v156, v156
	v_rcp_f32_e32 v157, v157
	v_fma_f32 v78, -|v78|, v76, v82
	v_fma_f32 v79, -|v79|, v77, v83
	v_pk_fma_f32 v[76:77], v[156:157], s[40:41], v[146:147] op_sel_hi:[1,0,0]
	v_pk_mul_f32 v[158:159], v[158:159], s[50:51] op_sel_hi:[1,0]
	v_pk_fma_f32 v[76:77], v[156:157], v[76:77], s[44:45] op_sel_hi:[1,1,0]
	v_exp_f32_e32 v158, v158
	v_exp_f32_e32 v159, v159
	v_fma_f32 v170, |v74|, s38, 1.0
	v_fma_f32 v171, |v75|, s38, 1.0
	v_pk_fma_f32 v[76:77], v[156:157], v[76:77], s[46:47] op_sel_hi:[1,1,0]
	v_rcp_f32_e32 v170, v170
	v_rcp_f32_e32 v171, v171
	v_pk_fma_f32 v[76:77], v[156:157], v[76:77], s[48:49] op_sel_hi:[1,1,0]
	v_pk_mul_f32 v[76:77], v[156:157], v[76:77]
	v_pk_mul_f32 v[156:157], v[74:75], v[74:75]
	v_max_f32_e32 v154, 0, v72
	v_max_f32_e32 v155, 0, v73
	v_pk_mul_f32 v[76:77], v[158:159], v[76:77]
	v_fma_f32 v76, -|v72|, v76, v154
	v_fma_f32 v77, -|v73|, v77, v155
	v_pk_fma_f32 v[72:73], v[170:171], s[40:41], v[146:147] op_sel_hi:[1,0,0]
	v_pk_mul_f32 v[154:155], v[156:157], s[50:51] op_sel_hi:[1,0]
	v_pk_fma_f32 v[72:73], v[170:171], v[72:73], s[44:45] op_sel_hi:[1,1,0]
	v_exp_f32_e32 v154, v154
	v_exp_f32_e32 v155, v155
	v_pk_fma_f32 v[72:73], v[170:171], v[72:73], s[46:47] op_sel_hi:[1,1,0]
	v_pk_fma_f32 v[72:73], v[170:171], v[72:73], s[48:49] op_sel_hi:[1,1,0]
	v_max_f32_e32 v82, 0, v74
	v_pk_mul_f32 v[72:73], v[170:171], v[72:73]
	v_max_f32_e32 v83, 0, v75
	v_pk_mul_f32 v[72:73], v[154:155], v[72:73]
	v_pk_mul_f32 v[156:157], v[68:69], v[68:69]
	v_fma_f32 v72, -|v74|, v72, v82
	v_fma_f32 v73, -|v75|, v73, v83
	s_waitcnt vmcnt(0)
	v_pk_mul_f32 v[74:75], v[152:153], v[168:169] op_sel:[0,1] op_sel_hi:[1,1]
	v_pk_fma_f32 v[82:83], v[152:153], v[152:153], v[98:99]
	v_cvt_pk_bf16_f32 v152, v74, v75
	v_pk_mul_f32 v[74:75], v[78:79], v[168:169] op_sel:[0,1] op_sel_hi:[1,1]
	v_cvt_pk_bf16_f32 v153, v74, v75
	v_pk_mul_f32 v[74:75], v[76:77], v[168:169] op_sel:[0,1] op_sel_hi:[1,1]
	v_cvt_pk_bf16_f32 v154, v74, v75
	v_pk_mul_f32 v[74:75], v[72:73], v[168:169] op_sel:[0,1] op_sel_hi:[1,1]
	v_cvt_pk_bf16_f32 v155, v74, v75
	v_fma_f32 v98, |v68|, s38, 1.0
	v_fma_f32 v99, |v69|, s38, 1.0
	global_store_dwordx4 v[114:115], v[152:155], off
	v_rcp_f32_e32 v98, v98
	v_rcp_f32_e32 v99, v99
	v_pk_mul_f32 v[156:157], v[156:157], s[50:51] op_sel_hi:[1,0]
	v_pk_fma_f32 v[154:155], v[98:99], s[40:41], v[146:147] op_sel_hi:[1,0,0]
	v_exp_f32_e32 v156, v156
	v_pk_fma_f32 v[154:155], v[98:99], v[154:155], s[44:45] op_sel_hi:[1,1,0]
	v_exp_f32_e32 v157, v157
	v_fma_f32 v158, |v70|, s38, 1.0
	v_fma_f32 v159, |v71|, s38, 1.0
	v_pk_fma_f32 v[154:155], v[98:99], v[154:155], s[46:47] op_sel_hi:[1,1,0]
	v_rcp_f32_e32 v158, v158
	v_rcp_f32_e32 v159, v159
	v_pk_fma_f32 v[154:155], v[98:99], v[154:155], s[48:49] op_sel_hi:[1,1,0]
	v_pk_mul_f32 v[98:99], v[98:99], v[154:155]
	v_pk_mul_f32 v[154:155], v[70:71], v[70:71]
	v_max_f32_e32 v74, 0, v68
	v_max_f32_e32 v75, 0, v69
	v_pk_mul_f32 v[98:99], v[156:157], v[98:99]
	v_fma_f32 v74, -|v68|, v98, v74
	v_fma_f32 v75, -|v69|, v99, v75
	v_pk_fma_f32 v[68:69], v[158:159], s[40:41], v[146:147] op_sel_hi:[1,0,0]
	v_pk_mul_f32 v[98:99], v[154:155], s[50:51] op_sel_hi:[1,0]
	v_pk_fma_f32 v[68:69], v[158:159], v[68:69], s[44:45] op_sel_hi:[1,1,0]
	v_exp_f32_e32 v98, v98
	v_exp_f32_e32 v99, v99
	v_pk_fma_f32 v[68:69], v[158:159], v[68:69], s[46:47] op_sel_hi:[1,1,0]
	v_pk_fma_f32 v[68:69], v[158:159], v[68:69], s[48:49] op_sel_hi:[1,1,0]
	v_max_f32_e32 v152, 0, v70
	v_pk_mul_f32 v[68:69], v[158:159], v[68:69]
	v_max_f32_e32 v153, 0, v71
	v_pk_mul_f32 v[68:69], v[98:99], v[68:69]
	v_fma_f32 v154, |v64|, s38, 1.0
	v_fma_f32 v155, |v65|, s38, 1.0
	v_pk_mul_f32 v[156:157], v[64:65], v[64:65]
	v_rcp_f32_e32 v154, v154
	v_rcp_f32_e32 v155, v155
	v_fma_f32 v70, -|v70|, v68, v152
	v_fma_f32 v71, -|v71|, v69, v153
	v_pk_fma_f32 v[68:69], v[154:155], s[40:41], v[146:147] op_sel_hi:[1,0,0]
	v_pk_mul_f32 v[156:157], v[156:157], s[50:51] op_sel_hi:[1,0]
	v_pk_fma_f32 v[68:69], v[154:155], v[68:69], s[44:45] op_sel_hi:[1,1,0]
	v_exp_f32_e32 v156, v156
	v_exp_f32_e32 v157, v157
	v_fma_f32 v158, |v66|, s38, 1.0
	v_fma_f32 v159, |v67|, s38, 1.0
	v_pk_fma_f32 v[68:69], v[154:155], v[68:69], s[46:47] op_sel_hi:[1,1,0]
	v_rcp_f32_e32 v158, v158
	v_rcp_f32_e32 v159, v159
	v_pk_fma_f32 v[68:69], v[154:155], v[68:69], s[48:49] op_sel_hi:[1,1,0]
	v_pk_mul_f32 v[68:69], v[154:155], v[68:69]
	v_pk_mul_f32 v[154:155], v[66:67], v[66:67]
	v_max_f32_e32 v98, 0, v64
	v_max_f32_e32 v99, 0, v65
	v_pk_mul_f32 v[68:69], v[156:157], v[68:69]
	v_fma_f32 v68, -|v64|, v68, v98
	v_fma_f32 v69, -|v65|, v69, v99
	v_pk_fma_f32 v[64:65], v[158:159], s[40:41], v[146:147] op_sel_hi:[1,0,0]
	v_pk_mul_f32 v[98:99], v[154:155], s[50:51] op_sel_hi:[1,0]
	v_pk_fma_f32 v[64:65], v[158:159], v[64:65], s[44:45] op_sel_hi:[1,1,0]
	v_exp_f32_e32 v98, v98
	v_exp_f32_e32 v99, v99
	v_pk_fma_f32 v[64:65], v[158:159], v[64:65], s[46:47] op_sel_hi:[1,1,0]
	v_pk_fma_f32 v[64:65], v[158:159], v[64:65], s[48:49] op_sel_hi:[1,1,0]
	v_max_f32_e32 v152, 0, v66
	v_pk_mul_f32 v[64:65], v[158:159], v[64:65]
	v_max_f32_e32 v153, 0, v67
	v_pk_mul_f32 v[64:65], v[98:99], v[64:65]
	v_pk_mul_f32 v[156:157], v[60:61], v[60:61]
	v_fma_f32 v64, -|v66|, v64, v152
	v_fma_f32 v65, -|v67|, v65, v153
	v_pk_mul_f32 v[66:67], v[74:75], v[168:169] op_sel:[0,1] op_sel_hi:[1,1]
	v_cvt_pk_bf16_f32 v152, v66, v67
	v_pk_mul_f32 v[66:67], v[70:71], v[168:169] op_sel:[0,1] op_sel_hi:[1,1]
	v_cvt_pk_bf16_f32 v153, v66, v67
	v_pk_mul_f32 v[66:67], v[68:69], v[168:169] op_sel:[0,1] op_sel_hi:[1,1]
	v_cvt_pk_bf16_f32 v154, v66, v67
	v_pk_mul_f32 v[66:67], v[64:65], v[168:169] op_sel:[0,1] op_sel_hi:[1,1]
	v_cvt_pk_bf16_f32 v155, v66, v67
	global_store_dwordx4 v[114:115], v[152:155], off offset:256
	global_load_dword v169, v[150:151], off offset:512
	v_fma_f32 v98, |v60|, s38, 1.0
	v_fma_f32 v99, |v61|, s38, 1.0
	v_rcp_f32_e32 v114, v98
	v_rcp_f32_e32 v115, v99
	v_pk_mul_f32 v[156:157], v[156:157], s[50:51] op_sel_hi:[1,0]
	v_fma_f32 v158, |v62|, s38, 1.0
	v_fma_f32 v159, |v63|, s38, 1.0
	v_pk_fma_f32 v[154:155], v[114:115], s[40:41], v[146:147] op_sel_hi:[1,0,0]
	v_exp_f32_e32 v156, v156
	v_pk_fma_f32 v[154:155], v[114:115], v[154:155], s[44:45] op_sel_hi:[1,1,0]
	v_exp_f32_e32 v157, v157
	v_pk_fma_f32 v[154:155], v[114:115], v[154:155], s[46:47] op_sel_hi:[1,1,0]
	v_rcp_f32_e32 v158, v158
	v_rcp_f32_e32 v159, v159
	v_pk_fma_f32 v[154:155], v[114:115], v[154:155], s[48:49] op_sel_hi:[1,1,0]
	v_pk_mul_f32 v[114:115], v[114:115], v[154:155]
	v_pk_mul_f32 v[154:155], v[62:63], v[62:63]
	v_max_f32_e32 v66, 0, v60
	v_max_f32_e32 v67, 0, v61
	v_pk_mul_f32 v[114:115], v[156:157], v[114:115]
	v_fma_f32 v114, -|v60|, v114, v66
	v_fma_f32 v115, -|v61|, v115, v67
	v_pk_fma_f32 v[60:61], v[158:159], s[40:41], v[146:147] op_sel_hi:[1,0,0]
	v_pk_mul_f32 v[66:67], v[154:155], s[50:51] op_sel_hi:[1,0]
	v_pk_fma_f32 v[60:61], v[158:159], v[60:61], s[44:45] op_sel_hi:[1,1,0]
	v_exp_f32_e32 v66, v66
	v_exp_f32_e32 v67, v67
	v_pk_fma_f32 v[60:61], v[158:159], v[60:61], s[46:47] op_sel_hi:[1,1,0]
	v_pk_fma_f32 v[60:61], v[158:159], v[60:61], s[48:49] op_sel_hi:[1,1,0]
	v_max_f32_e32 v152, 0, v62
	v_pk_mul_f32 v[60:61], v[158:159], v[60:61]
	v_max_f32_e32 v153, 0, v63
	v_pk_mul_f32 v[60:61], v[66:67], v[60:61]
	v_fma_f32 v154, |v56|, s38, 1.0
	v_fma_f32 v155, |v57|, s38, 1.0
	v_pk_mul_f32 v[156:157], v[56:57], v[56:57]
	v_rcp_f32_e32 v154, v154
	v_rcp_f32_e32 v155, v155
	v_fma_f32 v62, -|v62|, v60, v152
	v_fma_f32 v63, -|v63|, v61, v153
	v_pk_fma_f32 v[60:61], v[154:155], s[40:41], v[146:147] op_sel_hi:[1,0,0]
	v_pk_mul_f32 v[156:157], v[156:157], s[50:51] op_sel_hi:[1,0]
	v_pk_fma_f32 v[60:61], v[154:155], v[60:61], s[44:45] op_sel_hi:[1,1,0]
	v_exp_f32_e32 v156, v156
	v_exp_f32_e32 v157, v157
	v_fma_f32 v158, |v58|, s38, 1.0
	v_fma_f32 v159, |v59|, s38, 1.0
	v_pk_fma_f32 v[60:61], v[154:155], v[60:61], s[46:47] op_sel_hi:[1,1,0]
	v_rcp_f32_e32 v158, v158
	v_rcp_f32_e32 v159, v159
	v_pk_fma_f32 v[60:61], v[154:155], v[60:61], s[48:49] op_sel_hi:[1,1,0]
	v_pk_mul_f32 v[60:61], v[154:155], v[60:61]
	v_pk_mul_f32 v[154:155], v[58:59], v[58:59]
	v_max_f32_e32 v66, 0, v56
	v_max_f32_e32 v67, 0, v57
	v_pk_mul_f32 v[60:61], v[156:157], v[60:61]
	v_fma_f32 v60, -|v56|, v60, v66
	v_fma_f32 v61, -|v57|, v61, v67
	v_pk_fma_f32 v[56:57], v[158:159], s[40:41], v[146:147] op_sel_hi:[1,0,0]
	v_pk_mul_f32 v[66:67], v[154:155], s[50:51] op_sel_hi:[1,0]
	v_pk_fma_f32 v[56:57], v[158:159], v[56:57], s[44:45] op_sel_hi:[1,1,0]
	v_exp_f32_e32 v66, v66
	v_exp_f32_e32 v67, v67
	v_pk_fma_f32 v[56:57], v[158:159], v[56:57], s[46:47] op_sel_hi:[1,1,0]
	v_pk_fma_f32 v[56:57], v[158:159], v[56:57], s[48:49] op_sel_hi:[1,1,0]
	v_max_f32_e32 v152, 0, v58
	v_pk_mul_f32 v[56:57], v[158:159], v[56:57]
	v_max_f32_e32 v153, 0, v59
	v_pk_mul_f32 v[56:57], v[66:67], v[56:57]
	v_pk_fma_f32 v[66:67], v[114:115], v[114:115], v[82:83]
	v_fma_f32 v56, -|v58|, v56, v152
	v_fma_f32 v57, -|v59|, v57, v153
	s_waitcnt vmcnt(0)
	v_pk_mul_f32 v[58:59], v[114:115], v[168:169] op_sel:[0,1] op_sel_hi:[1,1]
	v_cvt_pk_bf16_f32 v152, v58, v59
	v_pk_mul_f32 v[58:59], v[62:63], v[168:169] op_sel:[0,1] op_sel_hi:[1,1]
	v_cvt_pk_bf16_f32 v153, v58, v59
	v_fma_f32 v114, |v52|, s38, 1.0
	v_fma_f32 v115, |v53|, s38, 1.0
	v_pk_mul_f32 v[58:59], v[60:61], v[168:169] op_sel:[0,1] op_sel_hi:[1,1]
	v_cvt_pk_bf16_f32 v154, v58, v59
	v_rcp_f32_e32 v114, v114
	v_rcp_f32_e32 v115, v115
	v_pk_mul_f32 v[58:59], v[56:57], v[168:169] op_sel:[0,1] op_sel_hi:[1,1]
	v_cvt_pk_bf16_f32 v155, v58, v59
	v_add_co_u32_e32 v58, vcc, s86, v148
	v_lshl_add_u64 v[98:99], v[148:149], 0, s[54:55]
	s_nop 0
	v_addc_co_u32_e32 v59, vcc, 0, v149, vcc
	global_store_dwordx4 v[58:59], v[152:155], off
	v_pk_fma_f32 v[58:59], v[114:115], s[40:41], v[146:147] op_sel_hi:[1,0,0]
	s_nop 0
	v_pk_mul_f32 v[154:155], v[52:53], v[52:53]
	v_pk_mul_f32 v[154:155], v[154:155], s[50:51] op_sel_hi:[1,0]
	v_pk_fma_f32 v[58:59], v[114:115], v[58:59], s[44:45] op_sel_hi:[1,1,0]
	v_exp_f32_e32 v154, v154
	v_exp_f32_e32 v155, v155
	v_fma_f32 v156, |v54|, s38, 1.0
	v_fma_f32 v157, |v55|, s38, 1.0
	v_pk_fma_f32 v[58:59], v[114:115], v[58:59], s[46:47] op_sel_hi:[1,1,0]
	v_rcp_f32_e32 v156, v156
	v_rcp_f32_e32 v157, v157
	v_pk_fma_f32 v[58:59], v[114:115], v[58:59], s[48:49] op_sel_hi:[1,1,0]
	v_pk_mul_f32 v[58:59], v[114:115], v[58:59]
	v_pk_mul_f32 v[114:115], v[54:55], v[54:55]
	v_max_f32_e32 v82, 0, v52
	v_max_f32_e32 v83, 0, v53
	v_pk_mul_f32 v[58:59], v[154:155], v[58:59]
	v_fma_f32 v58, -|v52|, v58, v82
	v_fma_f32 v59, -|v53|, v59, v83
	v_pk_fma_f32 v[52:53], v[156:157], s[40:41], v[146:147] op_sel_hi:[1,0,0]
	v_pk_mul_f32 v[82:83], v[114:115], s[50:51] op_sel_hi:[1,0]
	v_pk_fma_f32 v[52:53], v[156:157], v[52:53], s[44:45] op_sel_hi:[1,1,0]
	v_exp_f32_e32 v82, v82
	v_exp_f32_e32 v83, v83
	v_pk_fma_f32 v[52:53], v[156:157], v[52:53], s[46:47] op_sel_hi:[1,1,0]
	v_pk_fma_f32 v[52:53], v[156:157], v[52:53], s[48:49] op_sel_hi:[1,1,0]
	v_max_f32_e32 v152, 0, v54
	v_pk_mul_f32 v[52:53], v[156:157], v[52:53]
	v_max_f32_e32 v153, 0, v55
	v_pk_mul_f32 v[52:53], v[82:83], v[52:53]
	v_fma_f32 v114, |v48|, s38, 1.0
	v_fma_f32 v115, |v49|, s38, 1.0
	v_pk_mul_f32 v[154:155], v[48:49], v[48:49]
	v_rcp_f32_e32 v114, v114
	v_rcp_f32_e32 v115, v115
	v_fma_f32 v54, -|v54|, v52, v152
	v_fma_f32 v55, -|v55|, v53, v153
	v_pk_fma_f32 v[52:53], v[114:115], s[40:41], v[146:147] op_sel_hi:[1,0,0]
	v_pk_mul_f32 v[154:155], v[154:155], s[50:51] op_sel_hi:[1,0]
	v_pk_fma_f32 v[52:53], v[114:115], v[52:53], s[44:45] op_sel_hi:[1,1,0]
	v_exp_f32_e32 v154, v154
	v_exp_f32_e32 v155, v155
	v_fma_f32 v156, |v50|, s38, 1.0
	v_fma_f32 v157, |v51|, s38, 1.0
	v_pk_fma_f32 v[52:53], v[114:115], v[52:53], s[46:47] op_sel_hi:[1,1,0]
	v_rcp_f32_e32 v156, v156
	v_rcp_f32_e32 v157, v157
	v_pk_fma_f32 v[52:53], v[114:115], v[52:53], s[48:49] op_sel_hi:[1,1,0]
	v_pk_mul_f32 v[52:53], v[114:115], v[52:53]
	v_pk_mul_f32 v[114:115], v[50:51], v[50:51]
	v_max_f32_e32 v82, 0, v48
	v_max_f32_e32 v83, 0, v49
	v_pk_mul_f32 v[52:53], v[154:155], v[52:53]
	v_fma_f32 v52, -|v48|, v52, v82
	v_fma_f32 v53, -|v49|, v53, v83
	v_pk_fma_f32 v[48:49], v[156:157], s[40:41], v[146:147] op_sel_hi:[1,0,0]
	v_pk_mul_f32 v[82:83], v[114:115], s[50:51] op_sel_hi:[1,0]
	v_pk_fma_f32 v[48:49], v[156:157], v[48:49], s[44:45] op_sel_hi:[1,1,0]
	v_exp_f32_e32 v82, v82
	v_exp_f32_e32 v83, v83
	v_pk_fma_f32 v[48:49], v[156:157], v[48:49], s[46:47] op_sel_hi:[1,1,0]
	v_pk_fma_f32 v[48:49], v[156:157], v[48:49], s[48:49] op_sel_hi:[1,1,0]
	v_max_f32_e32 v152, 0, v50
	v_pk_mul_f32 v[48:49], v[156:157], v[48:49]
	v_max_f32_e32 v153, 0, v51
	v_pk_mul_f32 v[48:49], v[82:83], v[48:49]
	v_and_b32_e32 v115, 0x7fffffff, v47
	v_fma_f32 v48, -|v50|, v48, v152
	v_fma_f32 v49, -|v51|, v49, v153
	v_pk_mul_f32 v[50:51], v[58:59], v[168:169] op_sel:[0,1] op_sel_hi:[1,1]
	v_cvt_pk_bf16_f32 v152, v50, v51
	v_pk_mul_f32 v[50:51], v[54:55], v[168:169] op_sel:[0,1] op_sel_hi:[1,1]
	v_cvt_pk_bf16_f32 v153, v50, v51
	v_pk_mul_f32 v[50:51], v[52:53], v[168:169] op_sel:[0,1] op_sel_hi:[1,1]
	v_cvt_pk_bf16_f32 v154, v50, v51
	v_pk_mul_f32 v[50:51], v[48:49], v[168:169] op_sel:[0,1] op_sel_hi:[1,1]
	v_cvt_pk_bf16_f32 v155, v50, v51
	global_store_dwordx4 v[98:99], v[152:155], off offset:256
	global_load_dword v158, v[150:151], off offset:576
	v_fma_f32 v82, |v44|, s38, 1.0
	v_fma_f32 v83, |v45|, s38, 1.0
	v_pk_mul_f32 v[154:155], v[44:45], v[44:45]
	v_rcp_f32_e32 v98, v82
	v_rcp_f32_e32 v99, v83
	v_and_b32_e32 v114, 0x7fffffff, v46
	v_pk_mul_f32 v[154:155], v[154:155], s[50:51] op_sel_hi:[1,0]
	v_pk_fma_f32 v[156:157], v[114:115], s[38:39], 1.0 op_sel_hi:[1,0,0]
	v_pk_fma_f32 v[152:153], v[98:99], s[40:41], v[146:147] op_sel_hi:[1,0,0]
	v_exp_f32_e32 v154, v154
	v_pk_fma_f32 v[152:153], v[98:99], v[152:153], s[44:45] op_sel_hi:[1,1,0]
	v_exp_f32_e32 v155, v155
	v_pk_fma_f32 v[152:153], v[98:99], v[152:153], s[46:47] op_sel_hi:[1,1,0]
	v_rcp_f32_e32 v156, v156
	v_rcp_f32_e32 v157, v157
	v_pk_fma_f32 v[152:153], v[98:99], v[152:153], s[48:49] op_sel_hi:[1,1,0]
	v_pk_mul_f32 v[98:99], v[98:99], v[152:153]
	v_pk_mul_f32 v[152:153], v[46:47], v[46:47]
	v_max_f32_e32 v50, 0, v44
	v_max_f32_e32 v51, 0, v45
	v_pk_mul_f32 v[98:99], v[154:155], v[98:99]
	v_fma_f32 v98, -|v44|, v98, v50
	v_fma_f32 v99, -|v45|, v99, v51
	v_pk_fma_f32 v[44:45], v[156:157], s[40:41], v[146:147] op_sel_hi:[1,0,0]
	v_pk_mul_f32 v[50:51], v[152:153], s[50:51] op_sel_hi:[1,0]
	v_pk_fma_f32 v[44:45], v[156:157], v[44:45], s[44:45] op_sel_hi:[1,1,0]
	v_exp_f32_e32 v50, v50
	v_exp_f32_e32 v51, v51
	v_pk_fma_f32 v[44:45], v[156:157], v[44:45], s[46:47] op_sel_hi:[1,1,0]
	v_pk_fma_f32 v[44:45], v[156:157], v[44:45], s[48:49] op_sel_hi:[1,1,0]
	v_max_f32_e32 v46, 0, v46
	v_pk_mul_f32 v[44:45], v[156:157], v[44:45]
	v_max_f32_e32 v47, 0, v47
	v_pk_mul_f32 v[44:45], v[50:51], v[44:45]
	v_fma_f32 v152, |v40|, s38, 1.0
	v_fma_f32 v153, |v41|, s38, 1.0
	v_pk_mul_f32 v[154:155], v[40:41], v[40:41]
	v_rcp_f32_e32 v152, v152
	v_rcp_f32_e32 v153, v153
	v_pk_fma_f32 v[46:47], v[114:115], v[44:45], v[46:47] neg_lo:[1,0,0] neg_hi:[1,0,0]
	v_pk_fma_f32 v[44:45], v[152:153], s[40:41], v[146:147] op_sel_hi:[1,0,0]
	v_pk_mul_f32 v[154:155], v[154:155], s[50:51] op_sel_hi:[1,0]
	v_pk_fma_f32 v[44:45], v[152:153], v[44:45], s[44:45] op_sel_hi:[1,1,0]
	v_exp_f32_e32 v154, v154
	v_exp_f32_e32 v155, v155
	v_fma_f32 v156, |v42|, s38, 1.0
	v_fma_f32 v157, |v43|, s38, 1.0
	v_pk_fma_f32 v[44:45], v[152:153], v[44:45], s[46:47] op_sel_hi:[1,1,0]
	v_rcp_f32_e32 v156, v156
	v_rcp_f32_e32 v157, v157
	v_pk_fma_f32 v[44:45], v[152:153], v[44:45], s[48:49] op_sel_hi:[1,1,0]
	v_pk_mul_f32 v[44:45], v[152:153], v[44:45]
	v_pk_mul_f32 v[152:153], v[42:43], v[42:43]
	v_max_f32_e32 v50, 0, v40
	v_max_f32_e32 v51, 0, v41
	v_pk_mul_f32 v[44:45], v[154:155], v[44:45]
	v_fma_f32 v44, -|v40|, v44, v50
	v_fma_f32 v45, -|v41|, v45, v51
	v_pk_fma_f32 v[40:41], v[156:157], s[40:41], v[146:147] op_sel_hi:[1,0,0]
	v_pk_mul_f32 v[50:51], v[152:153], s[50:51] op_sel_hi:[1,0]
	v_pk_fma_f32 v[40:41], v[156:157], v[40:41], s[44:45] op_sel_hi:[1,1,0]
	v_exp_f32_e32 v50, v50
	v_exp_f32_e32 v51, v51
	v_pk_fma_f32 v[40:41], v[156:157], v[40:41], s[46:47] op_sel_hi:[1,1,0]
	v_pk_fma_f32 v[40:41], v[156:157], v[40:41], s[48:49] op_sel_hi:[1,1,0]
	v_max_f32_e32 v114, 0, v42
	v_pk_mul_f32 v[40:41], v[156:157], v[40:41]
	v_max_f32_e32 v115, 0, v43
	v_pk_mul_f32 v[40:41], v[50:51], v[40:41]
	v_pk_fma_f32 v[50:51], v[98:99], v[98:99], v[66:67]
	v_fma_f32 v40, -|v42|, v40, v114
	v_fma_f32 v41, -|v43|, v41, v115
	s_waitcnt vmcnt(0)
	v_pk_mul_f32 v[42:43], v[98:99], v[158:159] op_sel_hi:[1,0]
	v_cvt_pk_bf16_f32 v152, v42, v43
	v_pk_mul_f32 v[42:43], v[46:47], v[158:159] op_sel_hi:[1,0]
	v_cvt_pk_bf16_f32 v153, v42, v43
	v_fma_f32 v98, |v36|, s38, 1.0
	v_fma_f32 v99, |v37|, s38, 1.0
	v_pk_mul_f32 v[42:43], v[44:45], v[158:159] op_sel_hi:[1,0]
	v_cvt_pk_bf16_f32 v154, v42, v43
	v_rcp_f32_e32 v98, v98
	v_rcp_f32_e32 v99, v99
	v_pk_mul_f32 v[42:43], v[40:41], v[158:159] op_sel_hi:[1,0]
	v_cvt_pk_bf16_f32 v155, v42, v43
	v_add_co_u32_e32 v42, vcc, s87, v148
	s_nop 0
	v_addc_co_u32_e32 v43, vcc, 0, v149, vcc
	global_store_dwordx4 v[42:43], v[152:155], off
	s_nop 1
	v_pk_fma_f32 v[42:43], v[98:99], s[40:41], v[146:147] op_sel_hi:[1,0,0]
	v_pk_mul_f32 v[152:153], v[36:37], v[36:37]
	v_pk_fma_f32 v[42:43], v[98:99], v[42:43], s[44:45] op_sel_hi:[1,1,0]
	v_pk_mul_f32 v[152:153], v[152:153], s[50:51] op_sel_hi:[1,0]
	v_fma_f32 v154, |v38|, s38, 1.0
	v_fma_f32 v155, |v39|, s38, 1.0
	v_exp_f32_e32 v152, v152
	v_exp_f32_e32 v153, v153
	v_pk_fma_f32 v[42:43], v[98:99], v[42:43], s[46:47] op_sel_hi:[1,1,0]
	v_rcp_f32_e32 v154, v154
	v_rcp_f32_e32 v155, v155
	v_pk_fma_f32 v[42:43], v[98:99], v[42:43], s[48:49] op_sel_hi:[1,1,0]
	v_pk_mul_f32 v[42:43], v[98:99], v[42:43]
	v_pk_mul_f32 v[98:99], v[38:39], v[38:39]
	v_max_f32_e32 v66, 0, v36
	v_max_f32_e32 v67, 0, v37
	v_pk_mul_f32 v[42:43], v[152:153], v[42:43]
	v_fma_f32 v42, -|v36|, v42, v66
	v_fma_f32 v43, -|v37|, v43, v67
	v_pk_fma_f32 v[36:37], v[154:155], s[40:41], v[146:147] op_sel_hi:[1,0,0]
	v_pk_mul_f32 v[66:67], v[98:99], s[50:51] op_sel_hi:[1,0]
	v_pk_fma_f32 v[36:37], v[154:155], v[36:37], s[44:45] op_sel_hi:[1,1,0]
	v_exp_f32_e32 v66, v66
	v_exp_f32_e32 v67, v67
	v_pk_fma_f32 v[36:37], v[154:155], v[36:37], s[46:47] op_sel_hi:[1,1,0]
	v_pk_fma_f32 v[36:37], v[154:155], v[36:37], s[48:49] op_sel_hi:[1,1,0]
	v_max_f32_e32 v114, 0, v38
	v_pk_mul_f32 v[36:37], v[154:155], v[36:37]
	v_max_f32_e32 v115, 0, v39
	v_pk_mul_f32 v[36:37], v[66:67], v[36:37]
	v_fma_f32 v98, |v32|, s38, 1.0
	v_fma_f32 v99, |v33|, s38, 1.0
	v_pk_mul_f32 v[152:153], v[32:33], v[32:33]
	v_rcp_f32_e32 v98, v98
	v_rcp_f32_e32 v99, v99
	v_fma_f32 v38, -|v38|, v36, v114
	v_fma_f32 v39, -|v39|, v37, v115
	v_pk_fma_f32 v[36:37], v[98:99], s[40:41], v[146:147] op_sel_hi:[1,0,0]
	v_pk_mul_f32 v[152:153], v[152:153], s[50:51] op_sel_hi:[1,0]
	v_pk_fma_f32 v[36:37], v[98:99], v[36:37], s[44:45] op_sel_hi:[1,1,0]
	v_exp_f32_e32 v152, v152
	v_exp_f32_e32 v153, v153
	v_fma_f32 v154, |v34|, s38, 1.0
	v_fma_f32 v155, |v35|, s38, 1.0
	v_pk_fma_f32 v[36:37], v[98:99], v[36:37], s[46:47] op_sel_hi:[1,1,0]
	v_rcp_f32_e32 v154, v154
	v_rcp_f32_e32 v155, v155
	v_pk_fma_f32 v[36:37], v[98:99], v[36:37], s[48:49] op_sel_hi:[1,1,0]
	v_pk_mul_f32 v[36:37], v[98:99], v[36:37]
	v_pk_mul_f32 v[98:99], v[34:35], v[34:35]
	v_max_f32_e32 v66, 0, v32
	v_max_f32_e32 v67, 0, v33
	v_pk_mul_f32 v[36:37], v[152:153], v[36:37]
	v_fma_f32 v36, -|v32|, v36, v66
	v_fma_f32 v37, -|v33|, v37, v67
	v_pk_fma_f32 v[32:33], v[154:155], s[40:41], v[146:147] op_sel_hi:[1,0,0]
	v_pk_mul_f32 v[66:67], v[98:99], s[50:51] op_sel_hi:[1,0]
	v_pk_fma_f32 v[32:33], v[154:155], v[32:33], s[44:45] op_sel_hi:[1,1,0]
	v_exp_f32_e32 v66, v66
	v_exp_f32_e32 v67, v67
	v_pk_fma_f32 v[32:33], v[154:155], v[32:33], s[46:47] op_sel_hi:[1,1,0]
	v_pk_fma_f32 v[32:33], v[154:155], v[32:33], s[48:49] op_sel_hi:[1,1,0]
	v_max_f32_e32 v114, 0, v34
	v_pk_mul_f32 v[32:33], v[154:155], v[32:33]
	v_max_f32_e32 v115, 0, v35
	v_pk_mul_f32 v[32:33], v[66:67], v[32:33]
	v_lshl_add_u64 v[82:83], v[148:149], 0, s[56:57]
	v_fma_f32 v32, -|v34|, v32, v114
	v_fma_f32 v33, -|v35|, v33, v115
	v_pk_mul_f32 v[34:35], v[42:43], v[158:159] op_sel_hi:[1,0]
	v_cvt_pk_bf16_f32 v152, v34, v35
	v_pk_mul_f32 v[34:35], v[38:39], v[158:159] op_sel_hi:[1,0]
	v_cvt_pk_bf16_f32 v153, v34, v35
	v_pk_mul_f32 v[34:35], v[36:37], v[158:159] op_sel_hi:[1,0]
	v_cvt_pk_bf16_f32 v154, v34, v35
	v_pk_mul_f32 v[34:35], v[32:33], v[158:159] op_sel_hi:[1,0]
	v_cvt_pk_bf16_f32 v155, v34, v35
	global_store_dwordx4 v[82:83], v[152:155], off offset:256
	global_load_dword v156, v[150:151], off offset:640
	v_fma_f32 v66, |v28|, s38, 1.0
	v_fma_f32 v67, |v29|, s38, 1.0
	v_pk_mul_f32 v[152:153], v[28:29], v[28:29]
	v_rcp_f32_e32 v82, v66
	v_rcp_f32_e32 v83, v67
	v_pk_mul_f32 v[152:153], v[152:153], s[50:51] op_sel_hi:[1,0]
	v_pk_fma_f32 v[114:115], v[82:83], s[40:41], v[146:147] op_sel_hi:[1,0,0]
	v_exp_f32_e32 v152, v152
	v_pk_fma_f32 v[114:115], v[82:83], v[114:115], s[44:45] op_sel_hi:[1,1,0]
	v_exp_f32_e32 v153, v153
	v_fma_f32 v154, |v30|, s38, 1.0
	v_fma_f32 v155, |v31|, s38, 1.0
	v_pk_fma_f32 v[114:115], v[82:83], v[114:115], s[46:47] op_sel_hi:[1,1,0]
	v_rcp_f32_e32 v154, v154
	v_rcp_f32_e32 v155, v155
	v_pk_fma_f32 v[114:115], v[82:83], v[114:115], s[48:49] op_sel_hi:[1,1,0]
	v_pk_mul_f32 v[82:83], v[82:83], v[114:115]
	v_pk_mul_f32 v[114:115], v[30:31], v[30:31]
	v_max_f32_e32 v34, 0, v28
	v_max_f32_e32 v35, 0, v29
	v_pk_mul_f32 v[82:83], v[152:153], v[82:83]
	v_fma_f32 v82, -|v28|, v82, v34
	v_fma_f32 v83, -|v29|, v83, v35
	v_pk_fma_f32 v[28:29], v[154:155], s[40:41], v[146:147] op_sel_hi:[1,0,0]
	v_pk_mul_f32 v[34:35], v[114:115], s[50:51] op_sel_hi:[1,0]
	v_pk_fma_f32 v[28:29], v[154:155], v[28:29], s[44:45] op_sel_hi:[1,1,0]
	v_exp_f32_e32 v34, v34
	v_exp_f32_e32 v35, v35
	v_pk_fma_f32 v[28:29], v[154:155], v[28:29], s[46:47] op_sel_hi:[1,1,0]
	v_pk_fma_f32 v[28:29], v[154:155], v[28:29], s[48:49] op_sel_hi:[1,1,0]
	v_max_f32_e32 v98, 0, v30
	v_pk_mul_f32 v[28:29], v[154:155], v[28:29]
	v_max_f32_e32 v99, 0, v31
	v_pk_mul_f32 v[28:29], v[34:35], v[28:29]
	v_fma_f32 v114, |v24|, s38, 1.0
	v_fma_f32 v115, |v25|, s38, 1.0
	v_pk_mul_f32 v[152:153], v[24:25], v[24:25]
	v_rcp_f32_e32 v114, v114
	v_rcp_f32_e32 v115, v115
	v_fma_f32 v30, -|v30|, v28, v98
	v_fma_f32 v31, -|v31|, v29, v99
	v_pk_fma_f32 v[28:29], v[114:115], s[40:41], v[146:147] op_sel_hi:[1,0,0]
	v_pk_mul_f32 v[152:153], v[152:153], s[50:51] op_sel_hi:[1,0]
	v_pk_fma_f32 v[28:29], v[114:115], v[28:29], s[44:45] op_sel_hi:[1,1,0]
	v_exp_f32_e32 v152, v152
	v_exp_f32_e32 v153, v153
	v_fma_f32 v154, |v26|, s38, 1.0
	v_fma_f32 v155, |v27|, s38, 1.0
	v_pk_fma_f32 v[28:29], v[114:115], v[28:29], s[46:47] op_sel_hi:[1,1,0]
	v_rcp_f32_e32 v154, v154
	v_rcp_f32_e32 v155, v155
	v_pk_fma_f32 v[28:29], v[114:115], v[28:29], s[48:49] op_sel_hi:[1,1,0]
	v_pk_mul_f32 v[28:29], v[114:115], v[28:29]
	v_pk_mul_f32 v[114:115], v[26:27], v[26:27]
	v_max_f32_e32 v34, 0, v24
	v_max_f32_e32 v35, 0, v25
	v_pk_mul_f32 v[28:29], v[152:153], v[28:29]
	v_fma_f32 v28, -|v24|, v28, v34
	v_fma_f32 v29, -|v25|, v29, v35
	v_pk_fma_f32 v[24:25], v[154:155], s[40:41], v[146:147] op_sel_hi:[1,0,0]
	v_pk_mul_f32 v[34:35], v[114:115], s[50:51] op_sel_hi:[1,0]
	v_pk_fma_f32 v[24:25], v[154:155], v[24:25], s[44:45] op_sel_hi:[1,1,0]
	v_exp_f32_e32 v34, v34
	v_exp_f32_e32 v35, v35
	v_pk_fma_f32 v[24:25], v[154:155], v[24:25], s[46:47] op_sel_hi:[1,1,0]
	v_pk_fma_f32 v[24:25], v[154:155], v[24:25], s[48:49] op_sel_hi:[1,1,0]
	v_max_f32_e32 v98, 0, v26
	v_pk_mul_f32 v[24:25], v[154:155], v[24:25]
	v_max_f32_e32 v99, 0, v27
	v_pk_mul_f32 v[24:25], v[34:35], v[24:25]
	v_pk_fma_f32 v[34:35], v[82:83], v[82:83], v[50:51]
	v_fma_f32 v24, -|v26|, v24, v98
	v_fma_f32 v25, -|v27|, v25, v99
	s_waitcnt vmcnt(0)
	v_pk_mul_f32 v[26:27], v[82:83], v[156:157] op_sel_hi:[1,0]
	v_cvt_pk_bf16_f32 v152, v26, v27
	v_fma_f32 v82, |v20|, s38, 1.0
	v_fma_f32 v83, |v21|, s38, 1.0
	v_pk_mul_f32 v[26:27], v[30:31], v[156:157] op_sel_hi:[1,0]
	v_cvt_pk_bf16_f32 v153, v26, v27
	v_rcp_f32_e32 v82, v82
	v_rcp_f32_e32 v83, v83
	v_pk_mul_f32 v[26:27], v[28:29], v[156:157] op_sel_hi:[1,0]
	v_cvt_pk_bf16_f32 v154, v26, v27
	v_pk_mul_f32 v[26:27], v[24:25], v[156:157] op_sel_hi:[1,0]
	v_cvt_pk_bf16_f32 v155, v26, v27
	v_add_co_u32_e32 v26, vcc, s88, v148
	v_pk_mul_f32 v[114:115], v[20:21], v[20:21]
	s_nop 0
	v_addc_co_u32_e32 v27, vcc, 0, v149, vcc
	global_store_dwordx4 v[26:27], v[152:155], off
	v_pk_fma_f32 v[26:27], v[82:83], s[40:41], v[146:147] op_sel_hi:[1,0,0]
	v_pk_mul_f32 v[114:115], v[114:115], s[50:51] op_sel_hi:[1,0]
	v_pk_fma_f32 v[26:27], v[82:83], v[26:27], s[44:45] op_sel_hi:[1,1,0]
	v_exp_f32_e32 v114, v114
	v_exp_f32_e32 v115, v115
	v_fma_f32 v152, |v22|, s38, 1.0
	v_fma_f32 v153, |v23|, s38, 1.0
	v_pk_fma_f32 v[26:27], v[82:83], v[26:27], s[46:47] op_sel_hi:[1,1,0]
	v_rcp_f32_e32 v152, v152
	v_rcp_f32_e32 v153, v153
	v_pk_fma_f32 v[26:27], v[82:83], v[26:27], s[48:49] op_sel_hi:[1,1,0]
	v_pk_mul_f32 v[26:27], v[82:83], v[26:27]
	v_pk_mul_f32 v[82:83], v[22:23], v[22:23]
	v_max_f32_e32 v50, 0, v20
	v_max_f32_e32 v51, 0, v21
	v_pk_mul_f32 v[26:27], v[114:115], v[26:27]
	v_fma_f32 v26, -|v20|, v26, v50
	v_fma_f32 v27, -|v21|, v27, v51
	v_pk_fma_f32 v[20:21], v[152:153], s[40:41], v[146:147] op_sel_hi:[1,0,0]
	v_pk_mul_f32 v[50:51], v[82:83], s[50:51] op_sel_hi:[1,0]
	v_pk_fma_f32 v[20:21], v[152:153], v[20:21], s[44:45] op_sel_hi:[1,1,0]
	v_exp_f32_e32 v50, v50
	v_exp_f32_e32 v51, v51
	v_pk_fma_f32 v[20:21], v[152:153], v[20:21], s[46:47] op_sel_hi:[1,1,0]
	v_pk_fma_f32 v[20:21], v[152:153], v[20:21], s[48:49] op_sel_hi:[1,1,0]
	v_max_f32_e32 v98, 0, v22
	v_pk_mul_f32 v[20:21], v[152:153], v[20:21]
	v_max_f32_e32 v99, 0, v23
	v_pk_mul_f32 v[20:21], v[50:51], v[20:21]
	v_fma_f32 v82, |v16|, s38, 1.0
	v_fma_f32 v83, |v17|, s38, 1.0
	v_pk_mul_f32 v[114:115], v[16:17], v[16:17]
	v_rcp_f32_e32 v82, v82
	v_rcp_f32_e32 v83, v83
	v_fma_f32 v22, -|v22|, v20, v98
	v_fma_f32 v23, -|v23|, v21, v99
	v_pk_fma_f32 v[20:21], v[82:83], s[40:41], v[146:147] op_sel_hi:[1,0,0]
	v_pk_mul_f32 v[114:115], v[114:115], s[50:51] op_sel_hi:[1,0]
	v_pk_fma_f32 v[20:21], v[82:83], v[20:21], s[44:45] op_sel_hi:[1,1,0]
	v_exp_f32_e32 v114, v114
	v_exp_f32_e32 v115, v115
	v_fma_f32 v152, |v18|, s38, 1.0
	v_fma_f32 v153, |v19|, s38, 1.0
	v_pk_fma_f32 v[20:21], v[82:83], v[20:21], s[46:47] op_sel_hi:[1,1,0]
	v_rcp_f32_e32 v152, v152
	v_rcp_f32_e32 v153, v153
	v_pk_fma_f32 v[20:21], v[82:83], v[20:21], s[48:49] op_sel_hi:[1,1,0]
	v_pk_mul_f32 v[20:21], v[82:83], v[20:21]
	v_pk_mul_f32 v[82:83], v[18:19], v[18:19]
	v_max_f32_e32 v50, 0, v16
	v_max_f32_e32 v51, 0, v17
	v_pk_mul_f32 v[20:21], v[114:115], v[20:21]
	v_fma_f32 v20, -|v16|, v20, v50
	v_fma_f32 v21, -|v17|, v21, v51
	v_pk_fma_f32 v[16:17], v[152:153], s[40:41], v[146:147] op_sel_hi:[1,0,0]
	v_pk_mul_f32 v[50:51], v[82:83], s[50:51] op_sel_hi:[1,0]
	v_pk_fma_f32 v[16:17], v[152:153], v[16:17], s[44:45] op_sel_hi:[1,1,0]
	v_exp_f32_e32 v50, v50
	v_exp_f32_e32 v51, v51
	v_pk_fma_f32 v[16:17], v[152:153], v[16:17], s[46:47] op_sel_hi:[1,1,0]
	v_pk_fma_f32 v[16:17], v[152:153], v[16:17], s[48:49] op_sel_hi:[1,1,0]
	v_max_f32_e32 v98, 0, v18
	v_pk_mul_f32 v[16:17], v[152:153], v[16:17]
	v_max_f32_e32 v99, 0, v19
	v_pk_mul_f32 v[16:17], v[50:51], v[16:17]
	v_lshl_add_u64 v[66:67], v[148:149], 0, s[58:59]
	v_fma_f32 v16, -|v18|, v16, v98
	v_fma_f32 v17, -|v19|, v17, v99
	v_pk_mul_f32 v[18:19], v[26:27], v[156:157] op_sel_hi:[1,0]
	v_cvt_pk_bf16_f32 v152, v18, v19
	v_pk_mul_f32 v[18:19], v[22:23], v[156:157] op_sel_hi:[1,0]
	v_cvt_pk_bf16_f32 v153, v18, v19
	v_pk_mul_f32 v[18:19], v[20:21], v[156:157] op_sel_hi:[1,0]
	v_cvt_pk_bf16_f32 v154, v18, v19
	v_pk_mul_f32 v[18:19], v[16:17], v[156:157] op_sel_hi:[1,0]
	v_cvt_pk_bf16_f32 v155, v18, v19
	global_store_dwordx4 v[66:67], v[152:155], off offset:256
	global_load_dword v154, v[150:151], off offset:704
	v_fma_f32 v18, |v12|, s38, 1.0
	v_fma_f32 v19, |v13|, s38, 1.0
	v_pk_mul_f32 v[114:115], v[12:13], v[12:13]
	v_rcp_f32_e32 v66, v18
	v_rcp_f32_e32 v67, v19
	v_pk_mul_f32 v[114:115], v[114:115], s[50:51] op_sel_hi:[1,0]
	v_pk_fma_f32 v[98:99], v[66:67], s[40:41], v[146:147] op_sel_hi:[1,0,0]
	v_exp_f32_e32 v114, v114
	v_pk_fma_f32 v[98:99], v[66:67], v[98:99], s[44:45] op_sel_hi:[1,1,0]
	v_exp_f32_e32 v115, v115
	v_fma_f32 v150, |v14|, s38, 1.0
	v_fma_f32 v151, |v15|, s38, 1.0
	v_pk_fma_f32 v[98:99], v[66:67], v[98:99], s[46:47] op_sel_hi:[1,1,0]
	v_rcp_f32_e32 v150, v150
	v_rcp_f32_e32 v151, v151
	v_pk_fma_f32 v[98:99], v[66:67], v[98:99], s[48:49] op_sel_hi:[1,1,0]
	v_pk_mul_f32 v[66:67], v[66:67], v[98:99]
	v_pk_mul_f32 v[98:99], v[14:15], v[14:15]
	v_max_f32_e32 v50, 0, v12
	v_max_f32_e32 v51, 0, v13
	v_pk_mul_f32 v[66:67], v[114:115], v[66:67]
	v_fma_f32 v50, -|v12|, v66, v50
	v_fma_f32 v51, -|v13|, v67, v51
	v_pk_fma_f32 v[12:13], v[150:151], s[40:41], v[146:147] op_sel_hi:[1,0,0]
	v_pk_mul_f32 v[66:67], v[98:99], s[50:51] op_sel_hi:[1,0]
	v_pk_fma_f32 v[12:13], v[150:151], v[12:13], s[44:45] op_sel_hi:[1,1,0]
	v_exp_f32_e32 v66, v66
	v_exp_f32_e32 v67, v67
	v_pk_fma_f32 v[12:13], v[150:151], v[12:13], s[46:47] op_sel_hi:[1,1,0]
	v_pk_fma_f32 v[12:13], v[150:151], v[12:13], s[48:49] op_sel_hi:[1,1,0]
	v_max_f32_e32 v82, 0, v14
	v_pk_mul_f32 v[12:13], v[150:151], v[12:13]
	v_max_f32_e32 v83, 0, v15
	v_pk_mul_f32 v[12:13], v[66:67], v[12:13]
	v_fma_f32 v98, |v8|, s38, 1.0
	v_fma_f32 v99, |v9|, s38, 1.0
	v_pk_mul_f32 v[114:115], v[8:9], v[8:9]
	v_rcp_f32_e32 v98, v98
	v_rcp_f32_e32 v99, v99
	v_fma_f32 v14, -|v14|, v12, v82
	v_fma_f32 v15, -|v15|, v13, v83
	v_pk_fma_f32 v[12:13], v[98:99], s[40:41], v[146:147] op_sel_hi:[1,0,0]
	v_pk_mul_f32 v[114:115], v[114:115], s[50:51] op_sel_hi:[1,0]
	v_pk_fma_f32 v[12:13], v[98:99], v[12:13], s[44:45] op_sel_hi:[1,1,0]
	v_exp_f32_e32 v114, v114
	v_exp_f32_e32 v115, v115
	v_fma_f32 v150, |v10|, s38, 1.0
	v_fma_f32 v151, |v11|, s38, 1.0
	v_pk_fma_f32 v[12:13], v[98:99], v[12:13], s[46:47] op_sel_hi:[1,1,0]
	v_rcp_f32_e32 v150, v150
	v_rcp_f32_e32 v151, v151
	v_pk_fma_f32 v[12:13], v[98:99], v[12:13], s[48:49] op_sel_hi:[1,1,0]
	v_pk_mul_f32 v[12:13], v[98:99], v[12:13]
	v_pk_mul_f32 v[98:99], v[10:11], v[10:11]
	v_max_f32_e32 v66, 0, v8
	v_max_f32_e32 v67, 0, v9
	v_pk_mul_f32 v[12:13], v[114:115], v[12:13]
	v_fma_f32 v12, -|v8|, v12, v66
	v_fma_f32 v13, -|v9|, v13, v67
	v_pk_fma_f32 v[8:9], v[150:151], s[40:41], v[146:147] op_sel_hi:[1,0,0]
	v_pk_mul_f32 v[66:67], v[98:99], s[50:51] op_sel_hi:[1,0]
	v_pk_fma_f32 v[8:9], v[150:151], v[8:9], s[44:45] op_sel_hi:[1,1,0]
	v_exp_f32_e32 v66, v66
	v_exp_f32_e32 v67, v67
	v_pk_fma_f32 v[8:9], v[150:151], v[8:9], s[46:47] op_sel_hi:[1,1,0]
	v_pk_fma_f32 v[8:9], v[150:151], v[8:9], s[48:49] op_sel_hi:[1,1,0]
	v_max_f32_e32 v82, 0, v10
	v_pk_mul_f32 v[8:9], v[150:151], v[8:9]
	v_max_f32_e32 v83, 0, v11
	v_pk_mul_f32 v[8:9], v[66:67], v[8:9]
	v_pk_fma_f32 v[34:35], v[50:51], v[50:51], v[34:35]
	v_fma_f32 v8, -|v10|, v8, v82
	v_fma_f32 v9, -|v11|, v9, v83
	s_waitcnt vmcnt(0)
	v_pk_mul_f32 v[10:11], v[50:51], v[154:155] op_sel_hi:[1,0]
	v_cvt_pk_bf16_f32 v150, v10, v11
	v_fma_f32 v66, |v4|, s38, 1.0
	v_fma_f32 v67, |v5|, s38, 1.0
	v_pk_mul_f32 v[10:11], v[14:15], v[154:155] op_sel_hi:[1,0]
	v_cvt_pk_bf16_f32 v151, v10, v11
	v_rcp_f32_e32 v66, v66
	v_rcp_f32_e32 v67, v67
	v_pk_mul_f32 v[10:11], v[12:13], v[154:155] op_sel_hi:[1,0]
	v_cvt_pk_bf16_f32 v152, v10, v11
	v_pk_mul_f32 v[10:11], v[8:9], v[154:155] op_sel_hi:[1,0]
	v_cvt_pk_bf16_f32 v153, v10, v11
	v_add_co_u32_e32 v10, vcc, s89, v148
	v_pk_mul_f32 v[98:99], v[4:5], v[4:5]
	s_nop 0
	v_addc_co_u32_e32 v11, vcc, 0, v149, vcc
	global_store_dwordx4 v[10:11], v[150:153], off
	v_pk_fma_f32 v[10:11], v[66:67], s[40:41], v[146:147] op_sel_hi:[1,0,0]
	v_pk_mul_f32 v[98:99], v[98:99], s[50:51] op_sel_hi:[1,0]
	v_pk_fma_f32 v[10:11], v[66:67], v[10:11], s[44:45] op_sel_hi:[1,1,0]
	v_exp_f32_e32 v98, v98
	v_exp_f32_e32 v99, v99
	v_fma_f32 v114, |v6|, s38, 1.0
	v_fma_f32 v115, |v7|, s38, 1.0
	v_pk_fma_f32 v[10:11], v[66:67], v[10:11], s[46:47] op_sel_hi:[1,1,0]
	v_rcp_f32_e32 v114, v114
	v_rcp_f32_e32 v115, v115
	v_pk_fma_f32 v[10:11], v[66:67], v[10:11], s[48:49] op_sel_hi:[1,1,0]
	v_pk_mul_f32 v[10:11], v[66:67], v[10:11]
	v_pk_mul_f32 v[66:67], v[6:7], v[6:7]
	v_max_f32_e32 v50, 0, v4
	v_max_f32_e32 v51, 0, v5
	v_pk_mul_f32 v[10:11], v[98:99], v[10:11]
	v_fma_f32 v10, -|v4|, v10, v50
	v_fma_f32 v11, -|v5|, v11, v51
	v_pk_fma_f32 v[4:5], v[114:115], s[40:41], v[146:147] op_sel_hi:[1,0,0]
	v_pk_mul_f32 v[50:51], v[66:67], s[50:51] op_sel_hi:[1,0]
	v_pk_fma_f32 v[4:5], v[114:115], v[4:5], s[44:45] op_sel_hi:[1,1,0]
	v_exp_f32_e32 v50, v50
	v_exp_f32_e32 v51, v51
	v_pk_fma_f32 v[4:5], v[114:115], v[4:5], s[46:47] op_sel_hi:[1,1,0]
	v_pk_fma_f32 v[4:5], v[114:115], v[4:5], s[48:49] op_sel_hi:[1,1,0]
	v_max_f32_e32 v82, 0, v6
	v_pk_mul_f32 v[4:5], v[114:115], v[4:5]
	v_max_f32_e32 v83, 0, v7
	v_pk_mul_f32 v[4:5], v[50:51], v[4:5]
	v_fma_f32 v66, |v0|, s38, 1.0
	v_fma_f32 v67, |v1|, s38, 1.0
	v_pk_mul_f32 v[98:99], v[0:1], v[0:1]
	v_rcp_f32_e32 v66, v66
	v_rcp_f32_e32 v67, v67
	v_fma_f32 v6, -|v6|, v4, v82
	v_fma_f32 v7, -|v7|, v5, v83
	v_pk_fma_f32 v[4:5], v[66:67], s[40:41], v[146:147] op_sel_hi:[1,0,0]
	v_pk_mul_f32 v[98:99], v[98:99], s[50:51] op_sel_hi:[1,0]
	v_pk_fma_f32 v[4:5], v[66:67], v[4:5], s[44:45] op_sel_hi:[1,1,0]
	v_exp_f32_e32 v98, v98
	v_exp_f32_e32 v99, v99
	v_fma_f32 v114, |v2|, s38, 1.0
	v_fma_f32 v115, |v3|, s38, 1.0
	v_pk_fma_f32 v[4:5], v[66:67], v[4:5], s[46:47] op_sel_hi:[1,1,0]
	v_rcp_f32_e32 v114, v114
	v_rcp_f32_e32 v115, v115
	v_pk_fma_f32 v[4:5], v[66:67], v[4:5], s[48:49] op_sel_hi:[1,1,0]
	v_pk_mul_f32 v[4:5], v[66:67], v[4:5]
	v_pk_mul_f32 v[66:67], v[2:3], v[2:3]
	v_max_f32_e32 v50, 0, v0
	v_max_f32_e32 v51, 0, v1
	v_pk_mul_f32 v[4:5], v[98:99], v[4:5]
	v_fma_f32 v4, -|v0|, v4, v50
	v_fma_f32 v5, -|v1|, v5, v51
	v_pk_fma_f32 v[0:1], v[114:115], s[40:41], v[146:147] op_sel_hi:[1,0,0]
	v_pk_mul_f32 v[50:51], v[66:67], s[50:51] op_sel_hi:[1,0]
	v_pk_fma_f32 v[0:1], v[114:115], v[0:1], s[44:45] op_sel_hi:[1,1,0]
	v_exp_f32_e32 v50, v50
	v_exp_f32_e32 v51, v51
	v_pk_fma_f32 v[0:1], v[114:115], v[0:1], s[46:47] op_sel_hi:[1,1,0]
	v_pk_fma_f32 v[0:1], v[114:115], v[0:1], s[48:49] op_sel_hi:[1,1,0]
	v_max_f32_e32 v82, 0, v2
	v_pk_mul_f32 v[0:1], v[114:115], v[0:1]
	v_max_f32_e32 v83, 0, v3
	v_pk_mul_f32 v[0:1], v[50:51], v[0:1]
	v_lshl_add_u64 v[18:19], v[148:149], 0, s[60:61]
	v_fma_f32 v2, -|v2|, v0, v82
	v_fma_f32 v3, -|v3|, v1, v83
	v_pk_mul_f32 v[0:1], v[10:11], v[154:155] op_sel_hi:[1,0]
	v_cvt_pk_bf16_f32 v146, v0, v1
	v_pk_mul_f32 v[0:1], v[6:7], v[154:155] op_sel_hi:[1,0]
	v_cvt_pk_bf16_f32 v147, v0, v1
	v_pk_mul_f32 v[0:1], v[4:5], v[154:155] op_sel_hi:[1,0]
	v_cvt_pk_bf16_f32 v148, v0, v1
	v_pk_mul_f32 v[0:1], v[2:3], v[154:155] op_sel_hi:[1,0]
	v_cvt_pk_bf16_f32 v149, v0, v1
	global_store_dwordx4 v[18:19], v[146:149], off offset:256
	v_mov_b32_dpp v0, v34 row_ror:8 row_mask:0xf bank_mask:0xf
	v_add_f32_e32 v0, v34, v0
	s_nop 1
	v_mov_b32_dpp v1, v0 row_ror:4 row_mask:0xf bank_mask:0xf
	v_add_f32_e32 v0, v0, v1
	s_nop 1
	v_mov_b32_dpp v1, v0 row_ror:2 row_mask:0xf bank_mask:0xf
	v_add_f32_e32 v18, v0, v1
	v_lshl_add_u64 v[0:1], v[136:137], 3, s[16:17]
	s_nop 0
	v_mov_b32_dpp v19, v18 row_ror:1 row_mask:0xf bank_mask:0xf
	s_and_saveexec_b64 s[70:71], s[6:7]
	s_cbranch_execz .LBB0_283
	v_add_f32_e32 v18, v18, v19
	v_mul_f32_e32 v18, 0x4f800000, v18
	v_trunc_f32_e32 v18, v18
	v_mul_f32_e32 v19, 0x2f800000, v18
	v_floor_f32_e32 v19, v19
	v_fmac_f32_e32 v18, 0xcf800000, v19
	v_cvt_u32_f32_e32 v18, v18
	v_cvt_u32_f32_e32 v19, v19
	global_atomic_add_x2 v[0:1], v[18:19], off

.LBB0_667:
	v_pk_mul_f32 v[206:207], v[112:113], v[182:183] op_sel_hi:[1,0]
	v_pk_mul_f32 v[150:151], v[116:117], v[186:187] op_sel_hi:[1,0]
	v_pk_mul_f32 v[144:145], v[124:125], v[184:185] op_sel_hi:[1,0]
	s_waitcnt lgkmcnt(0)
	v_mov_b32_dpp v138, v206 row_shr:1 row_mask:0xf bank_mask:0xf
	v_mov_b32_dpp v139, v207 row_shr:1 row_mask:0xf bank_mask:0xf
	v_mov_b32_dpp v190, v150 row_ror:15 row_mask:0xf bank_mask:0xf
	v_mov_b32_dpp v191, v151 row_ror:15 row_mask:0xf bank_mask:0xf
	v_mov_b32_dpp v208, v206 row_ror:1 row_mask:0xf bank_mask:0xf
	v_mov_b32_dpp v209, v207 row_ror:1 row_mask:0xf bank_mask:0xf
	v_pk_mul_f32 v[138:139], v[134:135], v[138:139]
	v_pk_mul_f32 v[140:141], v[120:121], v[180:181] op_sel_hi:[1,0]
	v_mov_b32_dpp v146, v144 row_ror:1 row_mask:0xf bank_mask:0xf
	v_mov_b32_dpp v147, v145 row_ror:1 row_mask:0xf bank_mask:0xf
	v_mov_b32_dpp v188, v150 row_ror:1 row_mask:0xf bank_mask:0xf
	v_mov_b32_dpp v189, v151 row_ror:1 row_mask:0xf bank_mask:0xf
	v_pk_fma_f32 v[138:139], v[206:207], v[136:137], v[138:139]
	v_mov_b32_dpp v208, v150 row_shr:1 row_mask:0xf bank_mask:0xf
	v_mov_b32_dpp v190, v206 row_shl:1 row_mask:0xf bank_mask:0xf
	v_mov_b32_dpp v209, v151 row_shr:1 row_mask:0xf bank_mask:0xf
	v_mov_b32_dpp v191, v207 row_shl:1 row_mask:0xf bank_mask:0xf
	v_mov_b32_dpp v148, v144 row_ror:15 row_mask:0xf bank_mask:0xf
	v_mov_b32_dpp v149, v145 row_ror:15 row_mask:0xf bank_mask:0xf
	v_pk_fma_f32 v[138:139], v[128:129], v[190:191], v[138:139]
	v_pk_mul_f32 v[190:191], v[134:135], v[208:209]
	v_mov_b32_dpp v188, v144 row_shr:1 row_mask:0xf bank_mask:0xf
	v_mov_b32_dpp v189, v145 row_shr:1 row_mask:0xf bank_mask:0xf
	v_mov_b32_dpp v146, v140 row_shr:1 row_mask:0xf bank_mask:0xf
	v_mov_b32_dpp v147, v141 row_shr:1 row_mask:0xf bank_mask:0xf
	v_pk_add_f32 v[138:139], v[130:131], v[138:139]
	v_pk_fma_f32 v[190:191], v[150:151], v[136:137], v[190:191]
	v_mov_b32_dpp v148, v150 row_shl:1 row_mask:0xf bank_mask:0xf
	v_mov_b32_dpp v149, v151 row_shl:1 row_mask:0xf bank_mask:0xf
	v_pk_mul_f32 v[150:151], v[134:135], v[188:189]
	v_pk_mul_f32 v[134:135], v[134:135], v[146:147]
	v_pk_fma_f32 v[150:151], v[144:145], v[136:137], v[150:151]
	v_pk_fma_f32 v[134:135], v[140:141], v[136:137], v[134:135]
	v_mov_b32_dpp v142, v140 row_ror:15 row_mask:0xf bank_mask:0xf
	v_mov_b32_dpp v132, v140 row_shl:1 row_mask:0xf bank_mask:0xf
	v_mov_b32_dpp v143, v141 row_ror:15 row_mask:0xf bank_mask:0xf
	v_mov_b32_dpp v133, v141 row_shl:1 row_mask:0xf bank_mask:0xf
	v_fma_f32 v140, |v138|, s52, 1.0
	v_fma_f32 v141, |v139|, s52, 1.0
	v_mov_b32_dpp v142, v144 row_shl:1 row_mask:0xf bank_mask:0xf
	v_rcp_f32_e32 v140, v140
	v_rcp_f32_e32 v141, v141
	v_mov_b32_dpp v143, v145 row_shl:1 row_mask:0xf bank_mask:0xf
	v_pk_fma_f32 v[148:149], v[128:129], v[148:149], v[190:191]
	v_pk_fma_f32 v[142:143], v[128:129], v[142:143], v[150:151]
	v_pk_fma_f32 v[128:129], v[128:129], v[132:133], v[134:135]
	v_pk_mul_f32 v[132:133], v[138:139], v[138:139]
	v_pk_add_f32 v[148:149], v[130:131], v[148:149]
	v_pk_add_f32 v[142:143], v[130:131], v[142:143]
	v_pk_add_f32 v[130:131], v[130:131], v[128:129]
	v_pk_fma_f32 v[128:129], v[140:141], s[54:55], v[246:247] op_sel_hi:[1,0,0]
	v_pk_mul_f32 v[132:133], v[132:133], s[64:65] op_sel_hi:[1,0]
	v_pk_fma_f32 v[128:129], v[140:141], v[128:129], s[58:59] op_sel_hi:[1,1,0]
	v_exp_f32_e32 v132, v132
	v_exp_f32_e32 v133, v133
	v_pk_fma_f32 v[128:129], v[140:141], v[128:129], s[60:61] op_sel_hi:[1,1,0]
	v_max_f32_e32 v136, 0, v138
	v_pk_fma_f32 v[128:129], v[140:141], v[128:129], s[62:63] op_sel_hi:[1,1,0]
	v_max_f32_e32 v137, 0, v139
	v_pk_mul_f32 v[128:129], v[140:141], v[128:129]
	v_pk_mul_f32 v[140:141], v[148:149], v[148:149]
	v_pk_mul_f32 v[128:129], v[132:133], v[128:129]
	v_fma_f32 v128, -|v138|, v128, v136
	v_fma_f32 v129, -|v139|, v129, v137
	v_fma_f32 v136, |v148|, s52, 1.0
	v_fma_f32 v137, |v149|, s52, 1.0
	v_pk_mul_f32 v[140:141], v[140:141], s[64:65] op_sel_hi:[1,0]
	v_rcp_f32_e32 v136, v136
	v_rcp_f32_e32 v137, v137
	v_exp_f32_e32 v140, v140
	v_exp_f32_e32 v141, v141
	v_pk_mul_f32 v[144:145], v[142:143], v[142:143]
	v_pk_fma_f32 v[138:139], v[136:137], s[54:55], v[246:247] op_sel_hi:[1,0,0]
	v_pk_mul_f32 v[144:145], v[144:145], s[64:65] op_sel_hi:[1,0]
	v_pk_fma_f32 v[138:139], v[136:137], v[138:139], s[58:59] op_sel_hi:[1,1,0]
	v_exp_f32_e32 v144, v144
	v_pk_fma_f32 v[138:139], v[136:137], v[138:139], s[60:61] op_sel_hi:[1,1,0]
	v_exp_f32_e32 v145, v145
	v_pk_fma_f32 v[138:139], v[136:137], v[138:139], s[62:63] op_sel_hi:[1,1,0]
	v_pk_mul_f32 v[136:137], v[136:137], v[138:139]
	v_max_f32_e32 v138, 0, v148
	v_max_f32_e32 v139, 0, v149
	v_pk_mul_f32 v[136:137], v[140:141], v[136:137]
	v_pk_mul_f32 v[128:129], v[108:109], v[128:129]
	v_fma_f32 v132, -|v148|, v136, v138
	v_fma_f32 v133, -|v149|, v137, v139
	v_and_b32_e32 v137, 0x7fffffff, v143
	v_and_b32_e32 v136, 0x7fffffff, v142
	v_pk_fma_f32 v[138:139], v[136:137], s[52:53], 1.0 op_sel_hi:[1,0,0]
	v_rcp_f32_e32 v138, v138
	v_rcp_f32_e32 v139, v139
	v_pk_mul_f32 v[128:129], v[182:183], v[128:129] op_sel_hi:[0,1]
	v_cvt_pk_bf16_f32 v128, v128, v129
	v_pk_fma_f32 v[140:141], v[138:139], s[54:55], v[246:247] op_sel_hi:[1,0,0]
	v_pk_mul_f32 v[132:133], v[104:105], v[132:133]
	v_pk_fma_f32 v[140:141], v[138:139], v[140:141], s[58:59] op_sel_hi:[1,1,0]
	v_pk_fma_f32 v[140:141], v[138:139], v[140:141], s[60:61] op_sel_hi:[1,1,0]
	v_pk_mul_f32 v[132:133], v[186:187], v[132:133] op_sel_hi:[0,1]
	v_pk_fma_f32 v[140:141], v[138:139], v[140:141], s[62:63] op_sel_hi:[1,1,0]
	v_cvt_pk_bf16_f32 v132, v132, v133
	v_lshl_add_u32 v206, v204, 2, s89
	v_pk_mul_f32 v[138:139], v[138:139], v[140:141]
	v_max_f32_e32 v140, 0, v142
	v_max_f32_e32 v141, 0, v143
	v_pk_mul_f32 v[138:139], v[144:145], v[138:139]
	v_pk_mul_f32 v[142:143], v[130:131], v[130:131]
	v_pk_fma_f32 v[136:137], v[136:137], v[138:139], v[140:141] neg_lo:[1,0,0] neg_hi:[1,0,0]
	v_fma_f32 v140, |v130|, s52, 1.0
	v_fma_f32 v141, |v131|, s52, 1.0
	v_pk_mul_f32 v[142:143], v[142:143], s[64:65] op_sel_hi:[1,0]
	v_rcp_f32_e32 v140, v140
	v_rcp_f32_e32 v141, v141
	v_exp_f32_e32 v142, v142
	v_exp_f32_e32 v143, v143
	v_mul_f32_e32 v129, v100, v136
	v_pk_fma_f32 v[134:135], v[140:141], s[54:55], v[246:247] op_sel_hi:[1,0,0]
	v_max_f32_e32 v138, 0, v130
	v_pk_fma_f32 v[134:135], v[140:141], v[134:135], s[58:59] op_sel_hi:[1,1,0]
	v_max_f32_e32 v139, 0, v131
	v_pk_fma_f32 v[134:135], v[140:141], v[134:135], s[60:61] op_sel_hi:[1,1,0]
	v_mul_f32_e32 v129, v184, v129
	v_pk_fma_f32 v[134:135], v[140:141], v[134:135], s[62:63] op_sel_hi:[1,1,0]
	v_mul_f32_e32 v133, v101, v137
	v_pk_mul_f32 v[134:135], v[140:141], v[134:135]
	v_mul_f32_e32 v133, v184, v133
	v_pk_mul_f32 v[134:135], v[142:143], v[134:135]
	v_cvt_pk_bf16_f32 v136, v129, v133
	v_add_u32_e32 v207, 8, v206
	v_fma_f32 v130, -|v130|, v134, v138
	v_fma_f32 v131, -|v131|, v135, v139
	s_and_b64 vcc, exec, s[6:7]
	v_pk_mul_f32 v[130:131], v[96:97], v[130:131]
	v_pk_mul_f32 v[130:131], v[180:181], v[130:131] op_sel_hi:[0,1]
	v_cvt_pk_bf16_f32 v140, v130, v131
	ds_read2st64_b64 v[146:149], v207 offset0:10 offset1:11
	ds_read2st64_b64 v[142:145], v207 offset0:12 offset1:13
	v_mov_b32_e32 v130, 0
	v_mov_b32_e32 v134, 0
	v_mov_b32_e32 v135, 0
	s_cbranch_vccnz .LBB0_669
	v_lshl_add_u32 v129, v204, 2, s90
	ds_read_b64 v[134:135], v129 offset:1544

.LBB0_671:
	v_mov_b32_e32 v183, v182
	v_mov_b32_e32 v187, v186
	v_pk_mul_f32 v[218:219], v[114:115], v[182:183]
	v_mov_b32_e32 v185, v184
	v_pk_mul_f32 v[210:211], v[118:119], v[186:187]
	s_waitcnt lgkmcnt(0)
	v_mov_b32_dpp v134, v218 row_shr:1 row_mask:0xf bank_mask:0xf
	v_mov_b32_dpp v135, v219 row_shr:1 row_mask:0xf bank_mask:0xf
	v_mov_b32_e32 v181, v180
	v_pk_mul_f32 v[188:189], v[126:127], v[184:185]
	v_mov_b32_dpp v216, v210 row_ror:15 row_mask:0xf bank_mask:0xf
	v_mov_b32_dpp v217, v211 row_ror:15 row_mask:0xf bank_mask:0xf
	v_mov_b32_dpp v220, v218 row_ror:1 row_mask:0xf bank_mask:0xf
	v_mov_b32_dpp v221, v219 row_ror:1 row_mask:0xf bank_mask:0xf
	v_pk_mul_f32 v[134:135], v[146:147], v[134:135]
	v_pk_mul_f32 v[138:139], v[122:123], v[180:181]
	v_mov_b32_dpp v190, v188 row_ror:1 row_mask:0xf bank_mask:0xf
	v_mov_b32_dpp v191, v189 row_ror:1 row_mask:0xf bank_mask:0xf
	v_mov_b32_dpp v214, v210 row_ror:1 row_mask:0xf bank_mask:0xf
	v_mov_b32_dpp v215, v211 row_ror:1 row_mask:0xf bank_mask:0xf
	v_pk_fma_f32 v[134:135], v[218:219], v[148:149], v[134:135]
	v_mov_b32_dpp v220, v210 row_shr:1 row_mask:0xf bank_mask:0xf
	v_mov_b32_dpp v216, v218 row_shl:1 row_mask:0xf bank_mask:0xf
	v_mov_b32_dpp v221, v211 row_shr:1 row_mask:0xf bank_mask:0xf
	v_mov_b32_dpp v217, v219 row_shl:1 row_mask:0xf bank_mask:0xf
	v_mov_b32_dpp v208, v188 row_ror:15 row_mask:0xf bank_mask:0xf
	v_mov_b32_dpp v209, v189 row_ror:15 row_mask:0xf bank_mask:0xf
	v_pk_fma_f32 v[134:135], v[142:143], v[216:217], v[134:135]
	v_pk_mul_f32 v[216:217], v[146:147], v[220:221]
	v_mov_b32_dpp v214, v188 row_shr:1 row_mask:0xf bank_mask:0xf
	v_mov_b32_dpp v215, v189 row_shr:1 row_mask:0xf bank_mask:0xf
	v_mov_b32_dpp v190, v138 row_shr:1 row_mask:0xf bank_mask:0xf
	v_mov_b32_dpp v191, v139 row_shr:1 row_mask:0xf bank_mask:0xf
	v_pk_add_f32 v[134:135], v[144:145], v[134:135]
	v_pk_fma_f32 v[216:217], v[210:211], v[148:149], v[216:217]
	v_mov_b32_dpp v208, v210 row_shl:1 row_mask:0xf bank_mask:0xf
	v_mov_b32_dpp v209, v211 row_shl:1 row_mask:0xf bank_mask:0xf
	v_pk_mul_f32 v[210:211], v[146:147], v[214:215]
	v_pk_mul_f32 v[146:147], v[146:147], v[190:191]
	v_mov_b32_dpp v150, v138 row_ror:15 row_mask:0xf bank_mask:0xf
	v_mov_b32_dpp v130, v138 row_shl:1 row_mask:0xf bank_mask:0xf
	v_mov_b32_dpp v151, v139 row_ror:15 row_mask:0xf bank_mask:0xf
	v_mov_b32_dpp v131, v139 row_shl:1 row_mask:0xf bank_mask:0xf
	v_pk_fma_f32 v[138:139], v[138:139], v[148:149], v[146:147]
	v_pk_fma_f32 v[210:211], v[188:189], v[148:149], v[210:211]
	v_fma_f32 v148, |v134|, s52, 1.0
	v_fma_f32 v149, |v135|, s52, 1.0
	v_mov_b32_dpp v150, v188 row_shl:1 row_mask:0xf bank_mask:0xf
	v_rcp_f32_e32 v148, v148
	v_rcp_f32_e32 v149, v149
	v_mov_b32_dpp v151, v189 row_shl:1 row_mask:0xf bank_mask:0xf
	v_pk_fma_f32 v[208:209], v[142:143], v[208:209], v[216:217]
	v_pk_fma_f32 v[150:151], v[142:143], v[150:151], v[210:211]
	v_pk_fma_f32 v[130:131], v[142:143], v[130:131], v[138:139]
	v_pk_add_f32 v[208:209], v[144:145], v[208:209]
	v_pk_add_f32 v[150:151], v[144:145], v[150:151]
	v_pk_add_f32 v[130:131], v[144:145], v[130:131]
	v_pk_mul_f32 v[144:145], v[134:135], v[134:135]
	v_pk_fma_f32 v[142:143], v[148:149], s[54:55], v[246:247] op_sel_hi:[1,0,0]
	v_pk_mul_f32 v[144:145], v[144:145], s[64:65] op_sel_hi:[1,0]
	v_pk_fma_f32 v[142:143], v[148:149], v[142:143], s[58:59] op_sel_hi:[1,1,0]
	v_exp_f32_e32 v144, v144
	v_exp_f32_e32 v145, v145
	v_pk_fma_f32 v[142:143], v[148:149], v[142:143], s[60:61] op_sel_hi:[1,1,0]
	v_max_f32_e32 v146, 0, v134
	v_pk_fma_f32 v[142:143], v[148:149], v[142:143], s[62:63] op_sel_hi:[1,1,0]
	v_max_f32_e32 v147, 0, v135
	v_pk_mul_f32 v[142:143], v[148:149], v[142:143]
	s_and_b64 vcc, exec, s[6:7]
	v_pk_mul_f32 v[142:143], v[144:145], v[142:143]
	s_nop 0
	v_fma_f32 v134, -|v134|, v142, v146
	v_fma_f32 v135, -|v135|, v143, v147
	v_fma_f32 v144, |v208|, s52, 1.0
	v_fma_f32 v145, |v209|, s52, 1.0
	v_pk_mul_f32 v[146:147], v[208:209], v[208:209]
	v_rcp_f32_e32 v144, v144
	v_rcp_f32_e32 v145, v145
	v_pk_mul_f32 v[248:249], v[110:111], v[134:135]
	v_pk_mul_f32 v[146:147], v[146:147], s[64:65] op_sel_hi:[1,0]
	v_pk_fma_f32 v[134:135], v[144:145], s[54:55], v[246:247] op_sel_hi:[1,0,0]
	v_exp_f32_e32 v146, v146
	v_pk_fma_f32 v[134:135], v[144:145], v[134:135], s[58:59] op_sel_hi:[1,1,0]
	v_exp_f32_e32 v147, v147
	v_pk_fma_f32 v[134:135], v[144:145], v[134:135], s[60:61] op_sel_hi:[1,1,0]
	v_pk_mul_f32 v[248:249], v[182:183], v[248:249] op_sel_hi:[0,1]
	v_pk_fma_f32 v[134:135], v[144:145], v[134:135], s[62:63] op_sel_hi:[1,1,0]
	v_pk_mul_f32 v[134:135], v[144:145], v[134:135]
	v_max_f32_e32 v144, 0, v208
	v_max_f32_e32 v145, 0, v209
	v_pk_mul_f32 v[134:135], v[146:147], v[134:135]
	v_cvt_pk_bf16_f32 v129, v248, v249
	v_pk_mul_f32 v[146:147], v[150:151], v[150:151]
	v_fma_f32 v134, -|v208|, v134, v144
	v_fma_f32 v135, -|v209|, v135, v145
	v_fma_f32 v144, |v150|, s52, 1.0
	v_fma_f32 v145, |v151|, s52, 1.0
	v_rcp_f32_e32 v144, v144
	v_rcp_f32_e32 v145, v145
	v_pk_mul_f32 v[134:135], v[106:107], v[134:135]
	v_pk_mul_f32 v[134:135], v[186:187], v[134:135] op_sel_hi:[0,1]
	v_cvt_pk_bf16_f32 v133, v134, v135
	v_pk_fma_f32 v[134:135], v[144:145], s[54:55], v[246:247] op_sel_hi:[1,0,0]
	v_pk_mul_f32 v[146:147], v[146:147], s[64:65] op_sel_hi:[1,0]
	v_pk_fma_f32 v[134:135], v[144:145], v[134:135], s[58:59] op_sel_hi:[1,1,0]
	v_exp_f32_e32 v146, v146
	v_exp_f32_e32 v147, v147
	v_pk_fma_f32 v[134:135], v[144:145], v[134:135], s[60:61] op_sel_hi:[1,1,0]
	v_add_u32_e32 v208, 16, v206
	v_pk_fma_f32 v[134:135], v[144:145], v[134:135], s[62:63] op_sel_hi:[1,1,0]
	s_nop 0
	v_pk_mul_f32 v[134:135], v[144:145], v[134:135]
	v_max_f32_e32 v144, 0, v150
	v_max_f32_e32 v145, 0, v151
	v_pk_mul_f32 v[134:135], v[146:147], v[134:135]
	s_nop 0
	v_fma_f32 v134, -|v150|, v134, v144
	v_fma_f32 v135, -|v151|, v135, v145
	v_fma_f32 v144, |v130|, s52, 1.0
	v_fma_f32 v145, |v131|, s52, 1.0
	v_rcp_f32_e32 v144, v144
	v_rcp_f32_e32 v145, v145
	v_pk_mul_f32 v[134:135], v[102:103], v[134:135]
	v_pk_mul_f32 v[134:135], v[184:185], v[134:135] op_sel_hi:[0,1]
	v_cvt_pk_bf16_f32 v137, v134, v135
	v_pk_fma_f32 v[134:135], v[144:145], s[54:55], v[246:247] op_sel_hi:[1,0,0]
	v_pk_mul_f32 v[138:139], v[130:131], v[130:131]
	v_pk_fma_f32 v[134:135], v[144:145], v[134:135], s[58:59] op_sel_hi:[1,1,0]
	v_pk_mul_f32 v[138:139], v[138:139], s[64:65] op_sel_hi:[1,0]
	v_pk_fma_f32 v[134:135], v[144:145], v[134:135], s[60:61] op_sel_hi:[1,1,0]
	v_exp_f32_e32 v138, v138
	v_exp_f32_e32 v139, v139
	v_pk_fma_f32 v[134:135], v[144:145], v[134:135], s[62:63] op_sel_hi:[1,1,0]
	v_max_f32_e32 v142, 0, v130
	v_pk_mul_f32 v[134:135], v[144:145], v[134:135]
	v_max_f32_e32 v143, 0, v131
	v_pk_mul_f32 v[134:135], v[138:139], v[134:135]
	s_nop 0
	v_fma_f32 v130, -|v130|, v134, v142
	v_fma_f32 v131, -|v131|, v135, v143
	v_mov_b32_e32 v134, 0
	v_pk_mul_f32 v[130:131], v[98:99], v[130:131]
	v_pk_mul_f32 v[130:131], v[180:181], v[130:131] op_sel_hi:[0,1]
	v_cvt_pk_bf16_f32 v141, v130, v131
	ds_read2st64_b64 v[146:149], v208 offset0:10 offset1:11
	ds_read2st64_b64 v[142:145], v208 offset0:12 offset1:13
	v_mov_b32_e32 v130, 0
	v_mov_b32_e32 v135, 0
	s_cbranch_vccnz .LBB0_673
	v_lshl_add_u32 v131, v204, 2, s90
	ds_read_b64 v[134:135], v131 offset:1552

.LBB0_675:
	v_pk_mul_f32 v[220:221], v[80:81], v[182:183]
	v_pk_mul_f32 v[214:215], v[88:89], v[186:187]
	v_pk_mul_f32 v[188:189], v[92:93], v[184:185]
	s_waitcnt lgkmcnt(0)
	v_mov_b32_dpp v134, v220 row_shr:1 row_mask:0xf bank_mask:0xf
	v_mov_b32_dpp v135, v221 row_shr:1 row_mask:0xf bank_mask:0xf
	v_mov_b32_dpp v218, v214 row_ror:15 row_mask:0xf bank_mask:0xf
	v_mov_b32_dpp v219, v215 row_ror:15 row_mask:0xf bank_mask:0xf
	v_mov_b32_dpp v222, v220 row_ror:1 row_mask:0xf bank_mask:0xf
	v_mov_b32_dpp v223, v221 row_ror:1 row_mask:0xf bank_mask:0xf
	v_pk_mul_f32 v[134:135], v[146:147], v[134:135]
	v_pk_mul_f32 v[138:139], v[84:85], v[180:181]
	v_mov_b32_dpp v190, v188 row_ror:1 row_mask:0xf bank_mask:0xf
	v_mov_b32_dpp v191, v189 row_ror:1 row_mask:0xf bank_mask:0xf
	v_mov_b32_dpp v216, v214 row_ror:1 row_mask:0xf bank_mask:0xf
	v_mov_b32_dpp v217, v215 row_ror:1 row_mask:0xf bank_mask:0xf
	v_pk_fma_f32 v[134:135], v[220:221], v[148:149], v[134:135]
	v_mov_b32_dpp v222, v214 row_shr:1 row_mask:0xf bank_mask:0xf
	v_mov_b32_dpp v218, v220 row_shl:1 row_mask:0xf bank_mask:0xf
	v_mov_b32_dpp v223, v215 row_shr:1 row_mask:0xf bank_mask:0xf
	v_mov_b32_dpp v219, v221 row_shl:1 row_mask:0xf bank_mask:0xf
	v_mov_b32_dpp v210, v188 row_ror:15 row_mask:0xf bank_mask:0xf
	v_mov_b32_dpp v211, v189 row_ror:15 row_mask:0xf bank_mask:0xf
	v_pk_fma_f32 v[134:135], v[142:143], v[218:219], v[134:135]
	v_pk_mul_f32 v[218:219], v[146:147], v[222:223]
	v_mov_b32_dpp v216, v188 row_shr:1 row_mask:0xf bank_mask:0xf
	v_mov_b32_dpp v217, v189 row_shr:1 row_mask:0xf bank_mask:0xf
	v_mov_b32_dpp v190, v138 row_shr:1 row_mask:0xf bank_mask:0xf
	v_mov_b32_dpp v191, v139 row_shr:1 row_mask:0xf bank_mask:0xf
	v_pk_add_f32 v[134:135], v[144:145], v[134:135]
	v_pk_fma_f32 v[218:219], v[214:215], v[148:149], v[218:219]
	v_mov_b32_dpp v210, v214 row_shl:1 row_mask:0xf bank_mask:0xf
	v_mov_b32_dpp v211, v215 row_shl:1 row_mask:0xf bank_mask:0xf
	v_pk_mul_f32 v[214:215], v[146:147], v[216:217]
	v_pk_mul_f32 v[146:147], v[146:147], v[190:191]
	v_mov_b32_dpp v150, v138 row_ror:15 row_mask:0xf bank_mask:0xf
	v_mov_b32_dpp v130, v138 row_shl:1 row_mask:0xf bank_mask:0xf
	v_mov_b32_dpp v151, v139 row_ror:15 row_mask:0xf bank_mask:0xf
	v_mov_b32_dpp v131, v139 row_shl:1 row_mask:0xf bank_mask:0xf
	v_pk_fma_f32 v[138:139], v[138:139], v[148:149], v[146:147]
	v_pk_fma_f32 v[214:215], v[188:189], v[148:149], v[214:215]
	v_fma_f32 v148, |v134|, s52, 1.0
	v_fma_f32 v149, |v135|, s52, 1.0
	v_mov_b32_dpp v150, v188 row_shl:1 row_mask:0xf bank_mask:0xf
	v_rcp_f32_e32 v148, v148
	v_rcp_f32_e32 v149, v149
	v_mov_b32_dpp v151, v189 row_shl:1 row_mask:0xf bank_mask:0xf
	v_pk_fma_f32 v[210:211], v[142:143], v[210:211], v[218:219]
	v_pk_fma_f32 v[150:151], v[142:143], v[150:151], v[214:215]
	v_pk_fma_f32 v[130:131], v[142:143], v[130:131], v[138:139]
	v_pk_add_f32 v[210:211], v[144:145], v[210:211]
	v_pk_add_f32 v[150:151], v[144:145], v[150:151]
	v_pk_add_f32 v[142:143], v[144:145], v[130:131]
	v_pk_mul_f32 v[138:139], v[134:135], v[134:135]
	v_pk_fma_f32 v[130:131], v[148:149], s[54:55], v[246:247] op_sel_hi:[1,0,0]
	v_pk_mul_f32 v[138:139], v[138:139], s[64:65] op_sel_hi:[1,0]
	v_pk_fma_f32 v[130:131], v[148:149], v[130:131], s[58:59] op_sel_hi:[1,1,0]
	v_exp_f32_e32 v138, v138
	v_exp_f32_e32 v139, v139
	v_pk_fma_f32 v[130:131], v[148:149], v[130:131], s[60:61] op_sel_hi:[1,1,0]
	v_max_f32_e32 v146, 0, v134
	v_pk_fma_f32 v[130:131], v[148:149], v[130:131], s[62:63] op_sel_hi:[1,1,0]
	v_max_f32_e32 v147, 0, v135
	v_pk_mul_f32 v[130:131], v[148:149], v[130:131]
	v_pk_mul_f32 v[148:149], v[210:211], v[210:211]
	v_pk_mul_f32 v[130:131], v[138:139], v[130:131]
	v_pk_mul_f32 v[148:149], v[148:149], s[64:65] op_sel_hi:[1,0]
	v_fma_f32 v130, -|v134|, v130, v146
	v_fma_f32 v131, -|v135|, v131, v147
	v_fma_f32 v138, |v210|, s52, 1.0
	v_fma_f32 v139, |v211|, s52, 1.0
	v_exp_f32_e32 v148, v148
	v_rcp_f32_e32 v138, v138
	v_rcp_f32_e32 v139, v139
	v_exp_f32_e32 v149, v149
	v_pk_mul_f32 v[188:189], v[150:151], v[150:151]
	v_pk_fma_f32 v[146:147], v[138:139], s[54:55], v[246:247] op_sel_hi:[1,0,0]
	v_pk_mul_f32 v[188:189], v[188:189], s[64:65] op_sel_hi:[1,0]
	v_pk_fma_f32 v[146:147], v[138:139], v[146:147], s[58:59] op_sel_hi:[1,1,0]
	v_exp_f32_e32 v188, v188
	v_pk_fma_f32 v[146:147], v[138:139], v[146:147], s[60:61] op_sel_hi:[1,1,0]
	v_exp_f32_e32 v189, v189
	v_pk_fma_f32 v[146:147], v[138:139], v[146:147], s[62:63] op_sel_hi:[1,1,0]
	v_pk_mul_f32 v[130:131], v[76:77], v[130:131]
	v_pk_mul_f32 v[138:139], v[138:139], v[146:147]
	v_max_f32_e32 v146, 0, v210
	v_max_f32_e32 v147, 0, v211
	v_pk_mul_f32 v[138:139], v[148:149], v[138:139]
	v_fma_f32 v134, -|v210|, v138, v146
	v_fma_f32 v135, -|v211|, v139, v147
	v_and_b32_e32 v139, 0x7fffffff, v151
	v_and_b32_e32 v138, 0x7fffffff, v150
	v_pk_fma_f32 v[146:147], v[138:139], s[52:53], 1.0 op_sel_hi:[1,0,0]
	v_pk_mul_f32 v[130:131], v[182:183], v[130:131] op_sel_hi:[0,1]
	v_rcp_f32_e32 v146, v146
	v_rcp_f32_e32 v147, v147
	v_cvt_pk_bf16_f32 v130, v130, v131
	v_pk_mul_f32 v[134:135], v[72:73], v[134:135]
	v_pk_fma_f32 v[148:149], v[146:147], s[54:55], v[246:247] op_sel_hi:[1,0,0]
	v_pk_fma_f32 v[148:149], v[146:147], v[148:149], s[58:59] op_sel_hi:[1,1,0]
	v_pk_mul_f32 v[134:135], v[186:187], v[134:135] op_sel_hi:[0,1]
	v_pk_fma_f32 v[148:149], v[146:147], v[148:149], s[60:61] op_sel_hi:[1,1,0]
	v_cvt_pk_bf16_f32 v134, v134, v135
	v_add_u32_e32 v209, 24, v206
	v_pk_fma_f32 v[148:149], v[146:147], v[148:149], s[62:63] op_sel_hi:[1,1,0]
	s_and_b64 vcc, exec, s[6:7]
	v_pk_mul_f32 v[146:147], v[146:147], v[148:149]
	v_max_f32_e32 v148, 0, v150
	v_max_f32_e32 v149, 0, v151
	v_pk_mul_f32 v[146:147], v[188:189], v[146:147]
	v_pk_mul_f32 v[150:151], v[142:143], v[142:143]
	v_pk_fma_f32 v[138:139], v[138:139], v[146:147], v[148:149] neg_lo:[1,0,0] neg_hi:[1,0,0]
	v_fma_f32 v148, |v142|, s52, 1.0
	v_fma_f32 v149, |v143|, s52, 1.0
	v_pk_mul_f32 v[150:151], v[150:151], s[64:65] op_sel_hi:[1,0]
	v_rcp_f32_e32 v148, v148
	v_rcp_f32_e32 v149, v149
	v_exp_f32_e32 v150, v150
	v_exp_f32_e32 v151, v151
	v_pk_fma_f32 v[144:145], v[148:149], s[54:55], v[246:247] op_sel_hi:[1,0,0]
	v_pk_mul_f32 v[138:139], v[68:69], v[138:139]
	v_pk_fma_f32 v[144:145], v[148:149], v[144:145], s[58:59] op_sel_hi:[1,1,0]
	v_max_f32_e32 v146, 0, v142
	v_pk_fma_f32 v[144:145], v[148:149], v[144:145], s[60:61] op_sel_hi:[1,1,0]
	v_max_f32_e32 v147, 0, v143
	v_pk_fma_f32 v[144:145], v[148:149], v[144:145], s[62:63] op_sel_hi:[1,1,0]
	v_pk_mul_f32 v[144:145], v[148:149], v[144:145]
	v_pk_mul_f32 v[138:139], v[184:185], v[138:139] op_sel_hi:[0,1]
	v_pk_mul_f32 v[144:145], v[150:151], v[144:145]
	v_cvt_pk_bf16_f32 v138, v138, v139
	v_mov_b32_e32 v188, 0
	v_fma_f32 v142, -|v142|, v144, v146
	v_fma_f32 v143, -|v143|, v145, v147
	v_mov_b32_e32 v190, 0
	v_pk_mul_f32 v[142:143], v[64:65], v[142:143]
	v_pk_mul_f32 v[142:143], v[180:181], v[142:143] op_sel_hi:[0,1]
	v_cvt_pk_bf16_f32 v142, v142, v143
	ds_read2st64_b64 v[148:151], v209 offset0:10 offset1:11
	ds_read2st64_b64 v[144:147], v209 offset0:12 offset1:13
	v_mov_b32_e32 v191, 0
	s_cbranch_vccnz .LBB0_677
	v_lshl_add_u32 v131, v204, 2, s90
	ds_read_b64 v[190:191], v131 offset:1560

.LBB0_679:
	v_pk_mul_f32 v[228:229], v[82:83], v[182:183]
	v_pk_mul_f32 v[222:223], v[90:91], v[186:187]
	v_pk_mul_f32 v[216:217], v[94:95], v[184:185]
	s_waitcnt lgkmcnt(0)
	v_mov_b32_dpp v190, v228 row_shr:1 row_mask:0xf bank_mask:0xf
	v_mov_b32_dpp v191, v229 row_shr:1 row_mask:0xf bank_mask:0xf
	v_mov_b32_dpp v226, v222 row_ror:15 row_mask:0xf bank_mask:0xf
	v_mov_b32_dpp v227, v223 row_ror:15 row_mask:0xf bank_mask:0xf
	v_mov_b32_dpp v230, v228 row_ror:1 row_mask:0xf bank_mask:0xf
	v_mov_b32_dpp v231, v229 row_ror:1 row_mask:0xf bank_mask:0xf
	v_pk_mul_f32 v[190:191], v[148:149], v[190:191]
	v_pk_mul_f32 v[210:211], v[86:87], v[180:181]
	v_mov_b32_dpp v218, v216 row_ror:1 row_mask:0xf bank_mask:0xf
	v_mov_b32_dpp v219, v217 row_ror:1 row_mask:0xf bank_mask:0xf
	v_mov_b32_dpp v224, v222 row_ror:1 row_mask:0xf bank_mask:0xf
	v_mov_b32_dpp v225, v223 row_ror:1 row_mask:0xf bank_mask:0xf
	v_pk_fma_f32 v[190:191], v[228:229], v[150:151], v[190:191]
	v_mov_b32_dpp v230, v222 row_shr:1 row_mask:0xf bank_mask:0xf
	v_mov_b32_dpp v226, v228 row_shl:1 row_mask:0xf bank_mask:0xf
	v_mov_b32_dpp v231, v223 row_shr:1 row_mask:0xf bank_mask:0xf
	v_mov_b32_dpp v227, v229 row_shl:1 row_mask:0xf bank_mask:0xf
	v_mov_b32_dpp v220, v216 row_ror:15 row_mask:0xf bank_mask:0xf
	v_mov_b32_dpp v221, v217 row_ror:15 row_mask:0xf bank_mask:0xf
	v_pk_fma_f32 v[190:191], v[144:145], v[226:227], v[190:191]
	v_pk_mul_f32 v[226:227], v[148:149], v[230:231]
	v_mov_b32_dpp v224, v216 row_shr:1 row_mask:0xf bank_mask:0xf
	v_mov_b32_dpp v225, v217 row_shr:1 row_mask:0xf bank_mask:0xf
	v_mov_b32_dpp v218, v210 row_shr:1 row_mask:0xf bank_mask:0xf
	v_mov_b32_dpp v219, v211 row_shr:1 row_mask:0xf bank_mask:0xf
	v_pk_add_f32 v[190:191], v[146:147], v[190:191]
	v_pk_fma_f32 v[226:227], v[222:223], v[150:151], v[226:227]
	v_mov_b32_dpp v220, v222 row_shl:1 row_mask:0xf bank_mask:0xf
	v_mov_b32_dpp v221, v223 row_shl:1 row_mask:0xf bank_mask:0xf
	v_pk_mul_f32 v[222:223], v[148:149], v[224:225]
	v_pk_mul_f32 v[148:149], v[148:149], v[218:219]
	v_pk_fma_f32 v[222:223], v[216:217], v[150:151], v[222:223]
	v_pk_fma_f32 v[148:149], v[210:211], v[150:151], v[148:149]
	v_mov_b32_dpp v214, v210 row_ror:15 row_mask:0xf bank_mask:0xf
	v_mov_b32_dpp v188, v210 row_shl:1 row_mask:0xf bank_mask:0xf
	v_mov_b32_dpp v215, v211 row_ror:15 row_mask:0xf bank_mask:0xf
	v_mov_b32_dpp v189, v211 row_shl:1 row_mask:0xf bank_mask:0xf
	v_fma_f32 v210, |v190|, s52, 1.0
	v_fma_f32 v211, |v191|, s52, 1.0
	v_mov_b32_dpp v214, v216 row_shl:1 row_mask:0xf bank_mask:0xf
	v_rcp_f32_e32 v210, v210
	v_rcp_f32_e32 v211, v211
	v_mov_b32_dpp v215, v217 row_shl:1 row_mask:0xf bank_mask:0xf
	v_pk_fma_f32 v[220:221], v[144:145], v[220:221], v[226:227]
	v_pk_fma_f32 v[214:215], v[144:145], v[214:215], v[222:223]
	v_pk_fma_f32 v[144:145], v[144:145], v[188:189], v[148:149]
	v_pk_add_f32 v[220:221], v[146:147], v[220:221]
	v_pk_add_f32 v[214:215], v[146:147], v[214:215]
	v_pk_add_f32 v[144:145], v[146:147], v[144:145]
	v_pk_mul_f32 v[188:189], v[190:191], v[190:191]
	v_pk_fma_f32 v[148:149], v[210:211], s[54:55], v[246:247] op_sel_hi:[1,0,0]
	v_pk_mul_f32 v[188:189], v[188:189], s[64:65] op_sel_hi:[1,0]
	v_pk_fma_f32 v[148:149], v[210:211], v[148:149], s[58:59] op_sel_hi:[1,1,0]
	v_exp_f32_e32 v188, v188
	v_exp_f32_e32 v189, v189
	v_pk_fma_f32 v[148:149], v[210:211], v[148:149], s[60:61] op_sel_hi:[1,1,0]
	v_max_f32_e32 v150, 0, v190
	v_pk_fma_f32 v[148:149], v[210:211], v[148:149], s[62:63] op_sel_hi:[1,1,0]
	v_max_f32_e32 v151, 0, v191
	v_pk_mul_f32 v[148:149], v[210:211], v[148:149]
	v_cmp_gt_i32_e64 s[8:9], s78, v203
	v_pk_mul_f32 v[148:149], v[188:189], v[148:149]
	v_ashrrev_i32_e32 v175, 31, v174
	v_fma_f32 v148, -|v190|, v148, v150
	v_fma_f32 v149, -|v191|, v149, v151
	v_fma_f32 v188, |v220|, s52, 1.0
	v_fma_f32 v189, |v221|, s52, 1.0
	v_pk_mul_f32 v[190:191], v[220:221], v[220:221]
	v_rcp_f32_e32 v188, v188
	v_rcp_f32_e32 v189, v189
	v_pk_mul_f32 v[248:249], v[78:79], v[148:149]
	v_pk_mul_f32 v[190:191], v[190:191], s[64:65] op_sel_hi:[1,0]
	v_pk_fma_f32 v[148:149], v[188:189], s[54:55], v[246:247] op_sel_hi:[1,0,0]
	v_exp_f32_e32 v190, v190
	v_pk_fma_f32 v[148:149], v[188:189], v[148:149], s[58:59] op_sel_hi:[1,1,0]
	v_exp_f32_e32 v191, v191
	v_pk_fma_f32 v[148:149], v[188:189], v[148:149], s[60:61] op_sel_hi:[1,1,0]
	v_pk_mul_f32 v[248:249], v[182:183], v[248:249] op_sel_hi:[0,1]
	v_pk_fma_f32 v[148:149], v[188:189], v[148:149], s[62:63] op_sel_hi:[1,1,0]
	v_pk_mul_f32 v[148:149], v[188:189], v[148:149]
	v_max_f32_e32 v188, 0, v220
	v_max_f32_e32 v189, 0, v221
	v_pk_mul_f32 v[148:149], v[190:191], v[148:149]
	v_pk_mul_f32 v[190:191], v[214:215], v[214:215]
	v_fma_f32 v148, -|v220|, v148, v188
	v_fma_f32 v149, -|v221|, v149, v189
	v_fma_f32 v188, |v214|, s52, 1.0
	v_fma_f32 v189, |v215|, s52, 1.0
	v_cvt_pk_bf16_f32 v131, v248, v249
	v_pk_mul_f32 v[248:249], v[74:75], v[148:149]
	v_rcp_f32_e32 v188, v188
	v_rcp_f32_e32 v189, v189
	v_pk_mul_f32 v[190:191], v[190:191], s[64:65] op_sel_hi:[1,0]
	v_pk_mul_f32 v[248:249], v[186:187], v[248:249] op_sel_hi:[0,1]
	v_pk_fma_f32 v[148:149], v[188:189], s[54:55], v[246:247] op_sel_hi:[1,0,0]
	v_exp_f32_e32 v190, v190
	v_pk_fma_f32 v[148:149], v[188:189], v[148:149], s[58:59] op_sel_hi:[1,1,0]
	v_exp_f32_e32 v191, v191
	v_pk_fma_f32 v[148:149], v[188:189], v[148:149], s[60:61] op_sel_hi:[1,1,0]
	v_pk_fma_f32 v[148:149], v[188:189], v[148:149], s[62:63] op_sel_hi:[1,1,0]
	v_cvt_pk_bf16_f32 v135, v248, v249
	s_nop 0
	v_pk_mul_f32 v[148:149], v[188:189], v[148:149]
	v_max_f32_e32 v188, 0, v214
	v_max_f32_e32 v189, 0, v215
	v_pk_mul_f32 v[148:149], v[190:191], v[148:149]
	s_nop 0
	v_fma_f32 v148, -|v214|, v148, v188
	v_fma_f32 v149, -|v215|, v149, v189
	v_fma_f32 v188, |v144|, s52, 1.0
	v_fma_f32 v189, |v145|, s52, 1.0
	v_pk_mul_f32 v[248:249], v[70:71], v[148:149]
	v_rcp_f32_e32 v188, v188
	v_rcp_f32_e32 v189, v189
	v_pk_mul_f32 v[148:149], v[144:145], v[144:145]
	v_max_f32_e32 v150, 0, v144
	v_pk_fma_f32 v[146:147], v[188:189], s[54:55], v[246:247] op_sel_hi:[1,0,0]
	v_pk_mul_f32 v[148:149], v[148:149], s[64:65] op_sel_hi:[1,0]
	v_pk_fma_f32 v[146:147], v[188:189], v[146:147], s[58:59] op_sel_hi:[1,1,0]
	v_exp_f32_e32 v148, v148
	v_exp_f32_e32 v149, v149
	v_pk_fma_f32 v[146:147], v[188:189], v[146:147], s[60:61] op_sel_hi:[1,1,0]
	v_max_f32_e32 v151, 0, v145
	v_pk_fma_f32 v[146:147], v[188:189], v[146:147], s[62:63] op_sel_hi:[1,1,0]
	v_pk_mul_f32 v[248:249], v[184:185], v[248:249] op_sel_hi:[0,1]
	v_pk_mul_f32 v[146:147], v[188:189], v[146:147]
	v_pk_mul_f32 v[146:147], v[148:149], v[146:147]
	v_cvt_pk_bf16_f32 v139, v248, v249
	s_nop 0
	v_fma_f32 v144, -|v144|, v146, v150
	v_fma_f32 v145, -|v145|, v147, v151
	s_nop 0
	v_pk_mul_f32 v[144:145], v[66:67], v[144:145]
	v_pk_mul_f32 v[144:145], v[180:181], v[144:145] op_sel_hi:[0,1]
	v_cvt_pk_bf16_f32 v143, v144, v145
	v_add_u32_e32 v144, -1, v202
	v_cmp_gt_u32_e32 vcc, s76, v144
	s_and_b64 s[10:11], vcc, s[8:9]
	s_and_saveexec_b64 s[8:9], s[10:11]
	s_cbranch_execz .LBB0_681
	v_mov_b64_e32 v[144:145], s[38:39]
	v_mad_i64_i32 v[144:145], s[10:11], v203, s31, v[144:145]
	v_lshl_add_u64 v[144:145], v[174:175], 1, v[144:145]
	global_store_dwordx4 v[144:145], v[128:131], off

.LBB0_691:
	v_pk_mul_f32 v[210:211], v[48:49], v[172:173] op_sel_hi:[1,0]
	v_pk_mul_f32 v[150:151], v[52:53], v[178:179] op_sel_hi:[1,0]
	v_pk_mul_f32 v[144:145], v[60:61], v[176:177] op_sel_hi:[1,0]
	s_waitcnt lgkmcnt(0)
	v_mov_b32_dpp v138, v210 row_shr:1 row_mask:0xf bank_mask:0xf
	v_mov_b32_dpp v139, v211 row_shr:1 row_mask:0xf bank_mask:0xf
	v_mov_b32_dpp v190, v150 row_ror:15 row_mask:0xf bank_mask:0xf
	v_mov_b32_dpp v191, v151 row_ror:15 row_mask:0xf bank_mask:0xf
	v_mov_b32_dpp v214, v210 row_ror:1 row_mask:0xf bank_mask:0xf
	v_mov_b32_dpp v215, v211 row_ror:1 row_mask:0xf bank_mask:0xf
	v_pk_mul_f32 v[138:139], v[134:135], v[138:139]
	v_pk_mul_f32 v[140:141], v[56:57], v[170:171] op_sel_hi:[1,0]
	v_mov_b32_dpp v146, v144 row_ror:1 row_mask:0xf bank_mask:0xf
	v_mov_b32_dpp v147, v145 row_ror:1 row_mask:0xf bank_mask:0xf
	v_mov_b32_dpp v188, v150 row_ror:1 row_mask:0xf bank_mask:0xf
	v_mov_b32_dpp v189, v151 row_ror:1 row_mask:0xf bank_mask:0xf
	v_pk_fma_f32 v[138:139], v[210:211], v[136:137], v[138:139]
	v_mov_b32_dpp v214, v150 row_shr:1 row_mask:0xf bank_mask:0xf
	v_mov_b32_dpp v190, v210 row_shl:1 row_mask:0xf bank_mask:0xf
	v_mov_b32_dpp v215, v151 row_shr:1 row_mask:0xf bank_mask:0xf
	v_mov_b32_dpp v191, v211 row_shl:1 row_mask:0xf bank_mask:0xf
	v_mov_b32_dpp v148, v144 row_ror:15 row_mask:0xf bank_mask:0xf
	v_mov_b32_dpp v149, v145 row_ror:15 row_mask:0xf bank_mask:0xf
	v_pk_fma_f32 v[138:139], v[128:129], v[190:191], v[138:139]
	v_pk_mul_f32 v[190:191], v[134:135], v[214:215]
	v_mov_b32_dpp v188, v144 row_shr:1 row_mask:0xf bank_mask:0xf
	v_mov_b32_dpp v189, v145 row_shr:1 row_mask:0xf bank_mask:0xf
	v_mov_b32_dpp v146, v140 row_shr:1 row_mask:0xf bank_mask:0xf
	v_mov_b32_dpp v147, v141 row_shr:1 row_mask:0xf bank_mask:0xf
	v_pk_add_f32 v[138:139], v[130:131], v[138:139]
	v_pk_fma_f32 v[190:191], v[150:151], v[136:137], v[190:191]
	v_mov_b32_dpp v148, v150 row_shl:1 row_mask:0xf bank_mask:0xf
	v_mov_b32_dpp v149, v151 row_shl:1 row_mask:0xf bank_mask:0xf
	v_pk_mul_f32 v[150:151], v[134:135], v[188:189]
	v_pk_mul_f32 v[134:135], v[134:135], v[146:147]
	v_pk_fma_f32 v[150:151], v[144:145], v[136:137], v[150:151]
	v_pk_fma_f32 v[134:135], v[140:141], v[136:137], v[134:135]
	v_mov_b32_dpp v142, v140 row_ror:15 row_mask:0xf bank_mask:0xf
	v_mov_b32_dpp v132, v140 row_shl:1 row_mask:0xf bank_mask:0xf
	v_mov_b32_dpp v143, v141 row_ror:15 row_mask:0xf bank_mask:0xf
	v_mov_b32_dpp v133, v141 row_shl:1 row_mask:0xf bank_mask:0xf
	v_fma_f32 v140, |v138|, s52, 1.0
	v_fma_f32 v141, |v139|, s52, 1.0
	v_mov_b32_dpp v142, v144 row_shl:1 row_mask:0xf bank_mask:0xf
	v_rcp_f32_e32 v140, v140
	v_rcp_f32_e32 v141, v141
	v_mov_b32_dpp v143, v145 row_shl:1 row_mask:0xf bank_mask:0xf
	v_pk_fma_f32 v[148:149], v[128:129], v[148:149], v[190:191]
	v_pk_fma_f32 v[142:143], v[128:129], v[142:143], v[150:151]
	v_pk_fma_f32 v[128:129], v[128:129], v[132:133], v[134:135]
	v_pk_add_f32 v[148:149], v[130:131], v[148:149]
	v_pk_add_f32 v[142:143], v[130:131], v[142:143]
	v_pk_add_f32 v[128:129], v[130:131], v[128:129]
	v_pk_mul_f32 v[134:135], v[138:139], v[138:139]
	v_pk_fma_f32 v[132:133], v[140:141], s[54:55], v[246:247] op_sel_hi:[1,0,0]
	v_pk_mul_f32 v[134:135], v[134:135], s[64:65] op_sel_hi:[1,0]
	v_pk_fma_f32 v[132:133], v[140:141], v[132:133], s[58:59] op_sel_hi:[1,1,0]
	v_exp_f32_e32 v134, v134
	v_exp_f32_e32 v135, v135
	v_pk_fma_f32 v[132:133], v[140:141], v[132:133], s[60:61] op_sel_hi:[1,1,0]
	v_max_f32_e32 v136, 0, v138
	v_pk_fma_f32 v[132:133], v[140:141], v[132:133], s[62:63] op_sel_hi:[1,1,0]
	v_max_f32_e32 v137, 0, v139
	v_pk_mul_f32 v[132:133], v[140:141], v[132:133]
	v_pk_mul_f32 v[140:141], v[148:149], v[148:149]
	v_pk_mul_f32 v[132:133], v[134:135], v[132:133]
	v_fma_f32 v132, -|v138|, v132, v136
	v_fma_f32 v133, -|v139|, v133, v137
	v_fma_f32 v136, |v148|, s52, 1.0
	v_fma_f32 v137, |v149|, s52, 1.0
	v_pk_mul_f32 v[140:141], v[140:141], s[64:65] op_sel_hi:[1,0]
	v_rcp_f32_e32 v136, v136
	v_rcp_f32_e32 v137, v137
	v_exp_f32_e32 v140, v140
	v_exp_f32_e32 v141, v141
	v_pk_fma_f32 v[138:139], v[136:137], s[54:55], v[246:247] op_sel_hi:[1,0,0]
	v_pk_mul_f32 v[132:133], v[44:45], v[132:133]
	v_pk_fma_f32 v[138:139], v[136:137], v[138:139], s[58:59] op_sel_hi:[1,1,0]
	v_pk_fma_f32 v[138:139], v[136:137], v[138:139], s[60:61] op_sel_hi:[1,1,0]
	v_pk_mul_f32 v[132:133], v[172:173], v[132:133] op_sel_hi:[0,1]
	v_pk_fma_f32 v[138:139], v[136:137], v[138:139], s[62:63] op_sel_hi:[1,1,0]
	v_cvt_pk_bf16_f32 v132, v132, v133
	v_pk_mul_f32 v[144:145], v[142:143], v[142:143]
	v_pk_mul_f32 v[136:137], v[136:137], v[138:139]
	v_max_f32_e32 v138, 0, v148
	v_max_f32_e32 v139, 0, v149
	v_pk_mul_f32 v[136:137], v[140:141], v[136:137]
	v_pk_mul_f32 v[144:145], v[144:145], s[64:65] op_sel_hi:[1,0]
	v_fma_f32 v134, -|v148|, v136, v138
	v_fma_f32 v135, -|v149|, v137, v139
	v_fma_f32 v136, |v142|, s52, 1.0
	v_fma_f32 v137, |v143|, s52, 1.0
	v_rcp_f32_e32 v140, v136
	v_rcp_f32_e32 v141, v137
	v_pk_mul_f32 v[134:135], v[40:41], v[134:135]
	v_pk_mul_f32 v[134:135], v[178:179], v[134:135] op_sel_hi:[0,1]
	v_cvt_pk_bf16_f32 v136, v134, v135
	v_pk_fma_f32 v[134:135], v[140:141], s[54:55], v[246:247] op_sel_hi:[1,0,0]
	v_exp_f32_e32 v144, v144
	v_pk_fma_f32 v[134:135], v[140:141], v[134:135], s[58:59] op_sel_hi:[1,1,0]
	v_exp_f32_e32 v145, v145
	v_pk_fma_f32 v[134:135], v[140:141], v[134:135], s[60:61] op_sel_hi:[1,1,0]
	s_and_b64 vcc, exec, s[8:9]
	v_pk_fma_f32 v[134:135], v[140:141], v[134:135], s[62:63] op_sel_hi:[1,1,0]
	s_nop 0
	v_pk_mul_f32 v[134:135], v[140:141], v[134:135]
	v_max_f32_e32 v140, 0, v142
	v_max_f32_e32 v141, 0, v143
	v_pk_mul_f32 v[134:135], v[144:145], v[134:135]
	s_nop 0
	v_fma_f32 v134, -|v142|, v134, v140
	v_fma_f32 v135, -|v143|, v135, v141
	v_fma_f32 v140, |v128|, s52, 1.0
	v_fma_f32 v141, |v129|, s52, 1.0
	v_rcp_f32_e32 v142, v140
	v_rcp_f32_e32 v143, v141
	v_pk_mul_f32 v[134:135], v[36:37], v[134:135]
	v_pk_mul_f32 v[134:135], v[176:177], v[134:135] op_sel_hi:[0,1]
	v_cvt_pk_bf16_f32 v140, v134, v135
	v_pk_mul_f32 v[134:135], v[128:129], v[128:129]
	v_pk_fma_f32 v[130:131], v[142:143], s[54:55], v[246:247] op_sel_hi:[1,0,0]
	v_pk_mul_f32 v[134:135], v[134:135], s[64:65] op_sel_hi:[1,0]
	v_pk_fma_f32 v[130:131], v[142:143], v[130:131], s[58:59] op_sel_hi:[1,1,0]
	v_exp_f32_e32 v134, v134
	v_exp_f32_e32 v135, v135
	v_pk_fma_f32 v[130:131], v[142:143], v[130:131], s[60:61] op_sel_hi:[1,1,0]
	v_max_f32_e32 v138, 0, v128
	v_pk_fma_f32 v[130:131], v[142:143], v[130:131], s[62:63] op_sel_hi:[1,1,0]
	v_max_f32_e32 v139, 0, v129
	v_pk_mul_f32 v[130:131], v[142:143], v[130:131]
	s_nop 0
	v_pk_mul_f32 v[130:131], v[134:135], v[130:131]
	v_mov_b32_e32 v134, 0
	v_fma_f32 v128, -|v128|, v130, v138
	v_fma_f32 v129, -|v129|, v131, v139
	v_mov_b32_e32 v130, 0
	v_mul_f32_e32 v128, v32, v128
	v_mul_f32_e32 v128, v170, v128
	v_mul_f32_e32 v129, v33, v129
	v_mul_f32_e32 v129, v170, v129
	v_cvt_pk_bf16_f32 v128, v128, v129
	ds_read2st64_b64 v[146:149], v207 offset0:10 offset1:11
	ds_read2st64_b64 v[142:145], v207 offset0:12 offset1:13
	v_mov_b32_e32 v135, 0
	s_cbranch_vccnz .LBB0_693
	v_add_u32_e32 v129, s87, v206
	ds_read_b64 v[134:135], v129 offset:1544

.LBB0_695:
	v_mov_b32_e32 v173, v172
	v_mov_b32_e32 v179, v178
	v_pk_mul_f32 v[220:221], v[50:51], v[172:173]
	v_mov_b32_e32 v177, v176
	v_pk_mul_f32 v[214:215], v[54:55], v[178:179]
	s_waitcnt lgkmcnt(0)
	v_mov_b32_dpp v134, v220 row_shr:1 row_mask:0xf bank_mask:0xf
	v_mov_b32_dpp v135, v221 row_shr:1 row_mask:0xf bank_mask:0xf
	v_mov_b32_e32 v171, v170
	v_pk_mul_f32 v[188:189], v[62:63], v[176:177]
	v_mov_b32_dpp v218, v214 row_ror:15 row_mask:0xf bank_mask:0xf
	v_mov_b32_dpp v219, v215 row_ror:15 row_mask:0xf bank_mask:0xf
	v_mov_b32_dpp v222, v220 row_ror:1 row_mask:0xf bank_mask:0xf
	v_mov_b32_dpp v223, v221 row_ror:1 row_mask:0xf bank_mask:0xf
	v_pk_mul_f32 v[134:135], v[146:147], v[134:135]
	v_pk_mul_f32 v[138:139], v[58:59], v[170:171]
	v_mov_b32_dpp v190, v188 row_ror:1 row_mask:0xf bank_mask:0xf
	v_mov_b32_dpp v191, v189 row_ror:1 row_mask:0xf bank_mask:0xf
	v_mov_b32_dpp v216, v214 row_ror:1 row_mask:0xf bank_mask:0xf
	v_mov_b32_dpp v217, v215 row_ror:1 row_mask:0xf bank_mask:0xf
	v_pk_fma_f32 v[134:135], v[220:221], v[148:149], v[134:135]
	v_mov_b32_dpp v222, v214 row_shr:1 row_mask:0xf bank_mask:0xf
	v_mov_b32_dpp v218, v220 row_shl:1 row_mask:0xf bank_mask:0xf
	v_mov_b32_dpp v223, v215 row_shr:1 row_mask:0xf bank_mask:0xf
	v_mov_b32_dpp v219, v221 row_shl:1 row_mask:0xf bank_mask:0xf
	v_mov_b32_dpp v210, v188 row_ror:15 row_mask:0xf bank_mask:0xf
	v_mov_b32_dpp v211, v189 row_ror:15 row_mask:0xf bank_mask:0xf
	v_pk_fma_f32 v[134:135], v[142:143], v[218:219], v[134:135]
	v_pk_mul_f32 v[218:219], v[146:147], v[222:223]
	v_mov_b32_dpp v216, v188 row_shr:1 row_mask:0xf bank_mask:0xf
	v_mov_b32_dpp v217, v189 row_shr:1 row_mask:0xf bank_mask:0xf
	v_mov_b32_dpp v190, v138 row_shr:1 row_mask:0xf bank_mask:0xf
	v_mov_b32_dpp v191, v139 row_shr:1 row_mask:0xf bank_mask:0xf
	v_pk_add_f32 v[134:135], v[144:145], v[134:135]
	v_pk_fma_f32 v[218:219], v[214:215], v[148:149], v[218:219]
	v_mov_b32_dpp v210, v214 row_shl:1 row_mask:0xf bank_mask:0xf
	v_mov_b32_dpp v211, v215 row_shl:1 row_mask:0xf bank_mask:0xf
	v_pk_mul_f32 v[214:215], v[146:147], v[216:217]
	v_pk_mul_f32 v[146:147], v[146:147], v[190:191]
	v_mov_b32_dpp v150, v138 row_ror:15 row_mask:0xf bank_mask:0xf
	v_mov_b32_dpp v130, v138 row_shl:1 row_mask:0xf bank_mask:0xf
	v_mov_b32_dpp v151, v139 row_ror:15 row_mask:0xf bank_mask:0xf
	v_mov_b32_dpp v131, v139 row_shl:1 row_mask:0xf bank_mask:0xf
	v_pk_fma_f32 v[138:139], v[138:139], v[148:149], v[146:147]
	v_pk_fma_f32 v[214:215], v[188:189], v[148:149], v[214:215]
	v_fma_f32 v148, |v134|, s52, 1.0
	v_fma_f32 v149, |v135|, s52, 1.0
	v_mov_b32_dpp v150, v188 row_shl:1 row_mask:0xf bank_mask:0xf
	v_rcp_f32_e32 v148, v148
	v_rcp_f32_e32 v149, v149
	v_mov_b32_dpp v151, v189 row_shl:1 row_mask:0xf bank_mask:0xf
	v_pk_fma_f32 v[210:211], v[142:143], v[210:211], v[218:219]
	v_pk_fma_f32 v[150:151], v[142:143], v[150:151], v[214:215]
	v_pk_fma_f32 v[130:131], v[142:143], v[130:131], v[138:139]
	v_pk_add_f32 v[210:211], v[144:145], v[210:211]
	v_pk_add_f32 v[150:151], v[144:145], v[150:151]
	v_pk_add_f32 v[130:131], v[144:145], v[130:131]
	v_pk_mul_f32 v[144:145], v[134:135], v[134:135]
	v_pk_fma_f32 v[142:143], v[148:149], s[54:55], v[246:247] op_sel_hi:[1,0,0]
	v_pk_mul_f32 v[144:145], v[144:145], s[64:65] op_sel_hi:[1,0]
	v_pk_fma_f32 v[142:143], v[148:149], v[142:143], s[58:59] op_sel_hi:[1,1,0]
	v_exp_f32_e32 v144, v144
	v_exp_f32_e32 v145, v145
	v_pk_fma_f32 v[142:143], v[148:149], v[142:143], s[60:61] op_sel_hi:[1,1,0]
	v_max_f32_e32 v146, 0, v134
	v_pk_fma_f32 v[142:143], v[148:149], v[142:143], s[62:63] op_sel_hi:[1,1,0]
	v_max_f32_e32 v147, 0, v135
	v_pk_mul_f32 v[142:143], v[148:149], v[142:143]
	s_and_b64 vcc, exec, s[8:9]
	v_pk_mul_f32 v[142:143], v[144:145], v[142:143]
	s_nop 0
	v_fma_f32 v134, -|v134|, v142, v146
	v_fma_f32 v135, -|v135|, v143, v147
	v_fma_f32 v144, |v210|, s52, 1.0
	v_fma_f32 v145, |v211|, s52, 1.0
	v_pk_mul_f32 v[146:147], v[210:211], v[210:211]
	v_rcp_f32_e32 v144, v144
	v_rcp_f32_e32 v145, v145
	v_pk_mul_f32 v[248:249], v[46:47], v[134:135]
	v_pk_mul_f32 v[146:147], v[146:147], s[64:65] op_sel_hi:[1,0]
	v_pk_fma_f32 v[134:135], v[144:145], s[54:55], v[246:247] op_sel_hi:[1,0,0]
	v_exp_f32_e32 v146, v146
	v_pk_fma_f32 v[134:135], v[144:145], v[134:135], s[58:59] op_sel_hi:[1,1,0]
	v_exp_f32_e32 v147, v147
	v_pk_fma_f32 v[134:135], v[144:145], v[134:135], s[60:61] op_sel_hi:[1,1,0]
	v_pk_mul_f32 v[248:249], v[172:173], v[248:249] op_sel_hi:[0,1]
	v_pk_fma_f32 v[134:135], v[144:145], v[134:135], s[62:63] op_sel_hi:[1,1,0]
	v_pk_mul_f32 v[134:135], v[144:145], v[134:135]
	v_max_f32_e32 v144, 0, v210
	v_max_f32_e32 v145, 0, v211
	v_pk_mul_f32 v[134:135], v[146:147], v[134:135]
	v_cvt_pk_bf16_f32 v133, v248, v249
	v_pk_mul_f32 v[146:147], v[150:151], v[150:151]
	v_fma_f32 v134, -|v210|, v134, v144
	v_fma_f32 v135, -|v211|, v135, v145
	v_fma_f32 v144, |v150|, s52, 1.0
	v_fma_f32 v145, |v151|, s52, 1.0
	v_rcp_f32_e32 v144, v144
	v_rcp_f32_e32 v145, v145
	v_pk_mul_f32 v[134:135], v[42:43], v[134:135]
	v_pk_mul_f32 v[134:135], v[178:179], v[134:135] op_sel_hi:[0,1]
	v_cvt_pk_bf16_f32 v137, v134, v135
	v_pk_fma_f32 v[134:135], v[144:145], s[54:55], v[246:247] op_sel_hi:[1,0,0]
	v_pk_mul_f32 v[146:147], v[146:147], s[64:65] op_sel_hi:[1,0]
	v_pk_fma_f32 v[134:135], v[144:145], v[134:135], s[58:59] op_sel_hi:[1,1,0]
	v_exp_f32_e32 v146, v146
	v_exp_f32_e32 v147, v147
	v_pk_fma_f32 v[134:135], v[144:145], v[134:135], s[60:61] op_sel_hi:[1,1,0]
	s_nop 0
	v_pk_fma_f32 v[134:135], v[144:145], v[134:135], s[62:63] op_sel_hi:[1,1,0]
	s_nop 0
	v_pk_mul_f32 v[134:135], v[144:145], v[134:135]
	v_max_f32_e32 v144, 0, v150
	v_max_f32_e32 v145, 0, v151
	v_pk_mul_f32 v[134:135], v[146:147], v[134:135]
	s_nop 0
	v_fma_f32 v134, -|v150|, v134, v144
	v_fma_f32 v135, -|v151|, v135, v145
	v_fma_f32 v144, |v130|, s52, 1.0
	v_fma_f32 v145, |v131|, s52, 1.0
	v_rcp_f32_e32 v144, v144
	v_rcp_f32_e32 v145, v145
	v_pk_mul_f32 v[134:135], v[38:39], v[134:135]
	v_pk_mul_f32 v[134:135], v[176:177], v[134:135] op_sel_hi:[0,1]
	v_cvt_pk_bf16_f32 v141, v134, v135
	v_pk_fma_f32 v[134:135], v[144:145], s[54:55], v[246:247] op_sel_hi:[1,0,0]
	v_pk_mul_f32 v[138:139], v[130:131], v[130:131]
	v_pk_fma_f32 v[134:135], v[144:145], v[134:135], s[58:59] op_sel_hi:[1,1,0]
	v_pk_mul_f32 v[138:139], v[138:139], s[64:65] op_sel_hi:[1,0]
	v_pk_fma_f32 v[134:135], v[144:145], v[134:135], s[60:61] op_sel_hi:[1,1,0]
	v_exp_f32_e32 v138, v138
	v_exp_f32_e32 v139, v139
	v_pk_fma_f32 v[134:135], v[144:145], v[134:135], s[62:63] op_sel_hi:[1,1,0]
	v_max_f32_e32 v142, 0, v130
	v_pk_mul_f32 v[134:135], v[144:145], v[134:135]
	v_max_f32_e32 v143, 0, v131
	v_pk_mul_f32 v[134:135], v[138:139], v[134:135]
	s_nop 0
	v_fma_f32 v130, -|v130|, v134, v142
	v_fma_f32 v131, -|v131|, v135, v143
	v_mov_b32_e32 v134, 0
	v_mul_f32_e32 v129, v34, v130
	v_mul_f32_e32 v129, v170, v129
	v_mul_f32_e32 v130, v35, v131
	v_mul_f32_e32 v130, v170, v130
	v_cvt_pk_bf16_f32 v129, v129, v130
	ds_read2st64_b64 v[146:149], v208 offset0:10 offset1:11
	ds_read2st64_b64 v[142:145], v208 offset0:12 offset1:13
	v_mov_b32_e32 v130, 0
	v_mov_b32_e32 v135, 0
	s_cbranch_vccnz .LBB0_697
	v_add_u32_e32 v131, s87, v206
	ds_read_b64 v[134:135], v131 offset:1552

.LBB0_699:
	v_pk_mul_f32 v[220:221], v[16:17], v[172:173]
	v_pk_mul_f32 v[214:215], v[24:25], v[178:179]
	v_pk_mul_f32 v[188:189], v[28:29], v[176:177]
	s_waitcnt lgkmcnt(0)
	v_mov_b32_dpp v134, v220 row_shr:1 row_mask:0xf bank_mask:0xf
	v_mov_b32_dpp v135, v221 row_shr:1 row_mask:0xf bank_mask:0xf
	v_mov_b32_dpp v218, v214 row_ror:15 row_mask:0xf bank_mask:0xf
	v_mov_b32_dpp v219, v215 row_ror:15 row_mask:0xf bank_mask:0xf
	v_mov_b32_dpp v222, v220 row_ror:1 row_mask:0xf bank_mask:0xf
	v_mov_b32_dpp v223, v221 row_ror:1 row_mask:0xf bank_mask:0xf
	v_pk_mul_f32 v[134:135], v[146:147], v[134:135]
	v_pk_mul_f32 v[138:139], v[20:21], v[170:171]
	v_mov_b32_dpp v190, v188 row_ror:1 row_mask:0xf bank_mask:0xf
	v_mov_b32_dpp v191, v189 row_ror:1 row_mask:0xf bank_mask:0xf
	v_mov_b32_dpp v216, v214 row_ror:1 row_mask:0xf bank_mask:0xf
	v_mov_b32_dpp v217, v215 row_ror:1 row_mask:0xf bank_mask:0xf
	v_pk_fma_f32 v[134:135], v[220:221], v[148:149], v[134:135]
	v_mov_b32_dpp v222, v214 row_shr:1 row_mask:0xf bank_mask:0xf
	v_mov_b32_dpp v218, v220 row_shl:1 row_mask:0xf bank_mask:0xf
	v_mov_b32_dpp v223, v215 row_shr:1 row_mask:0xf bank_mask:0xf
	v_mov_b32_dpp v219, v221 row_shl:1 row_mask:0xf bank_mask:0xf
	v_mov_b32_dpp v210, v188 row_ror:15 row_mask:0xf bank_mask:0xf
	v_mov_b32_dpp v211, v189 row_ror:15 row_mask:0xf bank_mask:0xf
	v_pk_fma_f32 v[134:135], v[142:143], v[218:219], v[134:135]
	v_pk_mul_f32 v[218:219], v[146:147], v[222:223]
	v_mov_b32_dpp v216, v188 row_shr:1 row_mask:0xf bank_mask:0xf
	v_mov_b32_dpp v217, v189 row_shr:1 row_mask:0xf bank_mask:0xf
	v_mov_b32_dpp v190, v138 row_shr:1 row_mask:0xf bank_mask:0xf
	v_mov_b32_dpp v191, v139 row_shr:1 row_mask:0xf bank_mask:0xf
	v_pk_add_f32 v[134:135], v[144:145], v[134:135]
	v_pk_fma_f32 v[218:219], v[214:215], v[148:149], v[218:219]
	v_mov_b32_dpp v210, v214 row_shl:1 row_mask:0xf bank_mask:0xf
	v_mov_b32_dpp v211, v215 row_shl:1 row_mask:0xf bank_mask:0xf
	v_pk_mul_f32 v[214:215], v[146:147], v[216:217]
	v_pk_mul_f32 v[146:147], v[146:147], v[190:191]
	v_mov_b32_dpp v150, v138 row_ror:15 row_mask:0xf bank_mask:0xf
	v_mov_b32_dpp v130, v138 row_shl:1 row_mask:0xf bank_mask:0xf
	v_mov_b32_dpp v151, v139 row_ror:15 row_mask:0xf bank_mask:0xf
	v_mov_b32_dpp v131, v139 row_shl:1 row_mask:0xf bank_mask:0xf
	v_pk_fma_f32 v[138:139], v[138:139], v[148:149], v[146:147]
	v_pk_fma_f32 v[214:215], v[188:189], v[148:149], v[214:215]
	v_fma_f32 v148, |v134|, s52, 1.0
	v_fma_f32 v149, |v135|, s52, 1.0
	v_mov_b32_dpp v150, v188 row_shl:1 row_mask:0xf bank_mask:0xf
	v_rcp_f32_e32 v148, v148
	v_rcp_f32_e32 v149, v149
	v_mov_b32_dpp v151, v189 row_shl:1 row_mask:0xf bank_mask:0xf
	v_pk_fma_f32 v[210:211], v[142:143], v[210:211], v[218:219]
	v_pk_fma_f32 v[150:151], v[142:143], v[150:151], v[214:215]
	v_pk_fma_f32 v[130:131], v[142:143], v[130:131], v[138:139]
	v_pk_add_f32 v[210:211], v[144:145], v[210:211]
	v_pk_add_f32 v[150:151], v[144:145], v[150:151]
	v_pk_add_f32 v[130:131], v[144:145], v[130:131]
	v_pk_mul_f32 v[142:143], v[134:135], v[134:135]
	v_pk_fma_f32 v[138:139], v[148:149], s[54:55], v[246:247] op_sel_hi:[1,0,0]
	v_pk_mul_f32 v[142:143], v[142:143], s[64:65] op_sel_hi:[1,0]
	v_pk_fma_f32 v[138:139], v[148:149], v[138:139], s[58:59] op_sel_hi:[1,1,0]
	v_exp_f32_e32 v142, v142
	v_exp_f32_e32 v143, v143
	v_pk_fma_f32 v[138:139], v[148:149], v[138:139], s[60:61] op_sel_hi:[1,1,0]
	v_max_f32_e32 v146, 0, v134
	v_pk_fma_f32 v[138:139], v[148:149], v[138:139], s[62:63] op_sel_hi:[1,1,0]
	v_max_f32_e32 v147, 0, v135
	v_pk_mul_f32 v[138:139], v[148:149], v[138:139]
	v_pk_mul_f32 v[148:149], v[210:211], v[210:211]
	v_pk_mul_f32 v[138:139], v[142:143], v[138:139]
	v_pk_mul_f32 v[148:149], v[148:149], s[64:65] op_sel_hi:[1,0]
	v_fma_f32 v134, -|v134|, v138, v146
	v_fma_f32 v135, -|v135|, v139, v147
	v_fma_f32 v142, |v210|, s52, 1.0
	v_fma_f32 v143, |v211|, s52, 1.0
	v_exp_f32_e32 v148, v148
	v_rcp_f32_e32 v142, v142
	v_rcp_f32_e32 v143, v143
	v_exp_f32_e32 v149, v149
	v_pk_mul_f32 v[188:189], v[150:151], v[150:151]
	v_pk_fma_f32 v[146:147], v[142:143], s[54:55], v[246:247] op_sel_hi:[1,0,0]
	v_pk_mul_f32 v[188:189], v[188:189], s[64:65] op_sel_hi:[1,0]
	v_pk_fma_f32 v[146:147], v[142:143], v[146:147], s[58:59] op_sel_hi:[1,1,0]
	v_exp_f32_e32 v188, v188
	v_pk_fma_f32 v[146:147], v[142:143], v[146:147], s[60:61] op_sel_hi:[1,1,0]
	v_exp_f32_e32 v189, v189
	v_pk_fma_f32 v[146:147], v[142:143], v[146:147], s[62:63] op_sel_hi:[1,1,0]
	v_pk_mul_f32 v[134:135], v[12:13], v[134:135]
	v_pk_mul_f32 v[142:143], v[142:143], v[146:147]
	v_max_f32_e32 v146, 0, v210
	v_max_f32_e32 v147, 0, v211
	v_pk_mul_f32 v[142:143], v[148:149], v[142:143]
	v_fma_f32 v138, -|v210|, v142, v146
	v_fma_f32 v139, -|v211|, v143, v147
	v_and_b32_e32 v143, 0x7fffffff, v151
	v_and_b32_e32 v142, 0x7fffffff, v150
	v_pk_fma_f32 v[146:147], v[142:143], s[52:53], 1.0 op_sel_hi:[1,0,0]
	v_pk_mul_f32 v[134:135], v[172:173], v[134:135] op_sel_hi:[0,1]
	v_rcp_f32_e32 v146, v146
	v_rcp_f32_e32 v147, v147
	v_cvt_pk_bf16_f32 v134, v134, v135
	v_pk_mul_f32 v[138:139], v[8:9], v[138:139]
	v_pk_fma_f32 v[148:149], v[146:147], s[54:55], v[246:247] op_sel_hi:[1,0,0]
	v_pk_fma_f32 v[148:149], v[146:147], v[148:149], s[58:59] op_sel_hi:[1,1,0]
	v_pk_mul_f32 v[138:139], v[178:179], v[138:139] op_sel_hi:[0,1]
	v_pk_fma_f32 v[148:149], v[146:147], v[148:149], s[60:61] op_sel_hi:[1,1,0]
	v_cvt_pk_bf16_f32 v138, v138, v139
	s_and_b64 vcc, exec, s[8:9]
	v_pk_fma_f32 v[148:149], v[146:147], v[148:149], s[62:63] op_sel_hi:[1,1,0]
	v_mov_b32_e32 v190, 0
	v_pk_mul_f32 v[146:147], v[146:147], v[148:149]
	v_max_f32_e32 v148, 0, v150
	v_max_f32_e32 v149, 0, v151
	v_pk_mul_f32 v[146:147], v[188:189], v[146:147]
	v_pk_mul_f32 v[150:151], v[130:131], v[130:131]
	v_pk_fma_f32 v[142:143], v[142:143], v[146:147], v[148:149] neg_lo:[1,0,0] neg_hi:[1,0,0]
	v_fma_f32 v148, |v130|, s52, 1.0
	v_fma_f32 v149, |v131|, s52, 1.0
	v_pk_mul_f32 v[150:151], v[150:151], s[64:65] op_sel_hi:[1,0]
	v_rcp_f32_e32 v148, v148
	v_rcp_f32_e32 v149, v149
	v_exp_f32_e32 v150, v150
	v_exp_f32_e32 v151, v151
	v_max_f32_e32 v146, 0, v130
	v_pk_fma_f32 v[144:145], v[148:149], s[54:55], v[246:247] op_sel_hi:[1,0,0]
	v_max_f32_e32 v147, 0, v131
	v_pk_fma_f32 v[144:145], v[148:149], v[144:145], s[58:59] op_sel_hi:[1,1,0]
	v_pk_fma_f32 v[144:145], v[148:149], v[144:145], s[60:61] op_sel_hi:[1,1,0]
	v_pk_mul_f32 v[142:143], v[4:5], v[142:143]
	v_pk_fma_f32 v[144:145], v[148:149], v[144:145], s[62:63] op_sel_hi:[1,1,0]
	v_pk_mul_f32 v[144:145], v[148:149], v[144:145]
	v_pk_mul_f32 v[142:143], v[176:177], v[142:143] op_sel_hi:[0,1]
	v_pk_mul_f32 v[144:145], v[150:151], v[144:145]
	v_cvt_pk_bf16_f32 v142, v142, v143
	v_mov_b32_e32 v188, 0
	v_fma_f32 v130, -|v130|, v144, v146
	v_fma_f32 v131, -|v131|, v145, v147
	v_mov_b32_e32 v191, 0
	v_mul_f32_e32 v130, v0, v130
	v_mul_f32_e32 v130, v170, v130
	v_mul_f32_e32 v131, v1, v131
	v_mul_f32_e32 v131, v170, v131
	v_cvt_pk_bf16_f32 v130, v130, v131
	ds_read2st64_b64 v[148:151], v209 offset0:10 offset1:11
	ds_read2st64_b64 v[144:147], v209 offset0:12 offset1:13
	s_cbranch_vccnz .LBB0_701
	v_add_u32_e32 v131, s87, v206
	ds_read_b64 v[190:191], v131 offset:1560

.LBB0_703:
	v_pk_mul_f32 v[224:225], v[18:19], v[172:173]
	v_pk_mul_f32 v[218:219], v[26:27], v[178:179]
	v_pk_mul_f32 v[210:211], v[30:31], v[176:177]
	s_waitcnt lgkmcnt(0)
	v_mov_b32_dpp v190, v224 row_shr:1 row_mask:0xf bank_mask:0xf
	v_mov_b32_dpp v191, v225 row_shr:1 row_mask:0xf bank_mask:0xf
	v_mov_b32_dpp v222, v218 row_ror:15 row_mask:0xf bank_mask:0xf
	v_mov_b32_dpp v223, v219 row_ror:15 row_mask:0xf bank_mask:0xf
	v_mov_b32_dpp v226, v224 row_ror:1 row_mask:0xf bank_mask:0xf
	v_mov_b32_dpp v227, v225 row_ror:1 row_mask:0xf bank_mask:0xf
	v_pk_mul_f32 v[190:191], v[148:149], v[190:191]
	v_pk_mul_f32 v[206:207], v[22:23], v[170:171]
	v_mov_b32_dpp v214, v210 row_ror:1 row_mask:0xf bank_mask:0xf
	v_mov_b32_dpp v215, v211 row_ror:1 row_mask:0xf bank_mask:0xf
	v_mov_b32_dpp v220, v218 row_ror:1 row_mask:0xf bank_mask:0xf
	v_mov_b32_dpp v221, v219 row_ror:1 row_mask:0xf bank_mask:0xf
	v_pk_fma_f32 v[190:191], v[224:225], v[150:151], v[190:191]
	v_mov_b32_dpp v226, v218 row_shr:1 row_mask:0xf bank_mask:0xf
	v_mov_b32_dpp v222, v224 row_shl:1 row_mask:0xf bank_mask:0xf
	v_mov_b32_dpp v227, v219 row_shr:1 row_mask:0xf bank_mask:0xf
	v_mov_b32_dpp v223, v225 row_shl:1 row_mask:0xf bank_mask:0xf
	v_mov_b32_dpp v216, v210 row_ror:15 row_mask:0xf bank_mask:0xf
	v_mov_b32_dpp v217, v211 row_ror:15 row_mask:0xf bank_mask:0xf
	v_pk_fma_f32 v[190:191], v[144:145], v[222:223], v[190:191]
	v_pk_mul_f32 v[222:223], v[148:149], v[226:227]
	v_mov_b32_dpp v220, v210 row_shr:1 row_mask:0xf bank_mask:0xf
	v_mov_b32_dpp v221, v211 row_shr:1 row_mask:0xf bank_mask:0xf
	v_mov_b32_dpp v214, v206 row_shr:1 row_mask:0xf bank_mask:0xf
	v_mov_b32_dpp v215, v207 row_shr:1 row_mask:0xf bank_mask:0xf
	v_pk_add_f32 v[190:191], v[146:147], v[190:191]
	v_pk_fma_f32 v[222:223], v[218:219], v[150:151], v[222:223]
	v_mov_b32_dpp v216, v218 row_shl:1 row_mask:0xf bank_mask:0xf
	v_mov_b32_dpp v217, v219 row_shl:1 row_mask:0xf bank_mask:0xf
	v_pk_mul_f32 v[218:219], v[148:149], v[220:221]
	v_pk_mul_f32 v[148:149], v[148:149], v[214:215]
	v_pk_fma_f32 v[218:219], v[210:211], v[150:151], v[218:219]
	v_pk_fma_f32 v[148:149], v[206:207], v[150:151], v[148:149]
	v_mov_b32_dpp v208, v206 row_ror:15 row_mask:0xf bank_mask:0xf
	v_mov_b32_dpp v188, v206 row_shl:1 row_mask:0xf bank_mask:0xf
	v_mov_b32_dpp v209, v207 row_ror:15 row_mask:0xf bank_mask:0xf
	v_mov_b32_dpp v189, v207 row_shl:1 row_mask:0xf bank_mask:0xf
	v_fma_f32 v206, |v190|, s52, 1.0
	v_fma_f32 v207, |v191|, s52, 1.0
	v_mov_b32_dpp v208, v210 row_shl:1 row_mask:0xf bank_mask:0xf
	v_rcp_f32_e32 v206, v206
	v_rcp_f32_e32 v207, v207
	v_mov_b32_dpp v209, v211 row_shl:1 row_mask:0xf bank_mask:0xf
	v_pk_fma_f32 v[216:217], v[144:145], v[216:217], v[222:223]
	v_pk_fma_f32 v[208:209], v[144:145], v[208:209], v[218:219]
	v_pk_fma_f32 v[144:145], v[144:145], v[188:189], v[148:149]
	v_pk_add_f32 v[216:217], v[146:147], v[216:217]
	v_pk_add_f32 v[208:209], v[146:147], v[208:209]
	v_pk_add_f32 v[144:145], v[146:147], v[144:145]
	v_pk_mul_f32 v[188:189], v[190:191], v[190:191]
	v_pk_fma_f32 v[148:149], v[206:207], s[54:55], v[246:247] op_sel_hi:[1,0,0]
	v_pk_mul_f32 v[188:189], v[188:189], s[64:65] op_sel_hi:[1,0]
	v_pk_fma_f32 v[148:149], v[206:207], v[148:149], s[58:59] op_sel_hi:[1,1,0]
	v_exp_f32_e32 v188, v188
	v_exp_f32_e32 v189, v189
	v_pk_fma_f32 v[148:149], v[206:207], v[148:149], s[60:61] op_sel_hi:[1,1,0]
	v_max_f32_e32 v150, 0, v190
	v_pk_fma_f32 v[148:149], v[206:207], v[148:149], s[62:63] op_sel_hi:[1,1,0]
	v_max_f32_e32 v151, 0, v191
	v_pk_mul_f32 v[148:149], v[206:207], v[148:149]
	s_nop 0
	v_pk_mul_f32 v[148:149], v[188:189], v[148:149]
	s_nop 0
	v_fma_f32 v148, -|v190|, v148, v150
	v_fma_f32 v149, -|v191|, v149, v151
	v_fma_f32 v188, |v216|, s52, 1.0
	v_fma_f32 v189, |v217|, s52, 1.0
	v_pk_mul_f32 v[190:191], v[216:217], v[216:217]
	v_rcp_f32_e32 v188, v188
	v_rcp_f32_e32 v189, v189
	v_pk_mul_f32 v[248:249], v[14:15], v[148:149]
	v_pk_mul_f32 v[190:191], v[190:191], s[64:65] op_sel_hi:[1,0]
	v_pk_fma_f32 v[148:149], v[188:189], s[54:55], v[246:247] op_sel_hi:[1,0,0]
	v_exp_f32_e32 v190, v190
	v_pk_fma_f32 v[148:149], v[188:189], v[148:149], s[58:59] op_sel_hi:[1,1,0]
	v_exp_f32_e32 v191, v191
	v_pk_fma_f32 v[148:149], v[188:189], v[148:149], s[60:61] op_sel_hi:[1,1,0]
	v_pk_mul_f32 v[248:249], v[172:173], v[248:249] op_sel_hi:[0,1]
	v_pk_fma_f32 v[148:149], v[188:189], v[148:149], s[62:63] op_sel_hi:[1,1,0]
	v_pk_mul_f32 v[148:149], v[188:189], v[148:149]
	v_max_f32_e32 v188, 0, v216
	v_max_f32_e32 v189, 0, v217
	v_pk_mul_f32 v[148:149], v[190:191], v[148:149]
	v_pk_mul_f32 v[190:191], v[208:209], v[208:209]
	v_fma_f32 v148, -|v216|, v148, v188
	v_fma_f32 v149, -|v217|, v149, v189
	v_fma_f32 v188, |v208|, s52, 1.0
	v_fma_f32 v189, |v209|, s52, 1.0
	v_cvt_pk_bf16_f32 v135, v248, v249
	v_pk_mul_f32 v[248:249], v[10:11], v[148:149]
	v_rcp_f32_e32 v188, v188
	v_rcp_f32_e32 v189, v189
	v_pk_mul_f32 v[190:191], v[190:191], s[64:65] op_sel_hi:[1,0]
	v_pk_mul_f32 v[248:249], v[178:179], v[248:249] op_sel_hi:[0,1]
	v_pk_fma_f32 v[148:149], v[188:189], s[54:55], v[246:247] op_sel_hi:[1,0,0]
	v_exp_f32_e32 v190, v190
	v_pk_fma_f32 v[148:149], v[188:189], v[148:149], s[58:59] op_sel_hi:[1,1,0]
	v_exp_f32_e32 v191, v191
	v_pk_fma_f32 v[148:149], v[188:189], v[148:149], s[60:61] op_sel_hi:[1,1,0]
	v_pk_fma_f32 v[148:149], v[188:189], v[148:149], s[62:63] op_sel_hi:[1,1,0]
	v_cvt_pk_bf16_f32 v139, v248, v249
	s_nop 0
	v_pk_mul_f32 v[148:149], v[188:189], v[148:149]
	v_max_f32_e32 v188, 0, v208
	v_max_f32_e32 v189, 0, v209
	v_pk_mul_f32 v[148:149], v[190:191], v[148:149]
	s_nop 0
	v_fma_f32 v148, -|v208|, v148, v188
	v_fma_f32 v149, -|v209|, v149, v189
	v_fma_f32 v188, |v144|, s52, 1.0
	v_fma_f32 v189, |v145|, s52, 1.0
	v_pk_mul_f32 v[248:249], v[6:7], v[148:149]
	v_rcp_f32_e32 v188, v188
	v_rcp_f32_e32 v189, v189
	v_pk_mul_f32 v[148:149], v[144:145], v[144:145]
	v_max_f32_e32 v150, 0, v144
	v_pk_fma_f32 v[146:147], v[188:189], s[54:55], v[246:247] op_sel_hi:[1,0,0]
	v_pk_mul_f32 v[148:149], v[148:149], s[64:65] op_sel_hi:[1,0]
	v_pk_fma_f32 v[146:147], v[188:189], v[146:147], s[58:59] op_sel_hi:[1,1,0]
	v_exp_f32_e32 v148, v148
	v_exp_f32_e32 v149, v149
	v_pk_fma_f32 v[146:147], v[188:189], v[146:147], s[60:61] op_sel_hi:[1,1,0]
	v_max_f32_e32 v151, 0, v145
	v_pk_fma_f32 v[146:147], v[188:189], v[146:147], s[62:63] op_sel_hi:[1,1,0]
	v_pk_mul_f32 v[248:249], v[176:177], v[248:249] op_sel_hi:[0,1]
	v_pk_mul_f32 v[146:147], v[188:189], v[146:147]
	v_pk_mul_f32 v[146:147], v[148:149], v[146:147]
	v_cvt_pk_bf16_f32 v143, v248, v249
	s_nop 0
	v_fma_f32 v144, -|v144|, v146, v150
	v_fma_f32 v145, -|v145|, v147, v151
	s_nop 0
	v_pk_mul_f32 v[144:145], v[2:3], v[144:145]
	v_pk_mul_f32 v[144:145], v[170:171], v[144:145] op_sel_hi:[0,1]
	v_cvt_pk_bf16_f32 v131, v144, v145
	v_add_u32_e32 v144, s86, v201
	v_add_u32_e32 v145, s29, v144
	v_add_u32_e32 v146, -1, v144
	v_cmp_gt_u32_e32 vcc, s76, v146
	v_cmp_gt_i32_e64 s[8:9], s78, v145
	s_and_b64 s[10:11], vcc, s[8:9]
	s_and_saveexec_b64 s[8:9], s[10:11]
	s_cbranch_execz .LBB0_705
	v_mov_b64_e32 v[146:147], s[38:39]
	v_mad_i64_i32 v[146:147], s[10:11], v145, s31, v[146:147]
	v_lshl_add_u64 v[146:147], v[174:175], 1, v[146:147]
	global_store_dwordx4 v[146:147], v[132:135], off
